# v17 + epilogue-align barrier of the leading wave half moved into the epilogue body (gate/up and both residual GEMMs): the leading half starts its epilogue while the trailing half finishes its last MFM
# baseline (speedup 1.0000x reference)
; #define PG8_STAGE(bufoff, gbase, voff) do { _Pragma("unroll") for (int _i = 0; _i < 2; ++_i) \
;         __builtin_amdgcn_global_load_lds((const unsigned*)((const char*)(gbase) + (voff)[_i]), (PG8_LAS unsigned*)(lds + (bufoff) + ldsw + _i * 8192), 16, 0, 0); } while (0)
; #define PG8_LDA(dst, b, h) do { _Pragma("unroll") for (int m = 0; m < 4; ++m) _Pragma("unroll") for (int k = 0; k < 2; ++k) dst[m][k] = *(const PG8_LAS bf16x8*)(lds + PG8_SA(b, h) + aoff + m * 2048 + k * 1024); } while (0)
; #define PG8_LDB(dst, b, h) do { _Pragma("unroll") for (int n = 0; n < 2; ++n) _Pragma("unroll") for (int k = 0; k < 2; ++k) dst[n][k] = *(const PG8_LAS bf16x8*)(lds + PG8_SB(b, h) + boff + n * 2048 + k * 1024); } while (0)
; #define PG8_MMA(ai, bj, At, Bt) do { __builtin_amdgcn_s_setprio(1); _Pragma("unroll") for (int m = 0; m < 4; ++m) _Pragma("unroll") for (int n = 0; n < 2; ++n) _Pragma("unroll") for (int k = 0; k < 2; ++k) \
;         acc[ai][bj][m][n] = __builtin_amdgcn_mfma_f32_16x16x32_bf16(Bt[n][k], At[m][k], acc[ai][bj][m][n], 0, 0, 0); __builtin_amdgcn_s_setprio(0); } while (0)
; #define PG8_WAIT_V(n) asm volatile("s_waitcnt vmcnt(" #n ")" ::: "memory")
; #define PG8_WAIT_L(n) asm volatile("s_waitcnt lgkmcnt(" #n ")" ::: "memory")
; #define PG8_BAR __builtin_amdgcn_s_barrier()
; #define PG8_SCHED __builtin_amdgcn_sched_barrier(0)
; template <class Epi, class Sched, bool ALIGN_EPI = false, bool SP2 = false>
; __device__ __forceinline__ void gemm_phase(PG8_LAS unsigned char* lds, const Gemm g, const Sched& S, const Epi& E) {
;     ...
;             PG8_LDB(B0, 0, 0); PG8_LDB(B1, 0, 1); PG8_SCHED; PG8_LDA(At, 0, 0); PG8_STAGE(PG8_SA(1, 1), a1 + hstep, voffA);
;             PG8_WAIT_V(8); PG8_WAIT_L(0); PG8_BAR; PG8_MMA(0, 0, At, B0); PG8_MMA(0, 1, At, B1); PG8_BAR; PG8_SCHED;
;             PG8_LDA(At, 0, 1); PG8_STAGE(PG8_SB(0, 0), b2, voffB); PG8_STAGE(PG8_SB(0, 1), b2 + hstep, voffB); PG8_STAGE(PG8_SA(0, 0), a2, voffA);
;             PG8_WAIT_V(8); PG8_WAIT_L(0); PG8_BAR; PG8_MMA(1, 0, At, B0); PG8_MMA(1, 1, At, B1); PG8_BAR; PG8_SCHED;
;             PG8_LDB(B0, 1, 0); PG8_LDB(B1, 1, 1); PG8_SCHED; PG8_LDA(At, 1, 0); PG8_STAGE(PG8_SA(0, 1), a2 + hstep, voffA);
;             PG8_WAIT_V(8); PG8_WAIT_L(0); PG8_BAR; PG8_MMA(0, 0, At, B0); PG8_MMA(0, 1, At, B1); PG8_BAR; PG8_SCHED;
.LBB0_42:
	s_add_i32 s46, s24, 2
	s_add_u32 s47, s22, 0x80
	s_addc_u32 s25, s23, 0
	s_add_i32 s50, 0, 0x10000
	s_cmp_eq_u32 s37, s24
	s_cselect_b32 s25, s17, s25
	s_cselect_b32 s24, s42, s47
	s_cselect_b32 s49, s15, s45
	s_cselect_b32 s48, s43, s44
	s_add_i32 s47, 0, 0x14000
	v_add_u32_e32 v142, s50, v165
	v_add_u32_e32 v182, s47, v165
	ds_read_b128 v[130:133], v142
	ds_read_b128 v[134:137], v142 offset:1024
	ds_read_b128 v[138:141], v142 offset:2048
	ds_read_b128 v[142:145], v142 offset:3072
	ds_read_b128 v[146:149], v182
	ds_read_b128 v[150:153], v182 offset:1024
	ds_read_b128 v[154:157], v182 offset:2048
	ds_read_b128 v[182:185], v182 offset:3072
	v_lshl_add_u64 v[198:199], s[22:23], 0, v[178:179]
	s_add_i32 m0, s29, 0xc000
	ds_read_b128 v[186:189], v214
	ds_read_b128 v[190:193], v214 offset:1024
	ds_read_b128 v[194:197], v214 offset:2048
	ds_read_b128 v[216:219], v214 offset:3072
	ds_read_b128 v[220:223], v214 offset:4096
	ds_read_b128 v[224:227], v214 offset:5120
	ds_read_b128 v[228:231], v214 offset:6144
	ds_read_b128 v[232:235], v214 offset:7168
	global_load_lds_dwordx4 v[198:199], off
	v_lshl_add_u64 v[198:199], s[22:23], 0, v[180:181]
	s_add_i32 m0, s29, 0xe000
	s_nop 0
	global_load_lds_dwordx4 v[198:199], off
	s_waitcnt vmcnt(8)
	s_waitcnt lgkmcnt(0)
	s_barrier
	s_setprio 1
	s_waitcnt lgkmcnt(0)
	v_mfma_f32_16x16x32_bf16 v[126:129], v[130:133], v[186:189], v[126:129]
	v_mfma_f32_16x16x32_bf16 v[122:125], v[138:141], v[186:189], v[122:125]
	v_mfma_f32_16x16x32_bf16 v[110:113], v[130:133], v[194:197], v[110:113]
	v_mfma_f32_16x16x32_bf16 v[106:109], v[138:141], v[194:197], v[106:109]
	v_mfma_f32_16x16x32_bf16 v[94:97], v[130:133], v[220:223], v[94:97]
	v_mfma_f32_16x16x32_bf16 v[90:93], v[138:141], v[220:223], v[90:93]
	v_mfma_f32_16x16x32_bf16 v[78:81], v[130:133], v[228:231], v[78:81]
	v_mfma_f32_16x16x32_bf16 v[74:77], v[138:141], v[228:231], v[74:77]
	v_mfma_f32_16x16x32_bf16 v[126:129], v[134:137], v[190:193], v[126:129]
	v_mfma_f32_16x16x32_bf16 v[122:125], v[142:145], v[190:193], v[122:125]
	v_mfma_f32_16x16x32_bf16 v[110:113], v[134:137], v[216:219], v[110:113]
	v_mfma_f32_16x16x32_bf16 v[106:109], v[142:145], v[216:219], v[106:109]
	v_mfma_f32_16x16x32_bf16 v[94:97], v[134:137], v[224:227], v[94:97]
	v_mfma_f32_16x16x32_bf16 v[90:93], v[142:145], v[224:227], v[90:93]
	v_mfma_f32_16x16x32_bf16 v[78:81], v[134:137], v[232:235], v[78:81]
	v_mfma_f32_16x16x32_bf16 v[74:77], v[142:145], v[232:235], v[74:77]
	s_setprio 0
	s_setprio 1
	v_mfma_f32_16x16x32_bf16 v[118:121], v[146:149], v[186:189], v[118:121]
	v_mfma_f32_16x16x32_bf16 v[114:117], v[154:157], v[186:189], v[114:117]
	v_mfma_f32_16x16x32_bf16 v[102:105], v[146:149], v[194:197], v[102:105]
	v_mfma_f32_16x16x32_bf16 v[98:101], v[154:157], v[194:197], v[98:101]
	v_mfma_f32_16x16x32_bf16 v[86:89], v[146:149], v[220:223], v[86:89]
	v_mfma_f32_16x16x32_bf16 v[82:85], v[154:157], v[220:223], v[82:85]
	v_mfma_f32_16x16x32_bf16 v[70:73], v[146:149], v[228:231], v[70:73]
	v_mfma_f32_16x16x32_bf16 v[66:69], v[154:157], v[228:231], v[66:69]
	v_mfma_f32_16x16x32_bf16 v[118:121], v[150:153], v[190:193], v[118:121]
	v_mfma_f32_16x16x32_bf16 v[114:117], v[182:185], v[190:193], v[114:117]
	v_mfma_f32_16x16x32_bf16 v[102:105], v[150:153], v[216:219], v[102:105]
	v_mfma_f32_16x16x32_bf16 v[98:101], v[182:185], v[216:219], v[98:101]
	v_mfma_f32_16x16x32_bf16 v[86:89], v[150:153], v[224:227], v[86:89]
	v_mfma_f32_16x16x32_bf16 v[82:85], v[182:185], v[224:227], v[82:85]
	v_mfma_f32_16x16x32_bf16 v[70:73], v[150:153], v[232:235], v[70:73]
	v_mfma_f32_16x16x32_bf16 v[66:69], v[182:185], v[232:235], v[66:69]
	s_setprio 0
	s_barrier
	s_add_i32 s50, s50, s2
	v_lshl_add_u64 v[198:199], s[48:49], 0, v[0:1]
	s_mov_b32 m0, s50
	ds_read_b128 v[186:189], v214 offset:16384
	ds_read_b128 v[190:193], v214 offset:17408
	ds_read_b128 v[194:197], v214 offset:18432
	ds_read_b128 v[216:219], v214 offset:19456
	ds_read_b128 v[220:223], v214 offset:20480
	ds_read_b128 v[224:227], v214 offset:21504
	ds_read_b128 v[228:231], v214 offset:22528
	ds_read_b128 v[232:235], v214 offset:23552
	global_load_lds_dwordx4 v[198:199], off
	s_add_i32 m0, s50, 0x2000
	v_lshl_add_u64 v[236:237], s[48:49], 0, v[172:173]
	s_add_u32 s48, s48, s8
	s_addc_u32 s49, s49, 0
	s_add_i32 s47, s47, s2
	global_load_lds_dwordx4 v[236:237], off
	v_lshl_add_u64 v[238:239], s[48:49], 0, v[0:1]
	s_mov_b32 m0, s47
	v_lshl_add_u64 v[240:241], s[48:49], 0, v[172:173]
	global_load_lds_dwordx4 v[238:239], off
	s_add_i32 m0, s47, 0x2000
	v_lshl_add_u64 v[242:243], s[24:25], 0, v[176:177]
	global_load_lds_dwordx4 v[240:241], off
	s_mov_b32 m0, s29
	v_lshl_add_u64 v[244:245], s[24:25], 0, v[174:175]
	global_load_lds_dwordx4 v[242:243], off
	s_mov_b32 m0, s30
	s_nop 0
	global_load_lds_dwordx4 v[244:245], off
	s_waitcnt vmcnt(8)
	s_waitcnt lgkmcnt(0)
	s_barrier
; #define PG8_STAGE(bufoff, gbase, voff) do { _Pragma("unroll") for (int _i = 0; _i < 2; ++_i) \
;         __builtin_amdgcn_global_load_lds((const unsigned*)((const char*)(gbase) + (voff)[_i]), (PG8_LAS unsigned*)(lds + (bufoff) + ldsw + _i * 8192), 16, 0, 0); } while (0)
; #define PG8_LDA(dst, b, h) do { _Pragma("unroll") for (int m = 0; m < 4; ++m) _Pragma("unroll") for (int k = 0; k < 2; ++k) dst[m][k] = *(const PG8_LAS bf16x8*)(lds + PG8_SA(b, h) + aoff + m * 2048 + k * 1024); } while (0)
; #define PG8_LDB(dst, b, h) do { _Pragma("unroll") for (int n = 0; n < 2; ++n) _Pragma("unroll") for (int k = 0; k < 2; ++k) dst[n][k] = *(const PG8_LAS bf16x8*)(lds + PG8_SB(b, h) + boff + n * 2048 + k * 1024); } while (0)
; #define PG8_MMA(ai, bj, At, Bt) do { __builtin_amdgcn_s_setprio(1); _Pragma("unroll") for (int m = 0; m < 4; ++m) _Pragma("unroll") for (int n = 0; n < 2; ++n) _Pragma("unroll") for (int k = 0; k < 2; ++k) \
;         acc[ai][bj][m][n] = __builtin_amdgcn_mfma_f32_16x16x32_bf16(Bt[n][k], At[m][k], acc[ai][bj][m][n], 0, 0, 0); __builtin_amdgcn_s_setprio(0); } while (0)
; #define PG8_WAIT_V(n) asm volatile("s_waitcnt vmcnt(" #n ")" ::: "memory")
; #define PG8_WAIT_L(n) asm volatile("s_waitcnt lgkmcnt(" #n ")" ::: "memory")
; #define PG8_BAR __builtin_amdgcn_s_barrier()
; template <class Epi, class Sched, bool ALIGN_EPI = false, bool SP2 = false>
; __device__ __forceinline__ void gemm_phase(PG8_LAS unsigned char* lds, const Gemm g, const Sched& S, const Epi& E) {
;     ...
;             PG8_WAIT_V(8); PG8_WAIT_L(0); PG8_BAR; PG8_MMA(0, 0, At, B0); PG8_MMA(0, 1, At, B1); PG8_BAR; PG8_SCHED;
;             PG8_LDA(At, 0, 1); PG8_STAGE(PG8_SB(0, 0), b2, voffB); PG8_STAGE(PG8_SB(0, 1), b2 + hstep, voffB); PG8_STAGE(PG8_SA(0, 0), a2, voffA);
;             PG8_WAIT_V(8); PG8_WAIT_L(0); PG8_BAR; PG8_MMA(1, 0, At, B0); PG8_MMA(1, 1, At, B1); PG8_BAR; PG8_SCHED;
;             PG8_LDB(B0, 1, 0); PG8_LDB(B1, 1, 1); PG8_SCHED; PG8_LDA(At, 1, 0); PG8_STAGE(PG8_SA(0, 1), a2 + hstep, voffA);
;             PG8_WAIT_V(8); PG8_WAIT_L(0); PG8_BAR; PG8_MMA(0, 0, At, B0); PG8_MMA(0, 1, At, B1); PG8_BAR; PG8_SCHED;
;             PG8_LDA(At, 1, 1); PG8_STAGE(PG8_SB(1, 0), b3, voffB); PG8_STAGE(PG8_SB(1, 1), b3 + hstep, voffB); PG8_STAGE(PG8_SA(1, 0), a3, voffA);
;             PG8_WAIT_V(8); PG8_WAIT_L(0); PG8_BAR; PG8_MMA(1, 0, At, B0); PG8_MMA(1, 1, At, B1); PG8_BAR; PG8_SCHED;
	s_setprio 1
	s_waitcnt lgkmcnt(0)
	v_mfma_f32_16x16x32_bf16 v[62:65], v[130:133], v[186:189], v[62:65]
	v_mfma_f32_16x16x32_bf16 v[58:61], v[138:141], v[186:189], v[58:61]
	v_mfma_f32_16x16x32_bf16 v[46:49], v[130:133], v[194:197], v[46:49]
	v_mfma_f32_16x16x32_bf16 v[42:45], v[138:141], v[194:197], v[42:45]
	v_mfma_f32_16x16x32_bf16 v[30:33], v[130:133], v[220:223], v[30:33]
	v_mfma_f32_16x16x32_bf16 v[26:29], v[138:141], v[220:223], v[26:29]
	v_mfma_f32_16x16x32_bf16 v[14:17], v[130:133], v[228:231], v[14:17]
	v_mfma_f32_16x16x32_bf16 v[10:13], v[138:141], v[228:231], v[10:13]
	v_mfma_f32_16x16x32_bf16 v[62:65], v[134:137], v[190:193], v[62:65]
	v_mfma_f32_16x16x32_bf16 v[58:61], v[142:145], v[190:193], v[58:61]
	v_mfma_f32_16x16x32_bf16 v[46:49], v[134:137], v[216:219], v[46:49]
	v_mfma_f32_16x16x32_bf16 v[42:45], v[142:145], v[216:219], v[42:45]
	v_mfma_f32_16x16x32_bf16 v[30:33], v[134:137], v[224:227], v[30:33]
	v_mfma_f32_16x16x32_bf16 v[26:29], v[142:145], v[224:227], v[26:29]
	v_mfma_f32_16x16x32_bf16 v[14:17], v[134:137], v[232:235], v[14:17]
	v_mfma_f32_16x16x32_bf16 v[10:13], v[142:145], v[232:235], v[10:13]
	s_setprio 0
	s_setprio 1
	v_mfma_f32_16x16x32_bf16 v[54:57], v[146:149], v[186:189], v[54:57]
	v_mfma_f32_16x16x32_bf16 v[50:53], v[154:157], v[186:189], v[50:53]
	v_mfma_f32_16x16x32_bf16 v[38:41], v[146:149], v[194:197], v[38:41]
	v_mfma_f32_16x16x32_bf16 v[34:37], v[154:157], v[194:197], v[34:37]
	v_mfma_f32_16x16x32_bf16 v[22:25], v[146:149], v[220:223], v[22:25]
	v_mfma_f32_16x16x32_bf16 v[18:21], v[154:157], v[220:223], v[18:21]
	v_mfma_f32_16x16x32_bf16 v[6:9], v[146:149], v[228:231], v[6:9]
	v_mfma_f32_16x16x32_bf16 v[2:5], v[154:157], v[228:231], v[2:5]
	v_mfma_f32_16x16x32_bf16 v[54:57], v[150:153], v[190:193], v[54:57]
	v_mfma_f32_16x16x32_bf16 v[50:53], v[182:185], v[190:193], v[50:53]
	v_mfma_f32_16x16x32_bf16 v[38:41], v[150:153], v[216:219], v[38:41]
	v_mfma_f32_16x16x32_bf16 v[34:37], v[182:185], v[216:219], v[34:37]
	v_mfma_f32_16x16x32_bf16 v[22:25], v[150:153], v[224:227], v[22:25]
	v_mfma_f32_16x16x32_bf16 v[18:21], v[182:185], v[224:227], v[18:21]
	v_mfma_f32_16x16x32_bf16 v[6:9], v[150:153], v[232:235], v[6:9]
	v_mfma_f32_16x16x32_bf16 v[2:5], v[182:185], v[232:235], v[2:5]
	s_setprio 0
	s_barrier
	s_add_i32 s47, 0, 0x18000
	s_add_i32 s48, 0, 0x1c000
	v_add_u32_e32 v142, s47, v165
	v_add_u32_e32 v182, s48, v165
	ds_read_b128 v[130:133], v142
	ds_read_b128 v[134:137], v142 offset:1024
	ds_read_b128 v[138:141], v142 offset:2048
	ds_read_b128 v[142:145], v142 offset:3072
	ds_read_b128 v[146:149], v182
	ds_read_b128 v[150:153], v182 offset:1024
	ds_read_b128 v[154:157], v182 offset:2048
	ds_read_b128 v[182:185], v182 offset:3072
	s_add_u32 s24, s24, s8
	s_addc_u32 s25, s25, 0
	s_mov_b32 m0, s31
	v_lshl_add_u64 v[246:247], s[24:25], 0, v[176:177]
	ds_read_b128 v[186:189], v214 offset:32768
	ds_read_b128 v[190:193], v214 offset:33792
	ds_read_b128 v[194:197], v214 offset:34816
	ds_read_b128 v[216:219], v214 offset:35840
	ds_read_b128 v[220:223], v214 offset:36864
	ds_read_b128 v[224:227], v214 offset:37888
	ds_read_b128 v[228:231], v214 offset:38912
	ds_read_b128 v[232:235], v214 offset:39936
	global_load_lds_dwordx4 v[246:247], off
	v_lshl_add_u64 v[246:247], s[24:25], 0, v[174:175]
	s_mov_b32 m0, s34
	s_nop 0
	global_load_lds_dwordx4 v[246:247], off
	s_waitcnt vmcnt(8)
	s_waitcnt lgkmcnt(0)
	s_barrier
	s_setprio 1
	s_waitcnt lgkmcnt(0)
	v_mfma_f32_16x16x32_bf16 v[126:129], v[130:133], v[186:189], v[126:129]
	v_mfma_f32_16x16x32_bf16 v[122:125], v[138:141], v[186:189], v[122:125]
	v_mfma_f32_16x16x32_bf16 v[110:113], v[130:133], v[194:197], v[110:113]
	v_mfma_f32_16x16x32_bf16 v[106:109], v[138:141], v[194:197], v[106:109]
	v_mfma_f32_16x16x32_bf16 v[94:97], v[130:133], v[220:223], v[94:97]
	v_mfma_f32_16x16x32_bf16 v[90:93], v[138:141], v[220:223], v[90:93]
	v_mfma_f32_16x16x32_bf16 v[78:81], v[130:133], v[228:231], v[78:81]
	v_mfma_f32_16x16x32_bf16 v[74:77], v[138:141], v[228:231], v[74:77]
	v_mfma_f32_16x16x32_bf16 v[126:129], v[134:137], v[190:193], v[126:129]
	v_mfma_f32_16x16x32_bf16 v[122:125], v[142:145], v[190:193], v[122:125]
	v_mfma_f32_16x16x32_bf16 v[110:113], v[134:137], v[216:219], v[110:113]
	v_mfma_f32_16x16x32_bf16 v[106:109], v[142:145], v[216:219], v[106:109]
	v_mfma_f32_16x16x32_bf16 v[94:97], v[134:137], v[224:227], v[94:97]
	v_mfma_f32_16x16x32_bf16 v[90:93], v[142:145], v[224:227], v[90:93]
	v_mfma_f32_16x16x32_bf16 v[78:81], v[134:137], v[232:235], v[78:81]
	v_mfma_f32_16x16x32_bf16 v[74:77], v[142:145], v[232:235], v[74:77]
	s_setprio 0
	s_setprio 1
	v_mfma_f32_16x16x32_bf16 v[118:121], v[146:149], v[186:189], v[118:121]
	v_mfma_f32_16x16x32_bf16 v[114:117], v[154:157], v[186:189], v[114:117]
	v_mfma_f32_16x16x32_bf16 v[102:105], v[146:149], v[194:197], v[102:105]
	v_mfma_f32_16x16x32_bf16 v[98:101], v[154:157], v[194:197], v[98:101]
	v_mfma_f32_16x16x32_bf16 v[86:89], v[146:149], v[220:223], v[86:89]
	v_mfma_f32_16x16x32_bf16 v[82:85], v[154:157], v[220:223], v[82:85]
	v_mfma_f32_16x16x32_bf16 v[70:73], v[146:149], v[228:231], v[70:73]
	v_mfma_f32_16x16x32_bf16 v[66:69], v[154:157], v[228:231], v[66:69]
	v_mfma_f32_16x16x32_bf16 v[118:121], v[150:153], v[190:193], v[118:121]
	v_mfma_f32_16x16x32_bf16 v[114:117], v[182:185], v[190:193], v[114:117]
	v_mfma_f32_16x16x32_bf16 v[102:105], v[150:153], v[216:219], v[102:105]
	v_mfma_f32_16x16x32_bf16 v[98:101], v[182:185], v[216:219], v[98:101]
	v_mfma_f32_16x16x32_bf16 v[86:89], v[150:153], v[224:227], v[86:89]
	v_mfma_f32_16x16x32_bf16 v[82:85], v[182:185], v[224:227], v[82:85]
	v_mfma_f32_16x16x32_bf16 v[70:73], v[150:153], v[232:235], v[70:73]
	v_mfma_f32_16x16x32_bf16 v[66:69], v[182:185], v[232:235], v[66:69]
	s_setprio 0
	s_barrier
; template <class Epi, class Sched, bool ALIGN_EPI = false, bool SP2 = false>
; __device__ __forceinline__ void gemm_phase(PG8_LAS unsigned char* lds, const Gemm g, const Sched& S, const Epi& E) {
;     ...
;             PG8_LDA(At, 1, 1); PG8_STAGE(PG8_SB(1, 0), b3, voffB); PG8_STAGE(PG8_SB(1, 1), b3 + hstep, voffB); PG8_STAGE(PG8_SA(1, 0), a3, voffA);
;             PG8_WAIT_V(8); PG8_WAIT_L(0); PG8_BAR; PG8_MMA(1, 0, At, B0); PG8_MMA(1, 1, At, B1); PG8_BAR; PG8_SCHED;
;             } else {
;             PG8_LDB(B0, 0, 0); PG8_SCHED; PG8_LDA(At, 0, 0); PG8_STAGE(PG8_SA(1, 1), a1 + hstep, voffA);
;             PG8_WAIT_L(8); PG8_BAR; PG8_WAIT_L(0); PG8_MMA(0, 0, At, B0); PG8_BAR; PG8_SCHED;
;             PG8_LDB(B1, 0, 1); PG8_STAGE(PG8_SB(0, 0), b2, voffB);
;             PG8_BAR; PG8_WAIT_L(0); PG8_MMA(0, 1, At, B1); PG8_BAR;
;             PG8_LDA(At, 0, 1); PG8_STAGE(PG8_SA(0, 0), a2, voffA);
;             PG8_BAR; PG8_WAIT_L(0); PG8_MMA(1, 0, At, B0); PG8_BAR; PG8_SCHED;
;             PG8_STAGE(PG8_SB(0, 1), b2 + hstep, voffB);
;             PG8_WAIT_V(6); PG8_BAR; PG8_MMA(1, 1, At, B1); PG8_BAR;
;             PG8_LDB(B0, 1, 0); PG8_SCHED; PG8_LDA(At, 1, 0); PG8_STAGE(PG8_SA(0, 1), a2 + hstep, voffA);
;             PG8_WAIT_L(8); PG8_BAR; PG8_WAIT_L(0); PG8_MMA(0, 0, At, B0); PG8_BAR; PG8_SCHED;
;             PG8_LDB(B1, 1, 1); PG8_STAGE(PG8_SB(1, 0), b3, voffB);
;             PG8_BAR; PG8_WAIT_L(0); PG8_MMA(0, 1, At, B1); PG8_BAR;
;             PG8_LDA(At, 1, 1); PG8_STAGE(PG8_SA(1, 0), a3, voffA);
;             PG8_BAR; PG8_WAIT_L(0); PG8_MMA(1, 0, At, B0); PG8_BAR; PG8_SCHED;
;             PG8_STAGE(PG8_SB(1, 1), b3 + hstep, voffB);
;             PG8_WAIT_V(6); PG8_BAR; PG8_MMA(1, 1, At, B1); PG8_BAR;
;             }
;         }
;         if constexpr (ALIGN_EPI) { if (wr == 0) PG8_BAR; }
;     __device__ __forceinline__ void operator()(const f32x4 (&acc)[2][2][4][2], const Unit& u, int wr, int wc, int fr, int fq) const {
;         const int row0 = u.pm * BM + wr * 64 + fr, col0 = u.pn * BM + wc * 32 + 8 * fq;
; #pragma unroll
;         for (int ai = 0; ai < 2; ++ai) {
;             u32x4 xv[4][2];
; #pragma unroll
;             for (int m = 0; m < 4; ++m)
; #pragma unroll
;                 for (int bj = 0; bj < 2; ++bj) xv[m][bj] = *(const u32x4*)(XB + (size_t)(row0 + ai * HALF + m * 16) * 1024 + col0 + bj * HALF);
;             asm volatile("" ::: "memory");
	s_add_i32 s24, s47, s2
	v_lshl_add_u64 v[198:199], v[198:199], 0, s[90:91]
	s_mov_b32 m0, s24
	ds_read_b128 v[186:189], v214 offset:49152
	ds_read_b128 v[190:193], v214 offset:50176
	ds_read_b128 v[194:197], v214 offset:51200
	ds_read_b128 v[216:219], v214 offset:52224
	ds_read_b128 v[220:223], v214 offset:53248
	ds_read_b128 v[224:227], v214 offset:54272
	ds_read_b128 v[228:231], v214 offset:55296
	ds_read_b128 v[232:235], v214 offset:56320
	global_load_lds_dwordx4 v[198:199], off
	v_lshl_add_u64 v[198:199], v[236:237], 0, s[90:91]
	s_add_i32 m0, s24, 0x2000
	s_add_i32 s24, s48, s2
	global_load_lds_dwordx4 v[198:199], off
	v_lshl_add_u64 v[198:199], v[238:239], 0, s[90:91]
	s_mov_b32 m0, s24
	s_nop 0
	global_load_lds_dwordx4 v[198:199], off
	v_lshl_add_u64 v[198:199], v[240:241], 0, s[90:91]
	s_add_i32 m0, s24, 0x2000
	s_nop 0
	global_load_lds_dwordx4 v[198:199], off
	v_lshl_add_u64 v[198:199], v[242:243], 0, s[90:91]
	s_mov_b32 m0, s38
	s_nop 0
	global_load_lds_dwordx4 v[198:199], off
	v_lshl_add_u64 v[198:199], v[244:245], 0, s[90:91]
	s_mov_b32 m0, s39
	s_nop 0
	global_load_lds_dwordx4 v[198:199], off
	s_waitcnt vmcnt(8)
	s_waitcnt lgkmcnt(0)
	s_barrier
	s_setprio 1
	s_waitcnt lgkmcnt(0)
	v_mfma_f32_16x16x32_bf16 v[62:65], v[130:133], v[186:189], v[62:65]
	v_mfma_f32_16x16x32_bf16 v[58:61], v[138:141], v[186:189], v[58:61]
	v_mfma_f32_16x16x32_bf16 v[46:49], v[130:133], v[194:197], v[46:49]
	v_mfma_f32_16x16x32_bf16 v[42:45], v[138:141], v[194:197], v[42:45]
	v_mfma_f32_16x16x32_bf16 v[30:33], v[130:133], v[220:223], v[30:33]
	v_mfma_f32_16x16x32_bf16 v[26:29], v[138:141], v[220:223], v[26:29]
	v_mfma_f32_16x16x32_bf16 v[14:17], v[130:133], v[228:231], v[14:17]
	v_mfma_f32_16x16x32_bf16 v[10:13], v[138:141], v[228:231], v[10:13]
	v_mfma_f32_16x16x32_bf16 v[62:65], v[134:137], v[190:193], v[62:65]
	v_mfma_f32_16x16x32_bf16 v[58:61], v[142:145], v[190:193], v[58:61]
	v_mfma_f32_16x16x32_bf16 v[46:49], v[134:137], v[216:219], v[46:49]
	v_mfma_f32_16x16x32_bf16 v[42:45], v[142:145], v[216:219], v[42:45]
	v_mfma_f32_16x16x32_bf16 v[30:33], v[134:137], v[224:227], v[30:33]
	v_mfma_f32_16x16x32_bf16 v[26:29], v[142:145], v[224:227], v[26:29]
	v_mfma_f32_16x16x32_bf16 v[14:17], v[134:137], v[232:235], v[14:17]
	v_mfma_f32_16x16x32_bf16 v[10:13], v[142:145], v[232:235], v[10:13]
	s_setprio 0
	s_setprio 1
	v_mfma_f32_16x16x32_bf16 v[54:57], v[146:149], v[186:189], v[54:57]
	v_mfma_f32_16x16x32_bf16 v[50:53], v[154:157], v[186:189], v[50:53]
	v_mfma_f32_16x16x32_bf16 v[38:41], v[146:149], v[194:197], v[38:41]
	v_mfma_f32_16x16x32_bf16 v[34:37], v[154:157], v[194:197], v[34:37]
	v_mfma_f32_16x16x32_bf16 v[22:25], v[146:149], v[220:223], v[22:25]
	v_mfma_f32_16x16x32_bf16 v[18:21], v[154:157], v[220:223], v[18:21]
	v_mfma_f32_16x16x32_bf16 v[6:9], v[146:149], v[228:231], v[6:9]
	v_mfma_f32_16x16x32_bf16 v[2:5], v[154:157], v[228:231], v[2:5]
	v_mfma_f32_16x16x32_bf16 v[54:57], v[150:153], v[190:193], v[54:57]
	v_mfma_f32_16x16x32_bf16 v[50:53], v[182:185], v[190:193], v[50:53]
	v_mfma_f32_16x16x32_bf16 v[38:41], v[150:153], v[216:219], v[38:41]
	v_mfma_f32_16x16x32_bf16 v[34:37], v[182:185], v[216:219], v[34:37]
	v_mfma_f32_16x16x32_bf16 v[22:25], v[150:153], v[224:227], v[22:25]
	v_mfma_f32_16x16x32_bf16 v[18:21], v[182:185], v[224:227], v[18:21]
	v_mfma_f32_16x16x32_bf16 v[6:9], v[150:153], v[232:235], v[6:9]
	v_mfma_f32_16x16x32_bf16 v[2:5], v[182:185], v[232:235], v[2:5]
	s_setprio 0
	s_barrier
	s_add_u32 s22, s22, 0x100
	s_addc_u32 s23, s23, 0
	s_add_u32 s44, s44, 0x100
	s_addc_u32 s45, s45, 0
	s_cmp_ge_u32 s46, s36
	s_mov_b32 s24, s46
	s_cbranch_scc0 .LBB0_42
	v_lshl_or_b32 v198, s9, 8, v213
	v_lshl_add_u32 v217, s41, 8, v158
	v_lshlrev_b32_e32 v246, 1, v198
	v_lshl_add_u32 v246, v217, 11, v246
	v_mov_b32_e32 v247, 0
	s_mov_b32 s22, 0x8000
	s_mov_b32 s23, 0
	s_mov_b32 s88, 0x28000
	v_lshl_add_u64 v[246:247], s[94:95], 0, v[246:247]
	v_xor_b32_e32 v215, 16, v201
	v_xor_b32_e32 v216, 32, v201
	v_mov_b32_e32 v198, v246
	v_mov_b32_e32 v199, v247
	global_load_dwordx4 v[130:133], v[246:247], off
	global_load_dwordx4 v[134:137], v[246:247], off offset:256
	v_lshl_add_u64 v[246:247], v[246:247], 0, s[22:23]
	global_load_dwordx4 v[138:141], v[246:247], off
	global_load_dwordx4 v[142:145], v[246:247], off offset:256
	v_lshl_add_u64 v[246:247], v[246:247], 0, s[22:23]
	global_load_dwordx4 v[146:149], v[246:247], off
	global_load_dwordx4 v[150:153], v[246:247], off offset:256
	v_lshl_add_u64 v[246:247], v[246:247], 0, s[22:23]
	global_load_dwordx4 v[154:157], v[246:247], off
	global_load_dwordx4 v[218:221], v[246:247], off offset:256
	v_lshl_add_u64 v[246:247], v[246:247], 0, s[88:89]
	global_load_dwordx4 v[182:185], v[246:247], off
	global_load_dwordx4 v[186:189], v[246:247], off offset:256
	v_lshl_add_u64 v[246:247], v[246:247], 0, s[22:23]
	global_load_dwordx4 v[190:193], v[246:247], off
	global_load_dwordx4 v[194:197], v[246:247], off offset:256
	v_lshl_add_u64 v[246:247], v[246:247], 0, s[22:23]
	global_load_dwordx4 v[222:225], v[246:247], off
	global_load_dwordx4 v[226:229], v[246:247], off offset:256
	v_lshl_add_u64 v[246:247], v[246:247], 0, s[22:23]
	global_load_dwordx4 v[230:233], v[246:247], off
	global_load_dwordx4 v[234:237], v[246:247], off offset:256
	v_lshlrev_b32_e32 v215, 2, v215
	v_lshlrev_b32_e32 v216, 2, v216
	s_waitcnt vmcnt(15)
; __device__ __forceinline__ unsigned cvt_pk_bf16(float lo, float hi) { f32x2_cv v = {lo, hi}; bf16x2_cv b = __builtin_convertvector(v, bf16x2_cv); return __builtin_bit_cast(unsigned, b); }
;     __device__ __forceinline__ void operator()(const f32x4 (&acc)[2][2][4][2], const Unit& u, int wr, int wc, int fr, int fq) const {
;     ...
;             for (int m = 0; m < 4; ++m) {
;                 const int row = row0 + ai * HALF + m * 16; float ss = 0.f;
; #pragma unroll
;                 for (int bj = 0; bj < 2; ++bj) {
;                     const size_t off = (size_t)row * 1024 + col0 + bj * HALF;
;                     const u32x4 v = xv[m][bj];
;                     f32x4 x0 = {__uint_as_float(v.x << 16), __uint_as_float(v.x & 0xffff0000u), __uint_as_float(v.y << 16), __uint_as_float(v.y & 0xffff0000u)};
;                     f32x4 x1 = {__uint_as_float(v.z << 16), __uint_as_float(v.z & 0xffff0000u), __uint_as_float(v.w << 16), __uint_as_float(v.w & 0xffff0000u)};
;                     x0 = x0 + acc[ai][bj][m][0] * alpha; x1 = x1 + acc[ai][bj][m][1] * alpha;
;                     u32x4 w; w.x = cvt_pk_bf16(x0[0], x0[1]); w.y = cvt_pk_bf16(x0[2], x0[3]); w.z = cvt_pk_bf16(x1[0], x1[1]); w.w = cvt_pk_bf16(x1[2], x1[3]);
;                     *(u32x4*)(XB + off) = w;
;                     const f32x4 sq = x0 * x0 + x1 * x1;
;                     ss += (sq[0] + sq[1]) + (sq[2] + sq[3]);
;                 }
	v_lshlrev_b32_e32 v238, 16, v130
	v_and_b32_e32 v239, 0xffff0000, v130
	v_lshlrev_b32_e32 v240, 16, v131
	v_and_b32_e32 v241, 0xffff0000, v131
	v_lshlrev_b32_e32 v242, 16, v132
	v_and_b32_e32 v243, 0xffff0000, v132
	v_lshlrev_b32_e32 v244, 16, v133
	v_and_b32_e32 v245, 0xffff0000, v133
	v_pk_add_f32 v[126:127], v[126:127], v[238:239]
	v_pk_add_f32 v[128:129], v[128:129], v[240:241]
	v_pk_add_f32 v[122:123], v[122:123], v[242:243]
	v_pk_add_f32 v[124:125], v[124:125], v[244:245]
	v_cvt_pk_bf16_f32 v130, v126, v127
	v_cvt_pk_bf16_f32 v131, v128, v129
	v_cvt_pk_bf16_f32 v132, v122, v123
	v_cvt_pk_bf16_f32 v133, v124, v125
	global_store_dwordx4 v[198:199], v[130:133], off
	v_pk_mul_f32 v[238:239], v[122:123], v[122:123]
	v_pk_mul_f32 v[240:241], v[124:125], v[124:125]
	v_pk_fma_f32 v[238:239], v[126:127], v[126:127], v[238:239]
	v_pk_fma_f32 v[240:241], v[128:129], v[128:129], v[240:241]
	s_nop 0
	v_add_f32_e32 v238, v238, v239
	v_add_f32_e32 v239, v240, v241
	v_add_f32_e32 v126, v238, v239
	s_waitcnt vmcnt(15)
	v_lshlrev_b32_e32 v238, 16, v134
	v_and_b32_e32 v239, 0xffff0000, v134
	v_lshlrev_b32_e32 v240, 16, v135
	v_and_b32_e32 v241, 0xffff0000, v135
	v_lshlrev_b32_e32 v242, 16, v136
	v_and_b32_e32 v243, 0xffff0000, v136
	v_lshlrev_b32_e32 v244, 16, v137
	v_and_b32_e32 v245, 0xffff0000, v137
	v_pk_add_f32 v[118:119], v[118:119], v[238:239]
	v_pk_add_f32 v[120:121], v[120:121], v[240:241]
	v_pk_add_f32 v[114:115], v[114:115], v[242:243]
	v_pk_add_f32 v[116:117], v[116:117], v[244:245]
	v_cvt_pk_bf16_f32 v134, v118, v119
	v_cvt_pk_bf16_f32 v135, v120, v121
	v_cvt_pk_bf16_f32 v136, v114, v115
	v_cvt_pk_bf16_f32 v137, v116, v117
	global_store_dwordx4 v[198:199], v[134:137], off offset:256
	v_pk_mul_f32 v[238:239], v[114:115], v[114:115]
	v_pk_mul_f32 v[240:241], v[116:117], v[116:117]
	v_pk_fma_f32 v[238:239], v[118:119], v[118:119], v[238:239]
	v_pk_fma_f32 v[240:241], v[120:121], v[120:121], v[240:241]
	s_nop 0
	v_add_f32_e32 v238, v238, v239
	v_add_f32_e32 v239, v240, v241
	v_add_f32_e32 v238, v238, v239
	v_add_f32_e32 v126, v126, v238
	s_and_b64 vcc, exec, s[12:13]
	s_cbranch_vccz .LBB0_45
	s_barrier
.LBB0_45:
	v_lshl_add_u64 v[198:199], v[198:199], 0, s[22:23]
	s_waitcnt vmcnt(15)
	v_lshlrev_b32_e32 v238, 16, v138
	v_and_b32_e32 v239, 0xffff0000, v138
	v_lshlrev_b32_e32 v240, 16, v139
	v_and_b32_e32 v241, 0xffff0000, v139
	v_lshlrev_b32_e32 v242, 16, v140
	v_and_b32_e32 v243, 0xffff0000, v140
	v_lshlrev_b32_e32 v244, 16, v141
	v_and_b32_e32 v245, 0xffff0000, v141
	v_pk_add_f32 v[110:111], v[110:111], v[238:239]
	v_pk_add_f32 v[112:113], v[112:113], v[240:241]
	v_pk_add_f32 v[106:107], v[106:107], v[242:243]
	v_pk_add_f32 v[108:109], v[108:109], v[244:245]
	v_cvt_pk_bf16_f32 v138, v110, v111
	v_cvt_pk_bf16_f32 v139, v112, v113
	v_cvt_pk_bf16_f32 v140, v106, v107
	v_cvt_pk_bf16_f32 v141, v108, v109
	global_store_dwordx4 v[198:199], v[138:141], off
	v_pk_mul_f32 v[238:239], v[106:107], v[106:107]
	v_pk_mul_f32 v[240:241], v[108:109], v[108:109]
	v_pk_fma_f32 v[238:239], v[110:111], v[110:111], v[238:239]
	v_pk_fma_f32 v[240:241], v[112:113], v[112:113], v[240:241]
	s_nop 0
	v_add_f32_e32 v238, v238, v239
	v_add_f32_e32 v239, v240, v241
	v_add_f32_e32 v110, v238, v239
	s_waitcnt vmcnt(15)
	v_lshlrev_b32_e32 v238, 16, v142
	v_and_b32_e32 v239, 0xffff0000, v142
	v_lshlrev_b32_e32 v240, 16, v143
	v_and_b32_e32 v241, 0xffff0000, v143
	v_lshlrev_b32_e32 v242, 16, v144
	v_and_b32_e32 v243, 0xffff0000, v144
	v_lshlrev_b32_e32 v244, 16, v145
	v_and_b32_e32 v245, 0xffff0000, v145
	v_pk_add_f32 v[102:103], v[102:103], v[238:239]
	v_pk_add_f32 v[104:105], v[104:105], v[240:241]
	v_pk_add_f32 v[98:99], v[98:99], v[242:243]
	v_pk_add_f32 v[100:101], v[100:101], v[244:245]
	v_cvt_pk_bf16_f32 v142, v102, v103
	v_cvt_pk_bf16_f32 v143, v104, v105
	v_cvt_pk_bf16_f32 v144, v98, v99
	v_cvt_pk_bf16_f32 v145, v100, v101
	global_store_dwordx4 v[198:199], v[142:145], off offset:256
	v_pk_mul_f32 v[238:239], v[98:99], v[98:99]
	v_pk_mul_f32 v[240:241], v[100:101], v[100:101]
	v_pk_fma_f32 v[238:239], v[102:103], v[102:103], v[238:239]
	v_pk_fma_f32 v[240:241], v[104:105], v[104:105], v[240:241]
	s_nop 0
	v_add_f32_e32 v238, v238, v239
	v_add_f32_e32 v239, v240, v241
	v_add_f32_e32 v238, v238, v239
	v_add_f32_e32 v110, v110, v238
	v_lshl_add_u64 v[198:199], v[198:199], 0, s[22:23]
	s_waitcnt vmcnt(15)
	v_lshlrev_b32_e32 v238, 16, v146
	v_and_b32_e32 v239, 0xffff0000, v146
	v_lshlrev_b32_e32 v240, 16, v147
	v_and_b32_e32 v241, 0xffff0000, v147
	v_lshlrev_b32_e32 v242, 16, v148
	v_and_b32_e32 v243, 0xffff0000, v148
	v_lshlrev_b32_e32 v244, 16, v149
	v_and_b32_e32 v245, 0xffff0000, v149
	v_pk_add_f32 v[94:95], v[94:95], v[238:239]
	v_pk_add_f32 v[96:97], v[96:97], v[240:241]
	v_pk_add_f32 v[90:91], v[90:91], v[242:243]
	v_pk_add_f32 v[92:93], v[92:93], v[244:245]
	v_cvt_pk_bf16_f32 v146, v94, v95
	v_cvt_pk_bf16_f32 v147, v96, v97
	v_cvt_pk_bf16_f32 v148, v90, v91
	v_cvt_pk_bf16_f32 v149, v92, v93
	global_store_dwordx4 v[198:199], v[146:149], off
	v_pk_mul_f32 v[238:239], v[90:91], v[90:91]
	v_pk_mul_f32 v[240:241], v[92:93], v[92:93]
	v_pk_fma_f32 v[238:239], v[94:95], v[94:95], v[238:239]
	v_pk_fma_f32 v[240:241], v[96:97], v[96:97], v[240:241]
	s_nop 0
	v_add_f32_e32 v238, v238, v239
	v_add_f32_e32 v239, v240, v241
	v_add_f32_e32 v94, v238, v239
	s_waitcnt vmcnt(15)
; __device__ __forceinline__ unsigned cvt_pk_bf16(float lo, float hi) { f32x2_cv v = {lo, hi}; bf16x2_cv b = __builtin_convertvector(v, bf16x2_cv); return __builtin_bit_cast(unsigned, b); }
;     __device__ __forceinline__ void operator()(const f32x4 (&acc)[2][2][4][2], const Unit& u, int wr, int wc, int fr, int fq) const {
;     ...
;             for (int m = 0; m < 4; ++m) {
;                 const int row = row0 + ai * HALF + m * 16; float ss = 0.f;
; #pragma unroll
;                 for (int bj = 0; bj < 2; ++bj) {
;                     const size_t off = (size_t)row * 1024 + col0 + bj * HALF;
;                     const u32x4 v = xv[m][bj];
;                     f32x4 x0 = {__uint_as_float(v.x << 16), __uint_as_float(v.x & 0xffff0000u), __uint_as_float(v.y << 16), __uint_as_float(v.y & 0xffff0000u)};
;                     f32x4 x1 = {__uint_as_float(v.z << 16), __uint_as_float(v.z & 0xffff0000u), __uint_as_float(v.w << 16), __uint_as_float(v.w & 0xffff0000u)};
;                     x0 = x0 + acc[ai][bj][m][0] * alpha; x1 = x1 + acc[ai][bj][m][1] * alpha;
;                     u32x4 w; w.x = cvt_pk_bf16(x0[0], x0[1]); w.y = cvt_pk_bf16(x0[2], x0[3]); w.z = cvt_pk_bf16(x1[0], x1[1]); w.w = cvt_pk_bf16(x1[2], x1[3]);
;                     *(u32x4*)(XB + off) = w;
;                     const f32x4 sq = x0 * x0 + x1 * x1;
;                     ss += (sq[0] + sq[1]) + (sq[2] + sq[3]);
;                 }
	v_lshlrev_b32_e32 v238, 16, v150
	v_and_b32_e32 v239, 0xffff0000, v150
	v_lshlrev_b32_e32 v240, 16, v151
	v_and_b32_e32 v241, 0xffff0000, v151
	v_lshlrev_b32_e32 v242, 16, v152
	v_and_b32_e32 v243, 0xffff0000, v152
	v_lshlrev_b32_e32 v244, 16, v153
	v_and_b32_e32 v245, 0xffff0000, v153
	v_pk_add_f32 v[86:87], v[86:87], v[238:239]
	v_pk_add_f32 v[88:89], v[88:89], v[240:241]
	v_pk_add_f32 v[82:83], v[82:83], v[242:243]
	v_pk_add_f32 v[84:85], v[84:85], v[244:245]
	v_cvt_pk_bf16_f32 v150, v86, v87
	v_cvt_pk_bf16_f32 v151, v88, v89
	v_cvt_pk_bf16_f32 v152, v82, v83
	v_cvt_pk_bf16_f32 v153, v84, v85
	global_store_dwordx4 v[198:199], v[150:153], off offset:256
	v_pk_mul_f32 v[238:239], v[82:83], v[82:83]
	v_pk_mul_f32 v[240:241], v[84:85], v[84:85]
	v_pk_fma_f32 v[238:239], v[86:87], v[86:87], v[238:239]
	v_pk_fma_f32 v[240:241], v[88:89], v[88:89], v[240:241]
	s_nop 0
	v_add_f32_e32 v238, v238, v239
	v_add_f32_e32 v239, v240, v241
	v_add_f32_e32 v238, v238, v239
	v_add_f32_e32 v94, v94, v238
	v_lshl_add_u64 v[198:199], v[198:199], 0, s[22:23]
	s_waitcnt vmcnt(15)
	v_lshlrev_b32_e32 v238, 16, v154
	v_and_b32_e32 v239, 0xffff0000, v154
	v_lshlrev_b32_e32 v240, 16, v155
	v_and_b32_e32 v241, 0xffff0000, v155
	v_lshlrev_b32_e32 v242, 16, v156
	v_and_b32_e32 v243, 0xffff0000, v156
	v_lshlrev_b32_e32 v244, 16, v157
	v_and_b32_e32 v245, 0xffff0000, v157
	v_pk_add_f32 v[78:79], v[78:79], v[238:239]
	v_pk_add_f32 v[80:81], v[80:81], v[240:241]
	v_pk_add_f32 v[74:75], v[74:75], v[242:243]
	v_pk_add_f32 v[76:77], v[76:77], v[244:245]
	v_cvt_pk_bf16_f32 v154, v78, v79
	v_cvt_pk_bf16_f32 v155, v80, v81
	v_cvt_pk_bf16_f32 v156, v74, v75
	v_cvt_pk_bf16_f32 v157, v76, v77
	global_store_dwordx4 v[198:199], v[154:157], off
	v_pk_mul_f32 v[238:239], v[74:75], v[74:75]
	v_pk_mul_f32 v[240:241], v[76:77], v[76:77]
	v_pk_fma_f32 v[238:239], v[78:79], v[78:79], v[238:239]
	v_pk_fma_f32 v[240:241], v[80:81], v[80:81], v[240:241]
	s_nop 0
	v_add_f32_e32 v238, v238, v239
	v_add_f32_e32 v239, v240, v241
	v_add_f32_e32 v78, v238, v239
	s_waitcnt vmcnt(15)
	v_lshlrev_b32_e32 v238, 16, v218
	v_and_b32_e32 v239, 0xffff0000, v218
	v_lshlrev_b32_e32 v240, 16, v219
	v_and_b32_e32 v241, 0xffff0000, v219
	v_lshlrev_b32_e32 v242, 16, v220
	v_and_b32_e32 v243, 0xffff0000, v220
	v_lshlrev_b32_e32 v244, 16, v221
	v_and_b32_e32 v245, 0xffff0000, v221
	v_pk_add_f32 v[70:71], v[70:71], v[238:239]
	v_pk_add_f32 v[72:73], v[72:73], v[240:241]
	v_pk_add_f32 v[66:67], v[66:67], v[242:243]
	v_pk_add_f32 v[68:69], v[68:69], v[244:245]
	v_cvt_pk_bf16_f32 v218, v70, v71
	v_cvt_pk_bf16_f32 v219, v72, v73
	v_cvt_pk_bf16_f32 v220, v66, v67
	v_cvt_pk_bf16_f32 v221, v68, v69
	global_store_dwordx4 v[198:199], v[218:221], off offset:256
	v_pk_mul_f32 v[238:239], v[66:67], v[66:67]
	v_pk_mul_f32 v[240:241], v[68:69], v[68:69]
	v_pk_fma_f32 v[238:239], v[70:71], v[70:71], v[238:239]
	v_pk_fma_f32 v[240:241], v[72:73], v[72:73], v[240:241]
	s_nop 0
	v_add_f32_e32 v238, v238, v239
	v_add_f32_e32 v239, v240, v241
	v_add_f32_e32 v238, v238, v239
	v_add_f32_e32 v78, v78, v238
	v_lshl_add_u64 v[198:199], v[198:199], 0, s[88:89]
	s_waitcnt vmcnt(15)
	v_lshlrev_b32_e32 v238, 16, v182
	v_and_b32_e32 v239, 0xffff0000, v182
	v_lshlrev_b32_e32 v240, 16, v183
	v_and_b32_e32 v241, 0xffff0000, v183
	v_lshlrev_b32_e32 v242, 16, v184
	v_and_b32_e32 v243, 0xffff0000, v184
	v_lshlrev_b32_e32 v244, 16, v185
	v_and_b32_e32 v245, 0xffff0000, v185
	v_pk_add_f32 v[62:63], v[62:63], v[238:239]
	v_pk_add_f32 v[64:65], v[64:65], v[240:241]
	v_pk_add_f32 v[58:59], v[58:59], v[242:243]
	v_pk_add_f32 v[60:61], v[60:61], v[244:245]
	v_cvt_pk_bf16_f32 v182, v62, v63
	v_cvt_pk_bf16_f32 v183, v64, v65
	v_cvt_pk_bf16_f32 v184, v58, v59
	v_cvt_pk_bf16_f32 v185, v60, v61
	global_store_dwordx4 v[198:199], v[182:185], off
	v_pk_mul_f32 v[238:239], v[58:59], v[58:59]
	v_pk_mul_f32 v[240:241], v[60:61], v[60:61]
	v_pk_fma_f32 v[238:239], v[62:63], v[62:63], v[238:239]
	v_pk_fma_f32 v[240:241], v[64:65], v[64:65], v[240:241]
	s_nop 0
	v_add_f32_e32 v238, v238, v239
	v_add_f32_e32 v239, v240, v241
	v_add_f32_e32 v62, v238, v239
	s_waitcnt vmcnt(15)
	v_lshlrev_b32_e32 v238, 16, v186
	v_and_b32_e32 v239, 0xffff0000, v186
	v_lshlrev_b32_e32 v240, 16, v187
	v_and_b32_e32 v241, 0xffff0000, v187
	v_lshlrev_b32_e32 v242, 16, v188
	v_and_b32_e32 v243, 0xffff0000, v188
	v_lshlrev_b32_e32 v244, 16, v189
	v_and_b32_e32 v245, 0xffff0000, v189
	v_pk_add_f32 v[54:55], v[54:55], v[238:239]
	v_pk_add_f32 v[56:57], v[56:57], v[240:241]
	v_pk_add_f32 v[50:51], v[50:51], v[242:243]
	v_pk_add_f32 v[52:53], v[52:53], v[244:245]
	v_cvt_pk_bf16_f32 v186, v54, v55
	v_cvt_pk_bf16_f32 v187, v56, v57
	v_cvt_pk_bf16_f32 v188, v50, v51
	v_cvt_pk_bf16_f32 v189, v52, v53
	global_store_dwordx4 v[198:199], v[186:189], off offset:256
	v_pk_mul_f32 v[238:239], v[50:51], v[50:51]
	v_pk_mul_f32 v[240:241], v[52:53], v[52:53]
	v_pk_fma_f32 v[238:239], v[54:55], v[54:55], v[238:239]
	v_pk_fma_f32 v[240:241], v[56:57], v[56:57], v[240:241]
	s_nop 0
	v_add_f32_e32 v238, v238, v239
	v_add_f32_e32 v239, v240, v241
	v_add_f32_e32 v238, v238, v239
	v_add_f32_e32 v62, v62, v238
	v_lshl_add_u64 v[198:199], v[198:199], 0, s[22:23]
	s_waitcnt vmcnt(15)
; __device__ __forceinline__ unsigned cvt_pk_bf16(float lo, float hi) { f32x2_cv v = {lo, hi}; bf16x2_cv b = __builtin_convertvector(v, bf16x2_cv); return __builtin_bit_cast(unsigned, b); }
;     __device__ __forceinline__ void operator()(const f32x4 (&acc)[2][2][4][2], const Unit& u, int wr, int wc, int fr, int fq) const {
;     ...
;             for (int m = 0; m < 4; ++m) {
;                 const int row = row0 + ai * HALF + m * 16; float ss = 0.f;
; #pragma unroll
;                 for (int bj = 0; bj < 2; ++bj) {
;                     const size_t off = (size_t)row * 1024 + col0 + bj * HALF;
;                     const u32x4 v = xv[m][bj];
;                     f32x4 x0 = {__uint_as_float(v.x << 16), __uint_as_float(v.x & 0xffff0000u), __uint_as_float(v.y << 16), __uint_as_float(v.y & 0xffff0000u)};
;                     f32x4 x1 = {__uint_as_float(v.z << 16), __uint_as_float(v.z & 0xffff0000u), __uint_as_float(v.w << 16), __uint_as_float(v.w & 0xffff0000u)};
;                     x0 = x0 + acc[ai][bj][m][0] * alpha; x1 = x1 + acc[ai][bj][m][1] * alpha;
;                     u32x4 w; w.x = cvt_pk_bf16(x0[0], x0[1]); w.y = cvt_pk_bf16(x0[2], x0[3]); w.z = cvt_pk_bf16(x1[0], x1[1]); w.w = cvt_pk_bf16(x1[2], x1[3]);
;                     *(u32x4*)(XB + off) = w;
;                     const f32x4 sq = x0 * x0 + x1 * x1;
;                     ss += (sq[0] + sq[1]) + (sq[2] + sq[3]);
;                 }
	v_lshlrev_b32_e32 v238, 16, v190
	v_and_b32_e32 v239, 0xffff0000, v190
	v_lshlrev_b32_e32 v240, 16, v191
	v_and_b32_e32 v241, 0xffff0000, v191
	v_lshlrev_b32_e32 v242, 16, v192
	v_and_b32_e32 v243, 0xffff0000, v192
	v_lshlrev_b32_e32 v244, 16, v193
	v_and_b32_e32 v245, 0xffff0000, v193
	v_pk_add_f32 v[46:47], v[46:47], v[238:239]
	v_pk_add_f32 v[48:49], v[48:49], v[240:241]
	v_pk_add_f32 v[42:43], v[42:43], v[242:243]
	v_pk_add_f32 v[44:45], v[44:45], v[244:245]
	v_cvt_pk_bf16_f32 v190, v46, v47
	v_cvt_pk_bf16_f32 v191, v48, v49
	v_cvt_pk_bf16_f32 v192, v42, v43
	v_cvt_pk_bf16_f32 v193, v44, v45
	global_store_dwordx4 v[198:199], v[190:193], off
	v_pk_mul_f32 v[238:239], v[42:43], v[42:43]
	v_pk_mul_f32 v[240:241], v[44:45], v[44:45]
	v_pk_fma_f32 v[238:239], v[46:47], v[46:47], v[238:239]
	v_pk_fma_f32 v[240:241], v[48:49], v[48:49], v[240:241]
	s_nop 0
	v_add_f32_e32 v238, v238, v239
	v_add_f32_e32 v239, v240, v241
	v_add_f32_e32 v46, v238, v239
	s_waitcnt vmcnt(15)
	v_lshlrev_b32_e32 v238, 16, v194
	v_and_b32_e32 v239, 0xffff0000, v194
	v_lshlrev_b32_e32 v240, 16, v195
	v_and_b32_e32 v241, 0xffff0000, v195
	v_lshlrev_b32_e32 v242, 16, v196
	v_and_b32_e32 v243, 0xffff0000, v196
	v_lshlrev_b32_e32 v244, 16, v197
	v_and_b32_e32 v245, 0xffff0000, v197
	v_pk_add_f32 v[38:39], v[38:39], v[238:239]
	v_pk_add_f32 v[40:41], v[40:41], v[240:241]
	v_pk_add_f32 v[34:35], v[34:35], v[242:243]
	v_pk_add_f32 v[36:37], v[36:37], v[244:245]
	v_cvt_pk_bf16_f32 v194, v38, v39
	v_cvt_pk_bf16_f32 v195, v40, v41
	v_cvt_pk_bf16_f32 v196, v34, v35
	v_cvt_pk_bf16_f32 v197, v36, v37
	global_store_dwordx4 v[198:199], v[194:197], off offset:256
	v_pk_mul_f32 v[238:239], v[34:35], v[34:35]
	v_pk_mul_f32 v[240:241], v[36:37], v[36:37]
	v_pk_fma_f32 v[238:239], v[38:39], v[38:39], v[238:239]
	v_pk_fma_f32 v[240:241], v[40:41], v[40:41], v[240:241]
	s_nop 0
	v_add_f32_e32 v238, v238, v239
	v_add_f32_e32 v239, v240, v241
	v_add_f32_e32 v238, v238, v239
	v_add_f32_e32 v46, v46, v238
	v_lshl_add_u64 v[198:199], v[198:199], 0, s[22:23]
	s_waitcnt vmcnt(15)
	v_lshlrev_b32_e32 v238, 16, v222
	v_and_b32_e32 v239, 0xffff0000, v222
	v_lshlrev_b32_e32 v240, 16, v223
	v_and_b32_e32 v241, 0xffff0000, v223
	v_lshlrev_b32_e32 v242, 16, v224
	v_and_b32_e32 v243, 0xffff0000, v224
	v_lshlrev_b32_e32 v244, 16, v225
	v_and_b32_e32 v245, 0xffff0000, v225
	v_pk_add_f32 v[30:31], v[30:31], v[238:239]
	v_pk_add_f32 v[32:33], v[32:33], v[240:241]
	v_pk_add_f32 v[26:27], v[26:27], v[242:243]
	v_pk_add_f32 v[28:29], v[28:29], v[244:245]
	v_cvt_pk_bf16_f32 v222, v30, v31
	v_cvt_pk_bf16_f32 v223, v32, v33
	v_cvt_pk_bf16_f32 v224, v26, v27
	v_cvt_pk_bf16_f32 v225, v28, v29
	global_store_dwordx4 v[198:199], v[222:225], off
	v_pk_mul_f32 v[238:239], v[26:27], v[26:27]
	v_pk_mul_f32 v[240:241], v[28:29], v[28:29]
	v_pk_fma_f32 v[238:239], v[30:31], v[30:31], v[238:239]
	v_pk_fma_f32 v[240:241], v[32:33], v[32:33], v[240:241]
	s_nop 0
	v_add_f32_e32 v238, v238, v239
	v_add_f32_e32 v239, v240, v241
	v_add_f32_e32 v30, v238, v239
	s_waitcnt vmcnt(15)
	v_lshlrev_b32_e32 v238, 16, v226
	v_and_b32_e32 v239, 0xffff0000, v226
	v_lshlrev_b32_e32 v240, 16, v227
	v_and_b32_e32 v241, 0xffff0000, v227
	v_lshlrev_b32_e32 v242, 16, v228
	v_and_b32_e32 v243, 0xffff0000, v228
	v_lshlrev_b32_e32 v244, 16, v229
	v_and_b32_e32 v245, 0xffff0000, v229
	v_pk_add_f32 v[22:23], v[22:23], v[238:239]
	v_pk_add_f32 v[24:25], v[24:25], v[240:241]
	v_pk_add_f32 v[18:19], v[18:19], v[242:243]
	v_pk_add_f32 v[20:21], v[20:21], v[244:245]
	v_cvt_pk_bf16_f32 v226, v22, v23
	v_cvt_pk_bf16_f32 v227, v24, v25
	v_cvt_pk_bf16_f32 v228, v18, v19
	v_cvt_pk_bf16_f32 v229, v20, v21
	global_store_dwordx4 v[198:199], v[226:229], off offset:256
	v_pk_mul_f32 v[238:239], v[18:19], v[18:19]
	v_pk_mul_f32 v[240:241], v[20:21], v[20:21]
	v_pk_fma_f32 v[238:239], v[22:23], v[22:23], v[238:239]
	v_pk_fma_f32 v[240:241], v[24:25], v[24:25], v[240:241]
	s_nop 0
	v_add_f32_e32 v238, v238, v239
	v_add_f32_e32 v239, v240, v241
	v_add_f32_e32 v238, v238, v239
	v_add_f32_e32 v30, v30, v238
	v_lshl_add_u64 v[198:199], v[198:199], 0, s[22:23]
	s_waitcnt vmcnt(15)
; __device__ __forceinline__ unsigned cvt_pk_bf16(float lo, float hi) { f32x2_cv v = {lo, hi}; bf16x2_cv b = __builtin_convertvector(v, bf16x2_cv); return __builtin_bit_cast(unsigned, b); }
;     __device__ __forceinline__ void operator()(const f32x4 (&acc)[2][2][4][2], const Unit& u, int wr, int wc, int fr, int fq) const {
;     ...
;                 for (int bj = 0; bj < 2; ++bj) {
;                     const size_t off = (size_t)row * 1024 + col0 + bj * HALF;
;                     const u32x4 v = xv[m][bj];
;                     f32x4 x0 = {__uint_as_float(v.x << 16), __uint_as_float(v.x & 0xffff0000u), __uint_as_float(v.y << 16), __uint_as_float(v.y & 0xffff0000u)};
;                     f32x4 x1 = {__uint_as_float(v.z << 16), __uint_as_float(v.z & 0xffff0000u), __uint_as_float(v.w << 16), __uint_as_float(v.w & 0xffff0000u)};
;                     x0 = x0 + acc[ai][bj][m][0] * alpha; x1 = x1 + acc[ai][bj][m][1] * alpha;
;                     u32x4 w; w.x = cvt_pk_bf16(x0[0], x0[1]); w.y = cvt_pk_bf16(x0[2], x0[3]); w.z = cvt_pk_bf16(x1[0], x1[1]); w.w = cvt_pk_bf16(x1[2], x1[3]);
;                     *(u32x4*)(XB + off) = w;
;                     const f32x4 sq = x0 * x0 + x1 * x1;
;                     ss += (sq[0] + sq[1]) + (sq[2] + sq[3]);
;                 }
;                 ss += __shfl_xor(ss, 16); ss += __shfl_xor(ss, 32);
;                 if (fq == 0) rsp_out[(size_t)row * 16 + u.pn * 4 + wc] = ss;
;             }
	v_lshlrev_b32_e32 v238, 16, v230
	v_and_b32_e32 v239, 0xffff0000, v230
	v_lshlrev_b32_e32 v240, 16, v231
	v_and_b32_e32 v241, 0xffff0000, v231
	v_lshlrev_b32_e32 v242, 16, v232
	v_and_b32_e32 v243, 0xffff0000, v232
	v_lshlrev_b32_e32 v244, 16, v233
	v_and_b32_e32 v245, 0xffff0000, v233
	v_pk_add_f32 v[14:15], v[14:15], v[238:239]
	v_pk_add_f32 v[16:17], v[16:17], v[240:241]
	v_pk_add_f32 v[10:11], v[10:11], v[242:243]
	v_pk_add_f32 v[12:13], v[12:13], v[244:245]
	v_cvt_pk_bf16_f32 v230, v14, v15
	v_cvt_pk_bf16_f32 v231, v16, v17
	v_cvt_pk_bf16_f32 v232, v10, v11
	v_cvt_pk_bf16_f32 v233, v12, v13
	global_store_dwordx4 v[198:199], v[230:233], off
	v_pk_mul_f32 v[238:239], v[10:11], v[10:11]
	v_pk_mul_f32 v[240:241], v[12:13], v[12:13]
	v_pk_fma_f32 v[238:239], v[14:15], v[14:15], v[238:239]
	v_pk_fma_f32 v[240:241], v[16:17], v[16:17], v[240:241]
	s_nop 0
	v_add_f32_e32 v238, v238, v239
	v_add_f32_e32 v239, v240, v241
	v_add_f32_e32 v14, v238, v239
	s_waitcnt vmcnt(15)
	v_lshlrev_b32_e32 v238, 16, v234
	v_and_b32_e32 v239, 0xffff0000, v234
	v_lshlrev_b32_e32 v240, 16, v235
	v_and_b32_e32 v241, 0xffff0000, v235
	v_lshlrev_b32_e32 v242, 16, v236
	v_and_b32_e32 v243, 0xffff0000, v236
	v_lshlrev_b32_e32 v244, 16, v237
	v_and_b32_e32 v245, 0xffff0000, v237
	v_pk_add_f32 v[6:7], v[6:7], v[238:239]
	v_pk_add_f32 v[8:9], v[8:9], v[240:241]
	v_pk_add_f32 v[2:3], v[2:3], v[242:243]
	v_pk_add_f32 v[4:5], v[4:5], v[244:245]
	v_cvt_pk_bf16_f32 v234, v6, v7
	v_cvt_pk_bf16_f32 v235, v8, v9
	v_cvt_pk_bf16_f32 v236, v2, v3
	v_cvt_pk_bf16_f32 v237, v4, v5
	global_store_dwordx4 v[198:199], v[234:237], off offset:256
	v_pk_mul_f32 v[238:239], v[2:3], v[2:3]
	v_pk_mul_f32 v[240:241], v[4:5], v[4:5]
	v_pk_fma_f32 v[238:239], v[6:7], v[6:7], v[238:239]
	v_pk_fma_f32 v[240:241], v[8:9], v[8:9], v[240:241]
	s_nop 0
	v_add_f32_e32 v238, v238, v239
	v_add_f32_e32 v239, v240, v241
	v_add_f32_e32 v238, v238, v239
	v_add_f32_e32 v14, v14, v238
	ds_bpermute_b32 v127, v215, v126
	ds_bpermute_b32 v111, v215, v110
	ds_bpermute_b32 v95, v215, v94
	ds_bpermute_b32 v79, v215, v78
	ds_bpermute_b32 v63, v215, v62
	ds_bpermute_b32 v47, v215, v46
	ds_bpermute_b32 v31, v215, v30
	ds_bpermute_b32 v15, v215, v14
	s_waitcnt lgkmcnt(0)
	v_add_f32_e32 v126, v126, v127
	v_add_f32_e32 v110, v110, v111
	v_add_f32_e32 v94, v94, v95
	v_add_f32_e32 v78, v78, v79
	v_add_f32_e32 v62, v62, v63
	v_add_f32_e32 v46, v46, v47
	v_add_f32_e32 v30, v30, v31
	v_add_f32_e32 v14, v14, v15
	ds_bpermute_b32 v127, v216, v126
	ds_bpermute_b32 v111, v216, v110
	ds_bpermute_b32 v95, v216, v94
	ds_bpermute_b32 v79, v216, v78
	ds_bpermute_b32 v63, v216, v62
	ds_bpermute_b32 v47, v216, v46
	ds_bpermute_b32 v31, v216, v30
	ds_bpermute_b32 v15, v216, v14
	s_waitcnt lgkmcnt(0)
	v_add_f32_e32 v126, v126, v127
	v_add_f32_e32 v110, v110, v111
	v_add_f32_e32 v94, v94, v95
	v_add_f32_e32 v78, v78, v79
	v_add_f32_e32 v62, v62, v63
	v_add_f32_e32 v46, v46, v47
	v_add_f32_e32 v30, v30, v31
	v_add_f32_e32 v14, v14, v15
	s_lshl_b32 s22, s9, 4
	s_lshl_b32 s88, s35, 2
	s_add_i32 s22, s22, s88
	v_lshlrev_b32_e32 v246, 6, v217
	v_mov_b32_e32 v247, 0
	v_lshl_add_u64 v[246:247], s[76:77], 0, v[246:247]
	v_lshl_add_u64 v[246:247], v[246:247], 0, s[22:23]
	s_mov_b32 s22, 0x2000
	v_lshl_add_u64 v[198:199], v[246:247], 0, s[22:23]
	s_and_saveexec_b64 s[24:25], s[4:5]
	global_store_dword v[246:247], v126, off
	global_store_dword v[246:247], v110, off offset:1024
	global_store_dword v[246:247], v94, off offset:2048
	global_store_dword v[246:247], v78, off offset:3072
	global_store_dword v[198:199], v62, off
	global_store_dword v[198:199], v46, off offset:1024
	global_store_dword v[198:199], v30, off offset:2048
	global_store_dword v[198:199], v14, off offset:3072
	s_or_b64 exec, exec, s[24:25]
	s_andn2_b64 vcc, exec, s[6:7]
	s_mov_b64 s[6:7], -1
	s_cbranch_vccnz .LBB0_34
	s_andn2_b64 vcc, exec, s[10:11]
	s_cbranch_vccnz .LBB0_33
	s_barrier
	s_branch .LBB0_33

; #define PG8_STAGE(bufoff, gbase, voff) do { _Pragma("unroll") for (int _i = 0; _i < 2; ++_i) \
;         __builtin_amdgcn_global_load_lds((const unsigned*)((const char*)(gbase) + (voff)[_i]), (PG8_LAS unsigned*)(lds + (bufoff) + ldsw + _i * 8192), 16, 0, 0); } while (0)
; #define PG8_LDA(dst, b, h) do { _Pragma("unroll") for (int m = 0; m < 4; ++m) _Pragma("unroll") for (int k = 0; k < 2; ++k) dst[m][k] = *(const PG8_LAS bf16x8*)(lds + PG8_SA(b, h) + aoff + m * 2048 + k * 1024); } while (0)
; #define PG8_LDB(dst, b, h) do { _Pragma("unroll") for (int n = 0; n < 2; ++n) _Pragma("unroll") for (int k = 0; k < 2; ++k) dst[n][k] = *(const PG8_LAS bf16x8*)(lds + PG8_SB(b, h) + boff + n * 2048 + k * 1024); } while (0)
; #define PG8_MMA(ai, bj, At, Bt) do { __builtin_amdgcn_s_setprio(1); _Pragma("unroll") for (int m = 0; m < 4; ++m) _Pragma("unroll") for (int n = 0; n < 2; ++n) _Pragma("unroll") for (int k = 0; k < 2; ++k) \
;         acc[ai][bj][m][n] = __builtin_amdgcn_mfma_f32_16x16x32_bf16(Bt[n][k], At[m][k], acc[ai][bj][m][n], 0, 0, 0); __builtin_amdgcn_s_setprio(0); } while (0)
; #define PG8_WAIT_V(n) asm volatile("s_waitcnt vmcnt(" #n ")" ::: "memory")
; #define PG8_WAIT_L(n) asm volatile("s_waitcnt lgkmcnt(" #n ")" ::: "memory")
; #define PG8_BAR __builtin_amdgcn_s_barrier()
; #define PG8_SCHED __builtin_amdgcn_sched_barrier(0)
; template <class Epi, class Sched, bool ALIGN_EPI = false, bool SP2 = false>
; __device__ __forceinline__ void gemm_phase(PG8_LAS unsigned char* lds, const Gemm g, const Sched& S, const Epi& E) {
;     ...
;             PG8_LDB(B0, 0, 0); PG8_LDB(B1, 0, 1); PG8_SCHED; PG8_LDA(At, 0, 0); PG8_STAGE(PG8_SA(1, 1), a1 + hstep, voffA);
;             PG8_WAIT_V(8); PG8_WAIT_L(0); PG8_BAR; PG8_MMA(0, 0, At, B0); PG8_MMA(0, 1, At, B1); PG8_BAR; PG8_SCHED;
;             PG8_LDA(At, 0, 1); PG8_STAGE(PG8_SB(0, 0), b2, voffB); PG8_STAGE(PG8_SB(0, 1), b2 + hstep, voffB); PG8_STAGE(PG8_SA(0, 0), a2, voffA);
;             PG8_WAIT_V(8); PG8_WAIT_L(0); PG8_BAR; PG8_MMA(1, 0, At, B0); PG8_MMA(1, 1, At, B1); PG8_BAR; PG8_SCHED;
;             PG8_LDB(B0, 1, 0); PG8_LDB(B1, 1, 1); PG8_SCHED; PG8_LDA(At, 1, 0); PG8_STAGE(PG8_SA(0, 1), a2 + hstep, voffA);
;             PG8_WAIT_V(8); PG8_WAIT_L(0); PG8_BAR; PG8_MMA(0, 0, At, B0); PG8_MMA(0, 1, At, B1); PG8_BAR; PG8_SCHED;
.LBB0_459:
	s_add_u32 s20, s18, 0x100
	s_addc_u32 s21, s19, 0
	s_add_i32 s50, 0, 0x10000
	s_cmp_eq_u32 s49, 40
	s_cselect_b32 s25, s9, s21
	s_cselect_b32 s24, s8, s20
	s_cselect_b32 s23, s17, s48
	s_cselect_b32 s22, s16, s47
	s_add_i32 s51, 0, 0x14000
	v_add_u32_e32 v142, s50, v165
	v_add_u32_e32 v182, s51, v165
	ds_read_b128 v[130:133], v142
	ds_read_b128 v[134:137], v142 offset:1024
	ds_read_b128 v[138:141], v142 offset:2048
	ds_read_b128 v[142:145], v142 offset:3072
	ds_read_b128 v[146:149], v182
	ds_read_b128 v[150:153], v182 offset:1024
	ds_read_b128 v[154:157], v182 offset:2048
	ds_read_b128 v[182:185], v182 offset:3072
	s_add_i32 m0, s28, 0xc000
	ds_read_b128 v[186:189], v214
	ds_read_b128 v[190:193], v214 offset:1024
	ds_read_b128 v[194:197], v214 offset:2048
	ds_read_b128 v[216:219], v214 offset:3072
	ds_read_b128 v[220:223], v214 offset:4096
	ds_read_b128 v[224:227], v214 offset:5120
	ds_read_b128 v[228:231], v214 offset:6144
	ds_read_b128 v[232:235], v214 offset:7168
	global_load_lds_dwordx4 v178, s[18:19]
	s_add_i32 m0, s28, 0xe000
	s_nop 0
	global_load_lds_dwordx4 v180, s[18:19]
	s_waitcnt vmcnt(8)
	s_waitcnt lgkmcnt(0)
	s_barrier
	s_setprio 1
	s_waitcnt lgkmcnt(0)
	v_mfma_f32_16x16x32_bf16 v[126:129], v[130:133], v[186:189], v[126:129]
	v_mfma_f32_16x16x32_bf16 v[122:125], v[138:141], v[186:189], v[122:125]
	v_mfma_f32_16x16x32_bf16 v[110:113], v[130:133], v[194:197], v[110:113]
	v_mfma_f32_16x16x32_bf16 v[106:109], v[138:141], v[194:197], v[106:109]
	v_mfma_f32_16x16x32_bf16 v[94:97], v[130:133], v[220:223], v[94:97]
	v_mfma_f32_16x16x32_bf16 v[90:93], v[138:141], v[220:223], v[90:93]
	v_mfma_f32_16x16x32_bf16 v[78:81], v[130:133], v[228:231], v[78:81]
	v_mfma_f32_16x16x32_bf16 v[74:77], v[138:141], v[228:231], v[74:77]
	v_mfma_f32_16x16x32_bf16 v[126:129], v[134:137], v[190:193], v[126:129]
	v_mfma_f32_16x16x32_bf16 v[122:125], v[142:145], v[190:193], v[122:125]
	v_mfma_f32_16x16x32_bf16 v[110:113], v[134:137], v[216:219], v[110:113]
	v_mfma_f32_16x16x32_bf16 v[106:109], v[142:145], v[216:219], v[106:109]
	v_mfma_f32_16x16x32_bf16 v[94:97], v[134:137], v[224:227], v[94:97]
	v_mfma_f32_16x16x32_bf16 v[90:93], v[142:145], v[224:227], v[90:93]
	v_mfma_f32_16x16x32_bf16 v[78:81], v[134:137], v[232:235], v[78:81]
	v_mfma_f32_16x16x32_bf16 v[74:77], v[142:145], v[232:235], v[74:77]
	s_setprio 0
	s_setprio 1
	v_mfma_f32_16x16x32_bf16 v[118:121], v[146:149], v[186:189], v[118:121]
	v_mfma_f32_16x16x32_bf16 v[114:117], v[154:157], v[186:189], v[114:117]
	v_mfma_f32_16x16x32_bf16 v[102:105], v[146:149], v[194:197], v[102:105]
	v_mfma_f32_16x16x32_bf16 v[98:101], v[154:157], v[194:197], v[98:101]
	v_mfma_f32_16x16x32_bf16 v[86:89], v[146:149], v[220:223], v[86:89]
	v_mfma_f32_16x16x32_bf16 v[82:85], v[154:157], v[220:223], v[82:85]
	v_mfma_f32_16x16x32_bf16 v[70:73], v[146:149], v[228:231], v[70:73]
	v_mfma_f32_16x16x32_bf16 v[66:69], v[154:157], v[228:231], v[66:69]
	v_mfma_f32_16x16x32_bf16 v[118:121], v[150:153], v[190:193], v[118:121]
	v_mfma_f32_16x16x32_bf16 v[114:117], v[182:185], v[190:193], v[114:117]
	v_mfma_f32_16x16x32_bf16 v[102:105], v[150:153], v[216:219], v[102:105]
	v_mfma_f32_16x16x32_bf16 v[98:101], v[182:185], v[216:219], v[98:101]
	v_mfma_f32_16x16x32_bf16 v[86:89], v[150:153], v[224:227], v[86:89]
	v_mfma_f32_16x16x32_bf16 v[82:85], v[182:185], v[224:227], v[82:85]
	v_mfma_f32_16x16x32_bf16 v[70:73], v[150:153], v[232:235], v[70:73]
	v_mfma_f32_16x16x32_bf16 v[66:69], v[182:185], v[232:235], v[66:69]
	s_setprio 0
	s_barrier
	s_add_i32 s18, s50, s2
	s_mov_b32 m0, s18
	ds_read_b128 v[186:189], v214 offset:16384
	ds_read_b128 v[190:193], v214 offset:17408
	ds_read_b128 v[194:197], v214 offset:18432
	ds_read_b128 v[216:219], v214 offset:19456
	ds_read_b128 v[220:223], v214 offset:20480
	ds_read_b128 v[224:227], v214 offset:21504
	ds_read_b128 v[228:231], v214 offset:22528
	ds_read_b128 v[232:235], v214 offset:23552
	global_load_lds_dwordx4 v0, s[22:23]
	s_add_i32 m0, s18, 0x2000
	s_add_u32 s18, s22, 0xb0000
	s_addc_u32 s19, s23, 0
	s_add_i32 s50, s51, s2
	global_load_lds_dwordx4 v172, s[22:23]
	s_mov_b32 m0, s50
	s_nop 0
	global_load_lds_dwordx4 v0, s[18:19]
	s_add_i32 m0, s50, 0x2000
	s_nop 0
	global_load_lds_dwordx4 v172, s[18:19]
	s_mov_b32 m0, s28
	s_nop 0
	global_load_lds_dwordx4 v176, s[24:25]
	s_mov_b32 m0, s29
	s_nop 0
	global_load_lds_dwordx4 v174, s[24:25]
	s_waitcnt vmcnt(8)
	s_waitcnt lgkmcnt(0)
	s_barrier
	s_setprio 1
	s_waitcnt lgkmcnt(0)
	v_mfma_f32_16x16x32_bf16 v[62:65], v[130:133], v[186:189], v[62:65]
	v_mfma_f32_16x16x32_bf16 v[58:61], v[138:141], v[186:189], v[58:61]
	v_mfma_f32_16x16x32_bf16 v[46:49], v[130:133], v[194:197], v[46:49]
	v_mfma_f32_16x16x32_bf16 v[42:45], v[138:141], v[194:197], v[42:45]
	v_mfma_f32_16x16x32_bf16 v[30:33], v[130:133], v[220:223], v[30:33]
	v_mfma_f32_16x16x32_bf16 v[26:29], v[138:141], v[220:223], v[26:29]
	v_mfma_f32_16x16x32_bf16 v[14:17], v[130:133], v[228:231], v[14:17]
	v_mfma_f32_16x16x32_bf16 v[10:13], v[138:141], v[228:231], v[10:13]
	v_mfma_f32_16x16x32_bf16 v[62:65], v[134:137], v[190:193], v[62:65]
	v_mfma_f32_16x16x32_bf16 v[58:61], v[142:145], v[190:193], v[58:61]
	v_mfma_f32_16x16x32_bf16 v[46:49], v[134:137], v[216:219], v[46:49]
	v_mfma_f32_16x16x32_bf16 v[42:45], v[142:145], v[216:219], v[42:45]
	v_mfma_f32_16x16x32_bf16 v[30:33], v[134:137], v[224:227], v[30:33]
	v_mfma_f32_16x16x32_bf16 v[26:29], v[142:145], v[224:227], v[26:29]
	v_mfma_f32_16x16x32_bf16 v[14:17], v[134:137], v[232:235], v[14:17]
	v_mfma_f32_16x16x32_bf16 v[10:13], v[142:145], v[232:235], v[10:13]
	s_setprio 0
	s_setprio 1
	v_mfma_f32_16x16x32_bf16 v[54:57], v[146:149], v[186:189], v[54:57]
	v_mfma_f32_16x16x32_bf16 v[50:53], v[154:157], v[186:189], v[50:53]
	v_mfma_f32_16x16x32_bf16 v[38:41], v[146:149], v[194:197], v[38:41]
	v_mfma_f32_16x16x32_bf16 v[34:37], v[154:157], v[194:197], v[34:37]
	v_mfma_f32_16x16x32_bf16 v[22:25], v[146:149], v[220:223], v[22:25]
	v_mfma_f32_16x16x32_bf16 v[18:21], v[154:157], v[220:223], v[18:21]
	v_mfma_f32_16x16x32_bf16 v[6:9], v[146:149], v[228:231], v[6:9]
	v_mfma_f32_16x16x32_bf16 v[2:5], v[154:157], v[228:231], v[2:5]
	v_mfma_f32_16x16x32_bf16 v[54:57], v[150:153], v[190:193], v[54:57]
	v_mfma_f32_16x16x32_bf16 v[50:53], v[182:185], v[190:193], v[50:53]
	v_mfma_f32_16x16x32_bf16 v[38:41], v[150:153], v[216:219], v[38:41]
	v_mfma_f32_16x16x32_bf16 v[34:37], v[182:185], v[216:219], v[34:37]
	v_mfma_f32_16x16x32_bf16 v[22:25], v[150:153], v[224:227], v[22:25]
	v_mfma_f32_16x16x32_bf16 v[18:21], v[182:185], v[224:227], v[18:21]
	v_mfma_f32_16x16x32_bf16 v[6:9], v[150:153], v[232:235], v[6:9]
	v_mfma_f32_16x16x32_bf16 v[2:5], v[182:185], v[232:235], v[2:5]
	s_setprio 0
	s_barrier
; #define PG8_STAGE(bufoff, gbase, voff) do { _Pragma("unroll") for (int _i = 0; _i < 2; ++_i) \
;         __builtin_amdgcn_global_load_lds((const unsigned*)((const char*)(gbase) + (voff)[_i]), (PG8_LAS unsigned*)(lds + (bufoff) + ldsw + _i * 8192), 16, 0, 0); } while (0)
; #define PG8_LDA(dst, b, h) do { _Pragma("unroll") for (int m = 0; m < 4; ++m) _Pragma("unroll") for (int k = 0; k < 2; ++k) dst[m][k] = *(const PG8_LAS bf16x8*)(lds + PG8_SA(b, h) + aoff + m * 2048 + k * 1024); } while (0)
; #define PG8_LDB(dst, b, h) do { _Pragma("unroll") for (int n = 0; n < 2; ++n) _Pragma("unroll") for (int k = 0; k < 2; ++k) dst[n][k] = *(const PG8_LAS bf16x8*)(lds + PG8_SB(b, h) + boff + n * 2048 + k * 1024); } while (0)
; #define PG8_MMA(ai, bj, At, Bt) do { __builtin_amdgcn_s_setprio(1); _Pragma("unroll") for (int m = 0; m < 4; ++m) _Pragma("unroll") for (int n = 0; n < 2; ++n) _Pragma("unroll") for (int k = 0; k < 2; ++k) \
;         acc[ai][bj][m][n] = __builtin_amdgcn_mfma_f32_16x16x32_bf16(Bt[n][k], At[m][k], acc[ai][bj][m][n], 0, 0, 0); __builtin_amdgcn_s_setprio(0); } while (0)
; #define PG8_WAIT_V(n) asm volatile("s_waitcnt vmcnt(" #n ")" ::: "memory")
; #define PG8_WAIT_L(n) asm volatile("s_waitcnt lgkmcnt(" #n ")" ::: "memory")
; #define PG8_BAR __builtin_amdgcn_s_barrier()
; #define PG8_SCHED __builtin_amdgcn_sched_barrier(0)
; template <class Epi, class Sched, bool ALIGN_EPI = false, bool SP2 = false>
; __device__ __forceinline__ void gemm_phase(PG8_LAS unsigned char* lds, const Gemm g, const Sched& S, const Epi& E) {
;     ...
;             PG8_LDB(B0, 1, 0); PG8_LDB(B1, 1, 1); PG8_SCHED; PG8_LDA(At, 1, 0); PG8_STAGE(PG8_SA(0, 1), a2 + hstep, voffA);
;             PG8_WAIT_V(8); PG8_WAIT_L(0); PG8_BAR; PG8_MMA(0, 0, At, B0); PG8_MMA(0, 1, At, B1); PG8_BAR; PG8_SCHED;
;             PG8_LDA(At, 1, 1); PG8_STAGE(PG8_SB(1, 0), b3, voffB); PG8_STAGE(PG8_SB(1, 1), b3 + hstep, voffB); PG8_STAGE(PG8_SA(1, 0), a3, voffA);
;             PG8_WAIT_V(8); PG8_WAIT_L(0); PG8_BAR; PG8_MMA(1, 0, At, B0); PG8_MMA(1, 1, At, B1); PG8_BAR; PG8_SCHED;
	s_add_i32 s50, 0, 0x18000
	s_add_i32 s51, 0, 0x1c000
	v_add_u32_e32 v142, s50, v165
	v_add_u32_e32 v182, s51, v165
	ds_read_b128 v[130:133], v142
	ds_read_b128 v[134:137], v142 offset:1024
	ds_read_b128 v[138:141], v142 offset:2048
	ds_read_b128 v[142:145], v142 offset:3072
	ds_read_b128 v[146:149], v182
	ds_read_b128 v[150:153], v182 offset:1024
	ds_read_b128 v[154:157], v182 offset:2048
	ds_read_b128 v[182:185], v182 offset:3072
	s_add_u32 s18, s24, 0xb0000
	s_addc_u32 s19, s25, 0
	s_mov_b32 m0, s30
	ds_read_b128 v[186:189], v214 offset:32768
	ds_read_b128 v[190:193], v214 offset:33792
	ds_read_b128 v[194:197], v214 offset:34816
	ds_read_b128 v[216:219], v214 offset:35840
	ds_read_b128 v[220:223], v214 offset:36864
	ds_read_b128 v[224:227], v214 offset:37888
	ds_read_b128 v[228:231], v214 offset:38912
	ds_read_b128 v[232:235], v214 offset:39936
	global_load_lds_dwordx4 v176, s[18:19]
	s_mov_b32 m0, s31
	s_nop 0
	global_load_lds_dwordx4 v174, s[18:19]
	s_waitcnt vmcnt(8)
	s_waitcnt lgkmcnt(0)
	s_barrier
	s_setprio 1
	s_waitcnt lgkmcnt(0)
	v_mfma_f32_16x16x32_bf16 v[126:129], v[130:133], v[186:189], v[126:129]
	v_mfma_f32_16x16x32_bf16 v[122:125], v[138:141], v[186:189], v[122:125]
	v_mfma_f32_16x16x32_bf16 v[110:113], v[130:133], v[194:197], v[110:113]
	v_mfma_f32_16x16x32_bf16 v[106:109], v[138:141], v[194:197], v[106:109]
	v_mfma_f32_16x16x32_bf16 v[94:97], v[130:133], v[220:223], v[94:97]
	v_mfma_f32_16x16x32_bf16 v[90:93], v[138:141], v[220:223], v[90:93]
	v_mfma_f32_16x16x32_bf16 v[78:81], v[130:133], v[228:231], v[78:81]
	v_mfma_f32_16x16x32_bf16 v[74:77], v[138:141], v[228:231], v[74:77]
	v_mfma_f32_16x16x32_bf16 v[126:129], v[134:137], v[190:193], v[126:129]
	v_mfma_f32_16x16x32_bf16 v[122:125], v[142:145], v[190:193], v[122:125]
	v_mfma_f32_16x16x32_bf16 v[110:113], v[134:137], v[216:219], v[110:113]
	v_mfma_f32_16x16x32_bf16 v[106:109], v[142:145], v[216:219], v[106:109]
	v_mfma_f32_16x16x32_bf16 v[94:97], v[134:137], v[224:227], v[94:97]
	v_mfma_f32_16x16x32_bf16 v[90:93], v[142:145], v[224:227], v[90:93]
	v_mfma_f32_16x16x32_bf16 v[78:81], v[134:137], v[232:235], v[78:81]
	v_mfma_f32_16x16x32_bf16 v[74:77], v[142:145], v[232:235], v[74:77]
	s_setprio 0
	s_setprio 1
	v_mfma_f32_16x16x32_bf16 v[118:121], v[146:149], v[186:189], v[118:121]
	v_mfma_f32_16x16x32_bf16 v[114:117], v[154:157], v[186:189], v[114:117]
	v_mfma_f32_16x16x32_bf16 v[102:105], v[146:149], v[194:197], v[102:105]
	v_mfma_f32_16x16x32_bf16 v[98:101], v[154:157], v[194:197], v[98:101]
	v_mfma_f32_16x16x32_bf16 v[86:89], v[146:149], v[220:223], v[86:89]
	v_mfma_f32_16x16x32_bf16 v[82:85], v[154:157], v[220:223], v[82:85]
	v_mfma_f32_16x16x32_bf16 v[70:73], v[146:149], v[228:231], v[70:73]
	v_mfma_f32_16x16x32_bf16 v[66:69], v[154:157], v[228:231], v[66:69]
	v_mfma_f32_16x16x32_bf16 v[118:121], v[150:153], v[190:193], v[118:121]
	v_mfma_f32_16x16x32_bf16 v[114:117], v[182:185], v[190:193], v[114:117]
	v_mfma_f32_16x16x32_bf16 v[102:105], v[150:153], v[216:219], v[102:105]
	v_mfma_f32_16x16x32_bf16 v[98:101], v[182:185], v[216:219], v[98:101]
	v_mfma_f32_16x16x32_bf16 v[86:89], v[150:153], v[224:227], v[86:89]
	v_mfma_f32_16x16x32_bf16 v[82:85], v[182:185], v[224:227], v[82:85]
	v_mfma_f32_16x16x32_bf16 v[70:73], v[150:153], v[232:235], v[70:73]
	v_mfma_f32_16x16x32_bf16 v[66:69], v[182:185], v[232:235], v[66:69]
	s_setprio 0
	s_barrier
	s_add_i32 s18, s50, s2
	s_add_u32 s98, s22, 0x80
	s_addc_u32 s99, s23, 0
	s_add_u32 s100, s24, 0x80
	s_addc_u32 s101, s25, 0
	s_mov_b32 m0, s18
	ds_read_b128 v[186:189], v214 offset:49152
	ds_read_b128 v[190:193], v214 offset:50176
	ds_read_b128 v[194:197], v214 offset:51200
	ds_read_b128 v[216:219], v214 offset:52224
	ds_read_b128 v[220:223], v214 offset:53248
	ds_read_b128 v[224:227], v214 offset:54272
	ds_read_b128 v[228:231], v214 offset:55296
	ds_read_b128 v[232:235], v214 offset:56320
	global_load_lds_dwordx4 v0, s[98:99]
	s_add_i32 m0, s18, 0x2000
	s_add_u32 s18, s22, 0xb0080
	s_addc_u32 s19, s23, 0
	s_add_i32 s22, s51, s2
	global_load_lds_dwordx4 v172, s[98:99]
	s_mov_b32 m0, s22
	s_nop 0
	global_load_lds_dwordx4 v0, s[18:19]
	s_add_i32 m0, s22, 0x2000
	s_nop 0
	global_load_lds_dwordx4 v172, s[18:19]
	s_mov_b32 m0, s35
	s_nop 0
	global_load_lds_dwordx4 v176, s[100:101]
	s_mov_b32 m0, s37
	s_nop 0
	global_load_lds_dwordx4 v174, s[100:101]
	s_waitcnt vmcnt(8)
	s_waitcnt lgkmcnt(0)
	s_barrier
	s_setprio 1
	s_waitcnt lgkmcnt(0)
	v_mfma_f32_16x16x32_bf16 v[62:65], v[130:133], v[186:189], v[62:65]
	v_mfma_f32_16x16x32_bf16 v[58:61], v[138:141], v[186:189], v[58:61]
	v_mfma_f32_16x16x32_bf16 v[46:49], v[130:133], v[194:197], v[46:49]
	v_mfma_f32_16x16x32_bf16 v[42:45], v[138:141], v[194:197], v[42:45]
	v_mfma_f32_16x16x32_bf16 v[30:33], v[130:133], v[220:223], v[30:33]
	v_mfma_f32_16x16x32_bf16 v[26:29], v[138:141], v[220:223], v[26:29]
	v_mfma_f32_16x16x32_bf16 v[14:17], v[130:133], v[228:231], v[14:17]
	v_mfma_f32_16x16x32_bf16 v[10:13], v[138:141], v[228:231], v[10:13]
	v_mfma_f32_16x16x32_bf16 v[62:65], v[134:137], v[190:193], v[62:65]
	v_mfma_f32_16x16x32_bf16 v[58:61], v[142:145], v[190:193], v[58:61]
	v_mfma_f32_16x16x32_bf16 v[46:49], v[134:137], v[216:219], v[46:49]
	v_mfma_f32_16x16x32_bf16 v[42:45], v[142:145], v[216:219], v[42:45]
	v_mfma_f32_16x16x32_bf16 v[30:33], v[134:137], v[224:227], v[30:33]
	v_mfma_f32_16x16x32_bf16 v[26:29], v[142:145], v[224:227], v[26:29]
	v_mfma_f32_16x16x32_bf16 v[14:17], v[134:137], v[232:235], v[14:17]
	v_mfma_f32_16x16x32_bf16 v[10:13], v[142:145], v[232:235], v[10:13]
	s_setprio 0
	s_setprio 1
	v_mfma_f32_16x16x32_bf16 v[54:57], v[146:149], v[186:189], v[54:57]
	v_mfma_f32_16x16x32_bf16 v[50:53], v[154:157], v[186:189], v[50:53]
	v_mfma_f32_16x16x32_bf16 v[38:41], v[146:149], v[194:197], v[38:41]
	v_mfma_f32_16x16x32_bf16 v[34:37], v[154:157], v[194:197], v[34:37]
	v_mfma_f32_16x16x32_bf16 v[22:25], v[146:149], v[220:223], v[22:25]
	v_mfma_f32_16x16x32_bf16 v[18:21], v[154:157], v[220:223], v[18:21]
	v_mfma_f32_16x16x32_bf16 v[6:9], v[146:149], v[228:231], v[6:9]
	v_mfma_f32_16x16x32_bf16 v[2:5], v[154:157], v[228:231], v[2:5]
	v_mfma_f32_16x16x32_bf16 v[54:57], v[150:153], v[190:193], v[54:57]
	v_mfma_f32_16x16x32_bf16 v[50:53], v[182:185], v[190:193], v[50:53]
	v_mfma_f32_16x16x32_bf16 v[38:41], v[150:153], v[216:219], v[38:41]
	v_mfma_f32_16x16x32_bf16 v[34:37], v[182:185], v[216:219], v[34:37]
	v_mfma_f32_16x16x32_bf16 v[22:25], v[150:153], v[224:227], v[22:25]
	v_mfma_f32_16x16x32_bf16 v[18:21], v[182:185], v[224:227], v[18:21]
	v_mfma_f32_16x16x32_bf16 v[6:9], v[150:153], v[232:235], v[6:9]
	v_mfma_f32_16x16x32_bf16 v[2:5], v[182:185], v[232:235], v[2:5]
	s_setprio 0
	s_barrier
; __device__ __forceinline__ unsigned cvt_pk_bf16(float lo, float hi) { f32x2_cv v = {lo, hi}; bf16x2_cv b = __builtin_convertvector(v, bf16x2_cv); return __builtin_bit_cast(unsigned, b); }
;     __device__ __forceinline__ void operator()(const f32x4 (&acc)[2][2][4][2], const Unit& u, int wr, int wc, int fr, int fq) const {
;         const int row0 = u.pm * BM + wr * 64 + fr, col0 = u.pn * BM + wc * 32 + 8 * fq;
; #pragma unroll
;         for (int ai = 0; ai < 2; ++ai) {
;             u32x4 xv[4][2];
; #pragma unroll
;             for (int m = 0; m < 4; ++m)
; #pragma unroll
;                 for (int bj = 0; bj < 2; ++bj) xv[m][bj] = *(const u32x4*)(XB + (size_t)(row0 + ai * HALF + m * 16) * 1024 + col0 + bj * HALF);
;             asm volatile("" ::: "memory");
; #pragma unroll
;             for (int m = 0; m < 4; ++m) {
;                 const int row = row0 + ai * HALF + m * 16; float ss = 0.f;
; #pragma unroll
;                 for (int bj = 0; bj < 2; ++bj) {
;                     const size_t off = (size_t)row * 1024 + col0 + bj * HALF;
;                     const u32x4 v = xv[m][bj];
;                     f32x4 x0 = {__uint_as_float(v.x << 16), __uint_as_float(v.x & 0xffff0000u), __uint_as_float(v.y << 16), __uint_as_float(v.y & 0xffff0000u)};
;                     f32x4 x1 = {__uint_as_float(v.z << 16), __uint_as_float(v.z & 0xffff0000u), __uint_as_float(v.w << 16), __uint_as_float(v.w & 0xffff0000u)};
;                     x0 = x0 + acc[ai][bj][m][0] * alpha; x1 = x1 + acc[ai][bj][m][1] * alpha;
;                     u32x4 w; w.x = cvt_pk_bf16(x0[0], x0[1]); w.y = cvt_pk_bf16(x0[2], x0[3]); w.z = cvt_pk_bf16(x1[0], x1[1]); w.w = cvt_pk_bf16(x1[2], x1[3]);
;                     *(u32x4*)(XB + off) = w;
;                     const f32x4 sq = x0 * x0 + x1 * x1;
;                     ss += (sq[0] + sq[1]) + (sq[2] + sq[3]);
;                 }
	s_add_i32 s49, s49, 2
	s_add_u32 s47, s47, 0x100
	s_addc_u32 s48, s48, 0
	s_cmp_gt_u32 s49, 41
	s_mov_b64 s[18:19], s[20:21]
	s_cbranch_scc0 .LBB0_459
	v_lshl_or_b32 v198, s45, 8, v213
	v_lshl_add_u32 v217, s46, 8, v158
	v_lshlrev_b32_e32 v246, 1, v198
	v_lshl_add_u32 v246, v217, 11, v246
	v_mov_b32_e32 v247, 0
	s_mov_b32 s18, 0x8000
	s_mov_b32 s19, 0
	s_mov_b32 s88, 0x28000
	v_lshl_add_u64 v[246:247], s[94:95], 0, v[246:247]
	v_xor_b32_e32 v215, 16, v201
	v_xor_b32_e32 v216, 32, v201
	v_mov_b32_e32 v198, v246
	v_mov_b32_e32 v199, v247
	global_load_dwordx4 v[130:133], v[246:247], off
	global_load_dwordx4 v[134:137], v[246:247], off offset:256
	v_lshl_add_u64 v[246:247], v[246:247], 0, s[18:19]
	global_load_dwordx4 v[138:141], v[246:247], off
	global_load_dwordx4 v[142:145], v[246:247], off offset:256
	v_lshl_add_u64 v[246:247], v[246:247], 0, s[18:19]
	global_load_dwordx4 v[146:149], v[246:247], off
	global_load_dwordx4 v[150:153], v[246:247], off offset:256
	v_lshl_add_u64 v[246:247], v[246:247], 0, s[18:19]
	global_load_dwordx4 v[154:157], v[246:247], off
	global_load_dwordx4 v[218:221], v[246:247], off offset:256
	v_lshl_add_u64 v[246:247], v[246:247], 0, s[88:89]
	global_load_dwordx4 v[182:185], v[246:247], off
	global_load_dwordx4 v[186:189], v[246:247], off offset:256
	v_lshl_add_u64 v[246:247], v[246:247], 0, s[18:19]
	global_load_dwordx4 v[190:193], v[246:247], off
	global_load_dwordx4 v[194:197], v[246:247], off offset:256
	v_lshl_add_u64 v[246:247], v[246:247], 0, s[18:19]
	global_load_dwordx4 v[222:225], v[246:247], off
	global_load_dwordx4 v[226:229], v[246:247], off offset:256
	v_lshl_add_u64 v[246:247], v[246:247], 0, s[18:19]
	global_load_dwordx4 v[230:233], v[246:247], off
	global_load_dwordx4 v[234:237], v[246:247], off offset:256
	v_lshlrev_b32_e32 v215, 2, v215
	v_lshlrev_b32_e32 v216, 2, v216
	s_waitcnt vmcnt(15)
	v_lshlrev_b32_e32 v238, 16, v130
	v_and_b32_e32 v239, 0xffff0000, v130
	v_lshlrev_b32_e32 v240, 16, v131
	v_and_b32_e32 v241, 0xffff0000, v131
	v_lshlrev_b32_e32 v242, 16, v132
	v_and_b32_e32 v243, 0xffff0000, v132
	v_lshlrev_b32_e32 v244, 16, v133
	v_and_b32_e32 v245, 0xffff0000, v133
	v_pk_fma_f32 v[126:127], v[126:127], 0.5, v[238:239] op_sel_hi:[1,0,1]
	v_pk_fma_f32 v[128:129], v[128:129], 0.5, v[240:241] op_sel_hi:[1,0,1]
	v_pk_fma_f32 v[122:123], v[122:123], 0.5, v[242:243] op_sel_hi:[1,0,1]
	v_pk_fma_f32 v[124:125], v[124:125], 0.5, v[244:245] op_sel_hi:[1,0,1]
	v_cvt_pk_bf16_f32 v130, v126, v127
	v_cvt_pk_bf16_f32 v131, v128, v129
	v_cvt_pk_bf16_f32 v132, v122, v123
	v_cvt_pk_bf16_f32 v133, v124, v125
	global_store_dwordx4 v[198:199], v[130:133], off
	v_pk_mul_f32 v[238:239], v[122:123], v[122:123]
	v_pk_mul_f32 v[240:241], v[124:125], v[124:125]
	v_pk_fma_f32 v[238:239], v[126:127], v[126:127], v[238:239]
	v_pk_fma_f32 v[240:241], v[128:129], v[128:129], v[240:241]
	s_nop 0
	v_add_f32_e32 v238, v238, v239
	v_add_f32_e32 v239, v240, v241
	v_add_f32_e32 v126, v238, v239
	s_waitcnt vmcnt(15)
	v_lshlrev_b32_e32 v238, 16, v134
	v_and_b32_e32 v239, 0xffff0000, v134
	v_lshlrev_b32_e32 v240, 16, v135
	v_and_b32_e32 v241, 0xffff0000, v135
	v_lshlrev_b32_e32 v242, 16, v136
	v_and_b32_e32 v243, 0xffff0000, v136
	v_lshlrev_b32_e32 v244, 16, v137
	v_and_b32_e32 v245, 0xffff0000, v137
	v_pk_fma_f32 v[118:119], v[118:119], 0.5, v[238:239] op_sel_hi:[1,0,1]
	v_pk_fma_f32 v[120:121], v[120:121], 0.5, v[240:241] op_sel_hi:[1,0,1]
	v_pk_fma_f32 v[114:115], v[114:115], 0.5, v[242:243] op_sel_hi:[1,0,1]
	v_pk_fma_f32 v[116:117], v[116:117], 0.5, v[244:245] op_sel_hi:[1,0,1]
	v_cvt_pk_bf16_f32 v134, v118, v119
	v_cvt_pk_bf16_f32 v135, v120, v121
	v_cvt_pk_bf16_f32 v136, v114, v115
	v_cvt_pk_bf16_f32 v137, v116, v117
	global_store_dwordx4 v[198:199], v[134:137], off offset:256
	v_pk_mul_f32 v[238:239], v[114:115], v[114:115]
	v_pk_mul_f32 v[240:241], v[116:117], v[116:117]
	v_pk_fma_f32 v[238:239], v[118:119], v[118:119], v[238:239]
	v_pk_fma_f32 v[240:241], v[120:121], v[120:121], v[240:241]
	s_nop 0
	v_add_f32_e32 v238, v238, v239
	v_add_f32_e32 v239, v240, v241
	v_add_f32_e32 v238, v238, v239
	v_add_f32_e32 v126, v126, v238
	s_and_b64 vcc, exec, s[14:15]
	s_cbranch_vccz .LBB0_462
	s_barrier
.LBB0_462:
	v_lshl_add_u64 v[198:199], v[198:199], 0, s[18:19]
	s_waitcnt vmcnt(15)
	v_lshlrev_b32_e32 v238, 16, v138
	v_and_b32_e32 v239, 0xffff0000, v138
	v_lshlrev_b32_e32 v240, 16, v139
	v_and_b32_e32 v241, 0xffff0000, v139
	v_lshlrev_b32_e32 v242, 16, v140
	v_and_b32_e32 v243, 0xffff0000, v140
	v_lshlrev_b32_e32 v244, 16, v141
	v_and_b32_e32 v245, 0xffff0000, v141
	v_pk_fma_f32 v[110:111], v[110:111], 0.5, v[238:239] op_sel_hi:[1,0,1]
	v_pk_fma_f32 v[112:113], v[112:113], 0.5, v[240:241] op_sel_hi:[1,0,1]
	v_pk_fma_f32 v[106:107], v[106:107], 0.5, v[242:243] op_sel_hi:[1,0,1]
	v_pk_fma_f32 v[108:109], v[108:109], 0.5, v[244:245] op_sel_hi:[1,0,1]
	v_cvt_pk_bf16_f32 v138, v110, v111
	v_cvt_pk_bf16_f32 v139, v112, v113
	v_cvt_pk_bf16_f32 v140, v106, v107
	v_cvt_pk_bf16_f32 v141, v108, v109
	global_store_dwordx4 v[198:199], v[138:141], off
	v_pk_mul_f32 v[238:239], v[106:107], v[106:107]
	v_pk_mul_f32 v[240:241], v[108:109], v[108:109]
	v_pk_fma_f32 v[238:239], v[110:111], v[110:111], v[238:239]
	v_pk_fma_f32 v[240:241], v[112:113], v[112:113], v[240:241]
	s_nop 0
	v_add_f32_e32 v238, v238, v239
	v_add_f32_e32 v239, v240, v241
	v_add_f32_e32 v110, v238, v239
	s_waitcnt vmcnt(15)
; __device__ __forceinline__ unsigned cvt_pk_bf16(float lo, float hi) { f32x2_cv v = {lo, hi}; bf16x2_cv b = __builtin_convertvector(v, bf16x2_cv); return __builtin_bit_cast(unsigned, b); }
;     __device__ __forceinline__ void operator()(const f32x4 (&acc)[2][2][4][2], const Unit& u, int wr, int wc, int fr, int fq) const {
;     ...
;             for (int m = 0; m < 4; ++m) {
;                 const int row = row0 + ai * HALF + m * 16; float ss = 0.f;
; #pragma unroll
;                 for (int bj = 0; bj < 2; ++bj) {
;                     const size_t off = (size_t)row * 1024 + col0 + bj * HALF;
;                     const u32x4 v = xv[m][bj];
;                     f32x4 x0 = {__uint_as_float(v.x << 16), __uint_as_float(v.x & 0xffff0000u), __uint_as_float(v.y << 16), __uint_as_float(v.y & 0xffff0000u)};
;                     f32x4 x1 = {__uint_as_float(v.z << 16), __uint_as_float(v.z & 0xffff0000u), __uint_as_float(v.w << 16), __uint_as_float(v.w & 0xffff0000u)};
;                     x0 = x0 + acc[ai][bj][m][0] * alpha; x1 = x1 + acc[ai][bj][m][1] * alpha;
;                     u32x4 w; w.x = cvt_pk_bf16(x0[0], x0[1]); w.y = cvt_pk_bf16(x0[2], x0[3]); w.z = cvt_pk_bf16(x1[0], x1[1]); w.w = cvt_pk_bf16(x1[2], x1[3]);
;                     *(u32x4*)(XB + off) = w;
;                     const f32x4 sq = x0 * x0 + x1 * x1;
;                     ss += (sq[0] + sq[1]) + (sq[2] + sq[3]);
;                 }
	v_lshlrev_b32_e32 v238, 16, v142
	v_and_b32_e32 v239, 0xffff0000, v142
	v_lshlrev_b32_e32 v240, 16, v143
	v_and_b32_e32 v241, 0xffff0000, v143
	v_lshlrev_b32_e32 v242, 16, v144
	v_and_b32_e32 v243, 0xffff0000, v144
	v_lshlrev_b32_e32 v244, 16, v145
	v_and_b32_e32 v245, 0xffff0000, v145
	v_pk_fma_f32 v[102:103], v[102:103], 0.5, v[238:239] op_sel_hi:[1,0,1]
	v_pk_fma_f32 v[104:105], v[104:105], 0.5, v[240:241] op_sel_hi:[1,0,1]
	v_pk_fma_f32 v[98:99], v[98:99], 0.5, v[242:243] op_sel_hi:[1,0,1]
	v_pk_fma_f32 v[100:101], v[100:101], 0.5, v[244:245] op_sel_hi:[1,0,1]
	v_cvt_pk_bf16_f32 v142, v102, v103
	v_cvt_pk_bf16_f32 v143, v104, v105
	v_cvt_pk_bf16_f32 v144, v98, v99
	v_cvt_pk_bf16_f32 v145, v100, v101
	global_store_dwordx4 v[198:199], v[142:145], off offset:256
	v_pk_mul_f32 v[238:239], v[98:99], v[98:99]
	v_pk_mul_f32 v[240:241], v[100:101], v[100:101]
	v_pk_fma_f32 v[238:239], v[102:103], v[102:103], v[238:239]
	v_pk_fma_f32 v[240:241], v[104:105], v[104:105], v[240:241]
	s_nop 0
	v_add_f32_e32 v238, v238, v239
	v_add_f32_e32 v239, v240, v241
	v_add_f32_e32 v238, v238, v239
	v_add_f32_e32 v110, v110, v238
	v_lshl_add_u64 v[198:199], v[198:199], 0, s[18:19]
	s_waitcnt vmcnt(15)
	v_lshlrev_b32_e32 v238, 16, v146
	v_and_b32_e32 v239, 0xffff0000, v146
	v_lshlrev_b32_e32 v240, 16, v147
	v_and_b32_e32 v241, 0xffff0000, v147
	v_lshlrev_b32_e32 v242, 16, v148
	v_and_b32_e32 v243, 0xffff0000, v148
	v_lshlrev_b32_e32 v244, 16, v149
	v_and_b32_e32 v245, 0xffff0000, v149
	v_pk_fma_f32 v[94:95], v[94:95], 0.5, v[238:239] op_sel_hi:[1,0,1]
	v_pk_fma_f32 v[96:97], v[96:97], 0.5, v[240:241] op_sel_hi:[1,0,1]
	v_pk_fma_f32 v[90:91], v[90:91], 0.5, v[242:243] op_sel_hi:[1,0,1]
	v_pk_fma_f32 v[92:93], v[92:93], 0.5, v[244:245] op_sel_hi:[1,0,1]
	v_cvt_pk_bf16_f32 v146, v94, v95
	v_cvt_pk_bf16_f32 v147, v96, v97
	v_cvt_pk_bf16_f32 v148, v90, v91
	v_cvt_pk_bf16_f32 v149, v92, v93
	global_store_dwordx4 v[198:199], v[146:149], off
	v_pk_mul_f32 v[238:239], v[90:91], v[90:91]
	v_pk_mul_f32 v[240:241], v[92:93], v[92:93]
	v_pk_fma_f32 v[238:239], v[94:95], v[94:95], v[238:239]
	v_pk_fma_f32 v[240:241], v[96:97], v[96:97], v[240:241]
	s_nop 0
	v_add_f32_e32 v238, v238, v239
	v_add_f32_e32 v239, v240, v241
	v_add_f32_e32 v94, v238, v239
	s_waitcnt vmcnt(15)
	v_lshlrev_b32_e32 v238, 16, v150
	v_and_b32_e32 v239, 0xffff0000, v150
	v_lshlrev_b32_e32 v240, 16, v151
	v_and_b32_e32 v241, 0xffff0000, v151
	v_lshlrev_b32_e32 v242, 16, v152
	v_and_b32_e32 v243, 0xffff0000, v152
	v_lshlrev_b32_e32 v244, 16, v153
	v_and_b32_e32 v245, 0xffff0000, v153
	v_pk_fma_f32 v[86:87], v[86:87], 0.5, v[238:239] op_sel_hi:[1,0,1]
	v_pk_fma_f32 v[88:89], v[88:89], 0.5, v[240:241] op_sel_hi:[1,0,1]
	v_pk_fma_f32 v[82:83], v[82:83], 0.5, v[242:243] op_sel_hi:[1,0,1]
	v_pk_fma_f32 v[84:85], v[84:85], 0.5, v[244:245] op_sel_hi:[1,0,1]
	v_cvt_pk_bf16_f32 v150, v86, v87
	v_cvt_pk_bf16_f32 v151, v88, v89
	v_cvt_pk_bf16_f32 v152, v82, v83
	v_cvt_pk_bf16_f32 v153, v84, v85
	global_store_dwordx4 v[198:199], v[150:153], off offset:256
	v_pk_mul_f32 v[238:239], v[82:83], v[82:83]
	v_pk_mul_f32 v[240:241], v[84:85], v[84:85]
	v_pk_fma_f32 v[238:239], v[86:87], v[86:87], v[238:239]
	v_pk_fma_f32 v[240:241], v[88:89], v[88:89], v[240:241]
	s_nop 0
	v_add_f32_e32 v238, v238, v239
	v_add_f32_e32 v239, v240, v241
	v_add_f32_e32 v238, v238, v239
	v_add_f32_e32 v94, v94, v238
	v_lshl_add_u64 v[198:199], v[198:199], 0, s[18:19]
	s_waitcnt vmcnt(15)
	v_lshlrev_b32_e32 v238, 16, v154
	v_and_b32_e32 v239, 0xffff0000, v154
	v_lshlrev_b32_e32 v240, 16, v155
	v_and_b32_e32 v241, 0xffff0000, v155
	v_lshlrev_b32_e32 v242, 16, v156
	v_and_b32_e32 v243, 0xffff0000, v156
	v_lshlrev_b32_e32 v244, 16, v157
	v_and_b32_e32 v245, 0xffff0000, v157
	v_pk_fma_f32 v[78:79], v[78:79], 0.5, v[238:239] op_sel_hi:[1,0,1]
	v_pk_fma_f32 v[80:81], v[80:81], 0.5, v[240:241] op_sel_hi:[1,0,1]
	v_pk_fma_f32 v[74:75], v[74:75], 0.5, v[242:243] op_sel_hi:[1,0,1]
	v_pk_fma_f32 v[76:77], v[76:77], 0.5, v[244:245] op_sel_hi:[1,0,1]
	v_cvt_pk_bf16_f32 v154, v78, v79
	v_cvt_pk_bf16_f32 v155, v80, v81
	v_cvt_pk_bf16_f32 v156, v74, v75
	v_cvt_pk_bf16_f32 v157, v76, v77
	global_store_dwordx4 v[198:199], v[154:157], off
	v_pk_mul_f32 v[238:239], v[74:75], v[74:75]
	v_pk_mul_f32 v[240:241], v[76:77], v[76:77]
	v_pk_fma_f32 v[238:239], v[78:79], v[78:79], v[238:239]
	v_pk_fma_f32 v[240:241], v[80:81], v[80:81], v[240:241]
	s_nop 0
	v_add_f32_e32 v238, v238, v239
	v_add_f32_e32 v239, v240, v241
	v_add_f32_e32 v78, v238, v239
	s_waitcnt vmcnt(15)
	v_lshlrev_b32_e32 v238, 16, v218
	v_and_b32_e32 v239, 0xffff0000, v218
	v_lshlrev_b32_e32 v240, 16, v219
	v_and_b32_e32 v241, 0xffff0000, v219
	v_lshlrev_b32_e32 v242, 16, v220
	v_and_b32_e32 v243, 0xffff0000, v220
	v_lshlrev_b32_e32 v244, 16, v221
	v_and_b32_e32 v245, 0xffff0000, v221
	v_pk_fma_f32 v[70:71], v[70:71], 0.5, v[238:239] op_sel_hi:[1,0,1]
	v_pk_fma_f32 v[72:73], v[72:73], 0.5, v[240:241] op_sel_hi:[1,0,1]
	v_pk_fma_f32 v[66:67], v[66:67], 0.5, v[242:243] op_sel_hi:[1,0,1]
	v_pk_fma_f32 v[68:69], v[68:69], 0.5, v[244:245] op_sel_hi:[1,0,1]
	v_cvt_pk_bf16_f32 v218, v70, v71
	v_cvt_pk_bf16_f32 v219, v72, v73
	v_cvt_pk_bf16_f32 v220, v66, v67
	v_cvt_pk_bf16_f32 v221, v68, v69
	global_store_dwordx4 v[198:199], v[218:221], off offset:256
	v_pk_mul_f32 v[238:239], v[66:67], v[66:67]
	v_pk_mul_f32 v[240:241], v[68:69], v[68:69]
	v_pk_fma_f32 v[238:239], v[70:71], v[70:71], v[238:239]
	v_pk_fma_f32 v[240:241], v[72:73], v[72:73], v[240:241]
	s_nop 0
	v_add_f32_e32 v238, v238, v239
	v_add_f32_e32 v239, v240, v241
	v_add_f32_e32 v238, v238, v239
	v_add_f32_e32 v78, v78, v238
	v_lshl_add_u64 v[198:199], v[198:199], 0, s[88:89]
	s_waitcnt vmcnt(15)
; __device__ __forceinline__ unsigned cvt_pk_bf16(float lo, float hi) { f32x2_cv v = {lo, hi}; bf16x2_cv b = __builtin_convertvector(v, bf16x2_cv); return __builtin_bit_cast(unsigned, b); }
;     __device__ __forceinline__ void operator()(const f32x4 (&acc)[2][2][4][2], const Unit& u, int wr, int wc, int fr, int fq) const {
;     ...
;             for (int m = 0; m < 4; ++m) {
;                 const int row = row0 + ai * HALF + m * 16; float ss = 0.f;
; #pragma unroll
;                 for (int bj = 0; bj < 2; ++bj) {
;                     const size_t off = (size_t)row * 1024 + col0 + bj * HALF;
;                     const u32x4 v = xv[m][bj];
;                     f32x4 x0 = {__uint_as_float(v.x << 16), __uint_as_float(v.x & 0xffff0000u), __uint_as_float(v.y << 16), __uint_as_float(v.y & 0xffff0000u)};
;                     f32x4 x1 = {__uint_as_float(v.z << 16), __uint_as_float(v.z & 0xffff0000u), __uint_as_float(v.w << 16), __uint_as_float(v.w & 0xffff0000u)};
;                     x0 = x0 + acc[ai][bj][m][0] * alpha; x1 = x1 + acc[ai][bj][m][1] * alpha;
;                     u32x4 w; w.x = cvt_pk_bf16(x0[0], x0[1]); w.y = cvt_pk_bf16(x0[2], x0[3]); w.z = cvt_pk_bf16(x1[0], x1[1]); w.w = cvt_pk_bf16(x1[2], x1[3]);
;                     *(u32x4*)(XB + off) = w;
;                     const f32x4 sq = x0 * x0 + x1 * x1;
;                     ss += (sq[0] + sq[1]) + (sq[2] + sq[3]);
;                 }
	v_lshlrev_b32_e32 v238, 16, v182
	v_and_b32_e32 v239, 0xffff0000, v182
	v_lshlrev_b32_e32 v240, 16, v183
	v_and_b32_e32 v241, 0xffff0000, v183
	v_lshlrev_b32_e32 v242, 16, v184
	v_and_b32_e32 v243, 0xffff0000, v184
	v_lshlrev_b32_e32 v244, 16, v185
	v_and_b32_e32 v245, 0xffff0000, v185
	v_pk_fma_f32 v[62:63], v[62:63], 0.5, v[238:239] op_sel_hi:[1,0,1]
	v_pk_fma_f32 v[64:65], v[64:65], 0.5, v[240:241] op_sel_hi:[1,0,1]
	v_pk_fma_f32 v[58:59], v[58:59], 0.5, v[242:243] op_sel_hi:[1,0,1]
	v_pk_fma_f32 v[60:61], v[60:61], 0.5, v[244:245] op_sel_hi:[1,0,1]
	v_cvt_pk_bf16_f32 v182, v62, v63
	v_cvt_pk_bf16_f32 v183, v64, v65
	v_cvt_pk_bf16_f32 v184, v58, v59
	v_cvt_pk_bf16_f32 v185, v60, v61
	global_store_dwordx4 v[198:199], v[182:185], off
	v_pk_mul_f32 v[238:239], v[58:59], v[58:59]
	v_pk_mul_f32 v[240:241], v[60:61], v[60:61]
	v_pk_fma_f32 v[238:239], v[62:63], v[62:63], v[238:239]
	v_pk_fma_f32 v[240:241], v[64:65], v[64:65], v[240:241]
	s_nop 0
	v_add_f32_e32 v238, v238, v239
	v_add_f32_e32 v239, v240, v241
	v_add_f32_e32 v62, v238, v239
	s_waitcnt vmcnt(15)
	v_lshlrev_b32_e32 v238, 16, v186
	v_and_b32_e32 v239, 0xffff0000, v186
	v_lshlrev_b32_e32 v240, 16, v187
	v_and_b32_e32 v241, 0xffff0000, v187
	v_lshlrev_b32_e32 v242, 16, v188
	v_and_b32_e32 v243, 0xffff0000, v188
	v_lshlrev_b32_e32 v244, 16, v189
	v_and_b32_e32 v245, 0xffff0000, v189
	v_pk_fma_f32 v[54:55], v[54:55], 0.5, v[238:239] op_sel_hi:[1,0,1]
	v_pk_fma_f32 v[56:57], v[56:57], 0.5, v[240:241] op_sel_hi:[1,0,1]
	v_pk_fma_f32 v[50:51], v[50:51], 0.5, v[242:243] op_sel_hi:[1,0,1]
	v_pk_fma_f32 v[52:53], v[52:53], 0.5, v[244:245] op_sel_hi:[1,0,1]
	v_cvt_pk_bf16_f32 v186, v54, v55
	v_cvt_pk_bf16_f32 v187, v56, v57
	v_cvt_pk_bf16_f32 v188, v50, v51
	v_cvt_pk_bf16_f32 v189, v52, v53
	global_store_dwordx4 v[198:199], v[186:189], off offset:256
	v_pk_mul_f32 v[238:239], v[50:51], v[50:51]
	v_pk_mul_f32 v[240:241], v[52:53], v[52:53]
	v_pk_fma_f32 v[238:239], v[54:55], v[54:55], v[238:239]
	v_pk_fma_f32 v[240:241], v[56:57], v[56:57], v[240:241]
	s_nop 0
	v_add_f32_e32 v238, v238, v239
	v_add_f32_e32 v239, v240, v241
	v_add_f32_e32 v238, v238, v239
	v_add_f32_e32 v62, v62, v238
	v_lshl_add_u64 v[198:199], v[198:199], 0, s[18:19]
	s_waitcnt vmcnt(15)
	v_lshlrev_b32_e32 v238, 16, v190
	v_and_b32_e32 v239, 0xffff0000, v190
	v_lshlrev_b32_e32 v240, 16, v191
	v_and_b32_e32 v241, 0xffff0000, v191
	v_lshlrev_b32_e32 v242, 16, v192
	v_and_b32_e32 v243, 0xffff0000, v192
	v_lshlrev_b32_e32 v244, 16, v193
	v_and_b32_e32 v245, 0xffff0000, v193
	v_pk_fma_f32 v[46:47], v[46:47], 0.5, v[238:239] op_sel_hi:[1,0,1]
	v_pk_fma_f32 v[48:49], v[48:49], 0.5, v[240:241] op_sel_hi:[1,0,1]
	v_pk_fma_f32 v[42:43], v[42:43], 0.5, v[242:243] op_sel_hi:[1,0,1]
	v_pk_fma_f32 v[44:45], v[44:45], 0.5, v[244:245] op_sel_hi:[1,0,1]
	v_cvt_pk_bf16_f32 v190, v46, v47
	v_cvt_pk_bf16_f32 v191, v48, v49
	v_cvt_pk_bf16_f32 v192, v42, v43
	v_cvt_pk_bf16_f32 v193, v44, v45
	global_store_dwordx4 v[198:199], v[190:193], off
	v_pk_mul_f32 v[238:239], v[42:43], v[42:43]
	v_pk_mul_f32 v[240:241], v[44:45], v[44:45]
	v_pk_fma_f32 v[238:239], v[46:47], v[46:47], v[238:239]
	v_pk_fma_f32 v[240:241], v[48:49], v[48:49], v[240:241]
	s_nop 0
	v_add_f32_e32 v238, v238, v239
	v_add_f32_e32 v239, v240, v241
	v_add_f32_e32 v46, v238, v239
	s_waitcnt vmcnt(15)
	v_lshlrev_b32_e32 v238, 16, v194
	v_and_b32_e32 v239, 0xffff0000, v194
	v_lshlrev_b32_e32 v240, 16, v195
	v_and_b32_e32 v241, 0xffff0000, v195
	v_lshlrev_b32_e32 v242, 16, v196
	v_and_b32_e32 v243, 0xffff0000, v196
	v_lshlrev_b32_e32 v244, 16, v197
	v_and_b32_e32 v245, 0xffff0000, v197
	v_pk_fma_f32 v[38:39], v[38:39], 0.5, v[238:239] op_sel_hi:[1,0,1]
	v_pk_fma_f32 v[40:41], v[40:41], 0.5, v[240:241] op_sel_hi:[1,0,1]
	v_pk_fma_f32 v[34:35], v[34:35], 0.5, v[242:243] op_sel_hi:[1,0,1]
	v_pk_fma_f32 v[36:37], v[36:37], 0.5, v[244:245] op_sel_hi:[1,0,1]
	v_cvt_pk_bf16_f32 v194, v38, v39
	v_cvt_pk_bf16_f32 v195, v40, v41
	v_cvt_pk_bf16_f32 v196, v34, v35
	v_cvt_pk_bf16_f32 v197, v36, v37
	global_store_dwordx4 v[198:199], v[194:197], off offset:256
	v_pk_mul_f32 v[238:239], v[34:35], v[34:35]
	v_pk_mul_f32 v[240:241], v[36:37], v[36:37]
	v_pk_fma_f32 v[238:239], v[38:39], v[38:39], v[238:239]
	v_pk_fma_f32 v[240:241], v[40:41], v[40:41], v[240:241]
	s_nop 0
	v_add_f32_e32 v238, v238, v239
	v_add_f32_e32 v239, v240, v241
	v_add_f32_e32 v238, v238, v239
	v_add_f32_e32 v46, v46, v238
	v_lshl_add_u64 v[198:199], v[198:199], 0, s[18:19]
	s_waitcnt vmcnt(15)
	v_lshlrev_b32_e32 v238, 16, v222
	v_and_b32_e32 v239, 0xffff0000, v222
	v_lshlrev_b32_e32 v240, 16, v223
	v_and_b32_e32 v241, 0xffff0000, v223
	v_lshlrev_b32_e32 v242, 16, v224
	v_and_b32_e32 v243, 0xffff0000, v224
	v_lshlrev_b32_e32 v244, 16, v225
	v_and_b32_e32 v245, 0xffff0000, v225
	v_pk_fma_f32 v[30:31], v[30:31], 0.5, v[238:239] op_sel_hi:[1,0,1]
	v_pk_fma_f32 v[32:33], v[32:33], 0.5, v[240:241] op_sel_hi:[1,0,1]
	v_pk_fma_f32 v[26:27], v[26:27], 0.5, v[242:243] op_sel_hi:[1,0,1]
	v_pk_fma_f32 v[28:29], v[28:29], 0.5, v[244:245] op_sel_hi:[1,0,1]
	v_cvt_pk_bf16_f32 v222, v30, v31
	v_cvt_pk_bf16_f32 v223, v32, v33
	v_cvt_pk_bf16_f32 v224, v26, v27
	v_cvt_pk_bf16_f32 v225, v28, v29
	global_store_dwordx4 v[198:199], v[222:225], off
	v_pk_mul_f32 v[238:239], v[26:27], v[26:27]
	v_pk_mul_f32 v[240:241], v[28:29], v[28:29]
	v_pk_fma_f32 v[238:239], v[30:31], v[30:31], v[238:239]
	v_pk_fma_f32 v[240:241], v[32:33], v[32:33], v[240:241]
	s_nop 0
	v_add_f32_e32 v238, v238, v239
	v_add_f32_e32 v239, v240, v241
	v_add_f32_e32 v30, v238, v239
	s_waitcnt vmcnt(15)
; __device__ __forceinline__ unsigned cvt_pk_bf16(float lo, float hi) { f32x2_cv v = {lo, hi}; bf16x2_cv b = __builtin_convertvector(v, bf16x2_cv); return __builtin_bit_cast(unsigned, b); }
;     __device__ __forceinline__ void operator()(const f32x4 (&acc)[2][2][4][2], const Unit& u, int wr, int wc, int fr, int fq) const {
;     ...
;                 for (int bj = 0; bj < 2; ++bj) {
;                     const size_t off = (size_t)row * 1024 + col0 + bj * HALF;
;                     const u32x4 v = xv[m][bj];
;                     f32x4 x0 = {__uint_as_float(v.x << 16), __uint_as_float(v.x & 0xffff0000u), __uint_as_float(v.y << 16), __uint_as_float(v.y & 0xffff0000u)};
;                     f32x4 x1 = {__uint_as_float(v.z << 16), __uint_as_float(v.z & 0xffff0000u), __uint_as_float(v.w << 16), __uint_as_float(v.w & 0xffff0000u)};
;                     x0 = x0 + acc[ai][bj][m][0] * alpha; x1 = x1 + acc[ai][bj][m][1] * alpha;
;                     u32x4 w; w.x = cvt_pk_bf16(x0[0], x0[1]); w.y = cvt_pk_bf16(x0[2], x0[3]); w.z = cvt_pk_bf16(x1[0], x1[1]); w.w = cvt_pk_bf16(x1[2], x1[3]);
;                     *(u32x4*)(XB + off) = w;
;                     const f32x4 sq = x0 * x0 + x1 * x1;
;                     ss += (sq[0] + sq[1]) + (sq[2] + sq[3]);
;                 }
;                 ss += __shfl_xor(ss, 16); ss += __shfl_xor(ss, 32);
;                 if (fq == 0) rsp_out[(size_t)row * 16 + u.pn * 4 + wc] = ss;
;             }
	v_lshlrev_b32_e32 v238, 16, v226
	v_and_b32_e32 v239, 0xffff0000, v226
	v_lshlrev_b32_e32 v240, 16, v227
	v_and_b32_e32 v241, 0xffff0000, v227
	v_lshlrev_b32_e32 v242, 16, v228
	v_and_b32_e32 v243, 0xffff0000, v228
	v_lshlrev_b32_e32 v244, 16, v229
	v_and_b32_e32 v245, 0xffff0000, v229
	v_pk_fma_f32 v[22:23], v[22:23], 0.5, v[238:239] op_sel_hi:[1,0,1]
	v_pk_fma_f32 v[24:25], v[24:25], 0.5, v[240:241] op_sel_hi:[1,0,1]
	v_pk_fma_f32 v[18:19], v[18:19], 0.5, v[242:243] op_sel_hi:[1,0,1]
	v_pk_fma_f32 v[20:21], v[20:21], 0.5, v[244:245] op_sel_hi:[1,0,1]
	v_cvt_pk_bf16_f32 v226, v22, v23
	v_cvt_pk_bf16_f32 v227, v24, v25
	v_cvt_pk_bf16_f32 v228, v18, v19
	v_cvt_pk_bf16_f32 v229, v20, v21
	global_store_dwordx4 v[198:199], v[226:229], off offset:256
	v_pk_mul_f32 v[238:239], v[18:19], v[18:19]
	v_pk_mul_f32 v[240:241], v[20:21], v[20:21]
	v_pk_fma_f32 v[238:239], v[22:23], v[22:23], v[238:239]
	v_pk_fma_f32 v[240:241], v[24:25], v[24:25], v[240:241]
	s_nop 0
	v_add_f32_e32 v238, v238, v239
	v_add_f32_e32 v239, v240, v241
	v_add_f32_e32 v238, v238, v239
	v_add_f32_e32 v30, v30, v238
	v_lshl_add_u64 v[198:199], v[198:199], 0, s[18:19]
	s_waitcnt vmcnt(15)
	v_lshlrev_b32_e32 v238, 16, v230
	v_and_b32_e32 v239, 0xffff0000, v230
	v_lshlrev_b32_e32 v240, 16, v231
	v_and_b32_e32 v241, 0xffff0000, v231
	v_lshlrev_b32_e32 v242, 16, v232
	v_and_b32_e32 v243, 0xffff0000, v232
	v_lshlrev_b32_e32 v244, 16, v233
	v_and_b32_e32 v245, 0xffff0000, v233
	v_pk_fma_f32 v[14:15], v[14:15], 0.5, v[238:239] op_sel_hi:[1,0,1]
	v_pk_fma_f32 v[16:17], v[16:17], 0.5, v[240:241] op_sel_hi:[1,0,1]
	v_pk_fma_f32 v[10:11], v[10:11], 0.5, v[242:243] op_sel_hi:[1,0,1]
	v_pk_fma_f32 v[12:13], v[12:13], 0.5, v[244:245] op_sel_hi:[1,0,1]
	v_cvt_pk_bf16_f32 v230, v14, v15
	v_cvt_pk_bf16_f32 v231, v16, v17
	v_cvt_pk_bf16_f32 v232, v10, v11
	v_cvt_pk_bf16_f32 v233, v12, v13
	global_store_dwordx4 v[198:199], v[230:233], off
	v_pk_mul_f32 v[238:239], v[10:11], v[10:11]
	v_pk_mul_f32 v[240:241], v[12:13], v[12:13]
	v_pk_fma_f32 v[238:239], v[14:15], v[14:15], v[238:239]
	v_pk_fma_f32 v[240:241], v[16:17], v[16:17], v[240:241]
	s_nop 0
	v_add_f32_e32 v238, v238, v239
	v_add_f32_e32 v239, v240, v241
	v_add_f32_e32 v14, v238, v239
	s_waitcnt vmcnt(15)
	v_lshlrev_b32_e32 v238, 16, v234
	v_and_b32_e32 v239, 0xffff0000, v234
	v_lshlrev_b32_e32 v240, 16, v235
	v_and_b32_e32 v241, 0xffff0000, v235
	v_lshlrev_b32_e32 v242, 16, v236
	v_and_b32_e32 v243, 0xffff0000, v236
	v_lshlrev_b32_e32 v244, 16, v237
	v_and_b32_e32 v245, 0xffff0000, v237
	v_pk_fma_f32 v[6:7], v[6:7], 0.5, v[238:239] op_sel_hi:[1,0,1]
	v_pk_fma_f32 v[8:9], v[8:9], 0.5, v[240:241] op_sel_hi:[1,0,1]
	v_pk_fma_f32 v[2:3], v[2:3], 0.5, v[242:243] op_sel_hi:[1,0,1]
	v_pk_fma_f32 v[4:5], v[4:5], 0.5, v[244:245] op_sel_hi:[1,0,1]
	v_cvt_pk_bf16_f32 v234, v6, v7
	v_cvt_pk_bf16_f32 v235, v8, v9
	v_cvt_pk_bf16_f32 v236, v2, v3
	v_cvt_pk_bf16_f32 v237, v4, v5
	global_store_dwordx4 v[198:199], v[234:237], off offset:256
	v_pk_mul_f32 v[238:239], v[2:3], v[2:3]
	v_pk_mul_f32 v[240:241], v[4:5], v[4:5]
	v_pk_fma_f32 v[238:239], v[6:7], v[6:7], v[238:239]
	v_pk_fma_f32 v[240:241], v[8:9], v[8:9], v[240:241]
	s_nop 0
	v_add_f32_e32 v238, v238, v239
	v_add_f32_e32 v239, v240, v241
	v_add_f32_e32 v238, v238, v239
	v_add_f32_e32 v14, v14, v238
	ds_bpermute_b32 v127, v215, v126
	ds_bpermute_b32 v111, v215, v110
	ds_bpermute_b32 v95, v215, v94
	ds_bpermute_b32 v79, v215, v78
	ds_bpermute_b32 v63, v215, v62
	ds_bpermute_b32 v47, v215, v46
	ds_bpermute_b32 v31, v215, v30
	ds_bpermute_b32 v15, v215, v14
	s_waitcnt lgkmcnt(0)
	v_add_f32_e32 v126, v126, v127
	v_add_f32_e32 v110, v110, v111
	v_add_f32_e32 v94, v94, v95
	v_add_f32_e32 v78, v78, v79
	v_add_f32_e32 v62, v62, v63
	v_add_f32_e32 v46, v46, v47
	v_add_f32_e32 v30, v30, v31
	v_add_f32_e32 v14, v14, v15
	ds_bpermute_b32 v127, v216, v126
	ds_bpermute_b32 v111, v216, v110
	ds_bpermute_b32 v95, v216, v94
	ds_bpermute_b32 v79, v216, v78
	ds_bpermute_b32 v63, v216, v62
	ds_bpermute_b32 v47, v216, v46
	ds_bpermute_b32 v31, v216, v30
	ds_bpermute_b32 v15, v216, v14
	s_waitcnt lgkmcnt(0)
	v_add_f32_e32 v126, v126, v127
	v_add_f32_e32 v110, v110, v111
	v_add_f32_e32 v94, v94, v95
	v_add_f32_e32 v78, v78, v79
	v_add_f32_e32 v62, v62, v63
	v_add_f32_e32 v46, v46, v47
	v_add_f32_e32 v30, v30, v31
	v_add_f32_e32 v14, v14, v15
	s_lshl_b32 s18, s45, 4
	s_lshl_b32 s88, s34, 2
	s_add_i32 s18, s18, s88
	v_lshlrev_b32_e32 v246, 6, v217
	v_mov_b32_e32 v247, 0
	v_lshl_add_u64 v[246:247], s[76:77], 0, v[246:247]
	v_lshl_add_u64 v[246:247], v[246:247], 0, s[18:19]
	s_mov_b32 s18, 0x2000
	v_lshl_add_u64 v[198:199], v[246:247], 0, s[18:19]
	s_and_saveexec_b64 s[20:21], s[4:5]
	global_store_dword v[246:247], v126, off
	global_store_dword v[246:247], v110, off offset:1024
	global_store_dword v[246:247], v94, off offset:2048
	global_store_dword v[246:247], v78, off offset:3072
	global_store_dword v[198:199], v62, off
	global_store_dword v[198:199], v46, off offset:1024
	global_store_dword v[198:199], v30, off offset:2048
	global_store_dword v[198:199], v14, off offset:3072
	s_or_b64 exec, exec, s[20:21]
	s_and_b64 vcc, exec, s[6:7]
	s_mov_b64 s[6:7], -1
	s_cbranch_vccnz .LBB0_447
	s_andn2_b64 vcc, exec, s[12:13]
	s_cbranch_vccnz .LBB0_446
	s_barrier
	s_branch .LBB0_446

; #define PG8_STAGE(bufoff, gbase, voff) do { _Pragma("unroll") for (int _i = 0; _i < 2; ++_i) \
;         __builtin_amdgcn_global_load_lds((const unsigned*)((const char*)(gbase) + (voff)[_i]), (PG8_LAS unsigned*)(lds + (bufoff) + ldsw + _i * 8192), 16, 0, 0); } while (0)
; #define PG8_LDA(dst, b, h) do { _Pragma("unroll") for (int m = 0; m < 4; ++m) _Pragma("unroll") for (int k = 0; k < 2; ++k) dst[m][k] = *(const PG8_LAS bf16x8*)(lds + PG8_SA(b, h) + aoff + m * 2048 + k * 1024); } while (0)
; #define PG8_LDB(dst, b, h) do { _Pragma("unroll") for (int n = 0; n < 2; ++n) _Pragma("unroll") for (int k = 0; k < 2; ++k) dst[n][k] = *(const PG8_LAS bf16x8*)(lds + PG8_SB(b, h) + boff + n * 2048 + k * 1024); } while (0)
; #define PG8_MMA(ai, bj, At, Bt) do { __builtin_amdgcn_s_setprio(1); _Pragma("unroll") for (int m = 0; m < 4; ++m) _Pragma("unroll") for (int n = 0; n < 2; ++n) _Pragma("unroll") for (int k = 0; k < 2; ++k) \
;         acc[ai][bj][m][n] = __builtin_amdgcn_mfma_f32_16x16x32_bf16(Bt[n][k], At[m][k], acc[ai][bj][m][n], 0, 0, 0); __builtin_amdgcn_s_setprio(0); } while (0)
; #define PG8_WAIT_V(n) asm volatile("s_waitcnt vmcnt(" #n ")" ::: "memory")
; #define PG8_WAIT_L(n) asm volatile("s_waitcnt lgkmcnt(" #n ")" ::: "memory")
; #define PG8_BAR __builtin_amdgcn_s_barrier()
; #define PG8_SCHED __builtin_amdgcn_sched_barrier(0)
; template <class Epi, class Sched, bool ALIGN_EPI = false, bool SP2 = false>
; __device__ __forceinline__ void gemm_phase(PG8_LAS unsigned char* lds, const Gemm g, const Sched& S, const Epi& E) {
;     ...
;             PG8_LDB(B0, 0, 0); PG8_LDB(B1, 0, 1); PG8_SCHED; PG8_LDA(At, 0, 0); PG8_STAGE(PG8_SA(1, 1), a1 + hstep, voffA);
;             PG8_WAIT_V(8); PG8_WAIT_L(0); PG8_BAR; PG8_MMA(0, 0, At, B0); PG8_MMA(0, 1, At, B1); PG8_BAR; PG8_SCHED;
;             PG8_LDA(At, 0, 1); PG8_STAGE(PG8_SB(0, 0), b2, voffB); PG8_STAGE(PG8_SB(0, 1), b2 + hstep, voffB); PG8_STAGE(PG8_SA(0, 0), a2, voffA);
;             PG8_WAIT_V(8); PG8_WAIT_L(0); PG8_BAR; PG8_MMA(1, 0, At, B0); PG8_MMA(1, 1, At, B1); PG8_BAR; PG8_SCHED;
;             PG8_LDB(B0, 1, 0); PG8_LDB(B1, 1, 1); PG8_SCHED; PG8_LDA(At, 1, 0); PG8_STAGE(PG8_SA(0, 1), a2 + hstep, voffA);
;             PG8_WAIT_V(8); PG8_WAIT_L(0); PG8_BAR; PG8_MMA(0, 0, At, B0); PG8_MMA(0, 1, At, B1); PG8_BAR; PG8_SCHED;
.LBB0_493:
	s_add_u32 s24, s22, 0xfffc0080
	s_addc_u32 s25, s23, -1
	s_add_i32 s51, 0, 0x10000
	s_cmp_eq_u32 s50, 12
	s_cselect_b32 s27, s17, s25
	s_cselect_b32 s26, s46, s24
	v_add_u32_e32 v146, s51, v149
	s_cselect_b32 s25, s15, s49
	s_cselect_b32 s24, s47, s48
	s_add_i32 s54, 0, 0x14000
	ds_read_b128 v[142:145], v146
	ds_read_b128 v[152:155], v146 offset:1024
	ds_read_b128 v[172:175], v146 offset:2048
	ds_read_b128 v[176:179], v146 offset:3072
	v_add_u32_e32 v146, s54, v149
	ds_read_b128 v[180:183], v146
	ds_read_b128 v[184:187], v146 offset:1024
	ds_read_b128 v[188:191], v146 offset:2048
	ds_read_b128 v[192:195], v146 offset:3072
	s_add_i32 m0, s30, 0xc000
	ds_read_b128 v[196:199], v151
	ds_read_b128 v[214:217], v151 offset:1024
	ds_read_b128 v[218:221], v151 offset:2048
	ds_read_b128 v[222:225], v151 offset:3072
	ds_read_b128 v[226:229], v151 offset:4096
	ds_read_b128 v[230:233], v151 offset:5120
	ds_read_b128 v[234:237], v151 offset:6144
	ds_read_b128 v[238:241], v151 offset:7168
	global_load_lds_dwordx4 v138, s[22:23]
	s_add_i32 m0, s30, 0xe000
	s_nop 0
	global_load_lds_dwordx4 v140, s[22:23]
	s_waitcnt vmcnt(8)
	s_waitcnt lgkmcnt(0)
	s_barrier
	s_setprio 1
	s_waitcnt lgkmcnt(0)
	v_mfma_f32_16x16x32_bf16 v[126:129], v[142:145], v[196:199], v[126:129]
	v_mfma_f32_16x16x32_bf16 v[118:121], v[172:175], v[196:199], v[118:121]
	v_mfma_f32_16x16x32_bf16 v[110:113], v[142:145], v[218:221], v[110:113]
	v_mfma_f32_16x16x32_bf16 v[102:105], v[172:175], v[218:221], v[102:105]
	v_mfma_f32_16x16x32_bf16 v[94:97], v[142:145], v[226:229], v[94:97]
	v_mfma_f32_16x16x32_bf16 v[86:89], v[172:175], v[226:229], v[86:89]
	v_mfma_f32_16x16x32_bf16 v[78:81], v[142:145], v[234:237], v[78:81]
	v_mfma_f32_16x16x32_bf16 v[70:73], v[172:175], v[234:237], v[70:73]
	v_mfma_f32_16x16x32_bf16 v[126:129], v[152:155], v[214:217], v[126:129]
	v_mfma_f32_16x16x32_bf16 v[118:121], v[176:179], v[214:217], v[118:121]
	v_mfma_f32_16x16x32_bf16 v[110:113], v[152:155], v[222:225], v[110:113]
	v_mfma_f32_16x16x32_bf16 v[102:105], v[176:179], v[222:225], v[102:105]
	v_mfma_f32_16x16x32_bf16 v[94:97], v[152:155], v[230:233], v[94:97]
	v_mfma_f32_16x16x32_bf16 v[86:89], v[176:179], v[230:233], v[86:89]
	v_mfma_f32_16x16x32_bf16 v[78:81], v[152:155], v[238:241], v[78:81]
	v_mfma_f32_16x16x32_bf16 v[70:73], v[176:179], v[238:241], v[70:73]
	s_setprio 0
	s_setprio 1
	v_mfma_f32_16x16x32_bf16 v[122:125], v[180:183], v[196:199], v[122:125]
	v_mfma_f32_16x16x32_bf16 v[114:117], v[188:191], v[196:199], v[114:117]
	v_mfma_f32_16x16x32_bf16 v[106:109], v[180:183], v[218:221], v[106:109]
	v_mfma_f32_16x16x32_bf16 v[98:101], v[188:191], v[218:221], v[98:101]
	v_mfma_f32_16x16x32_bf16 v[90:93], v[180:183], v[226:229], v[90:93]
	v_mfma_f32_16x16x32_bf16 v[82:85], v[188:191], v[226:229], v[82:85]
	v_mfma_f32_16x16x32_bf16 v[74:77], v[180:183], v[234:237], v[74:77]
	v_mfma_f32_16x16x32_bf16 v[66:69], v[188:191], v[234:237], v[66:69]
	v_mfma_f32_16x16x32_bf16 v[122:125], v[184:187], v[214:217], v[122:125]
	v_mfma_f32_16x16x32_bf16 v[114:117], v[192:195], v[214:217], v[114:117]
	v_mfma_f32_16x16x32_bf16 v[106:109], v[184:187], v[222:225], v[106:109]
	v_mfma_f32_16x16x32_bf16 v[98:101], v[192:195], v[222:225], v[98:101]
	v_mfma_f32_16x16x32_bf16 v[90:93], v[184:187], v[230:233], v[90:93]
	v_mfma_f32_16x16x32_bf16 v[82:85], v[192:195], v[230:233], v[82:85]
	v_mfma_f32_16x16x32_bf16 v[74:77], v[184:187], v[238:241], v[74:77]
	v_mfma_f32_16x16x32_bf16 v[66:69], v[192:195], v[238:241], v[66:69]
	s_setprio 0
	s_barrier
	s_add_i32 s51, s51, s2
	s_mov_b32 m0, s51
	ds_read_b128 v[196:199], v151 offset:16384
	ds_read_b128 v[214:217], v151 offset:17408
	ds_read_b128 v[218:221], v151 offset:18432
	ds_read_b128 v[222:225], v151 offset:19456
	ds_read_b128 v[226:229], v151 offset:20480
	ds_read_b128 v[230:233], v151 offset:21504
	ds_read_b128 v[234:237], v151 offset:22528
	ds_read_b128 v[238:241], v151 offset:23552
	global_load_lds_dwordx4 v0, s[24:25]
	s_add_i32 m0, s51, 0x2000
	s_add_u32 s52, s24, 0x40000
	s_addc_u32 s53, s25, 0
	s_add_i32 s51, s54, s2
	global_load_lds_dwordx4 v130, s[24:25]
	s_mov_b32 m0, s51
	s_nop 0
	global_load_lds_dwordx4 v0, s[52:53]
	s_add_i32 m0, s51, 0x2000
	s_nop 0
	global_load_lds_dwordx4 v130, s[52:53]
	s_mov_b32 m0, s30
	s_nop 0
	global_load_lds_dwordx4 v134, s[26:27]
	s_mov_b32 m0, s31
	s_nop 0
	global_load_lds_dwordx4 v132, s[26:27]
	s_waitcnt vmcnt(8)
	s_waitcnt lgkmcnt(0)
	s_barrier
	s_setprio 1
	s_waitcnt lgkmcnt(0)
	v_mfma_f32_16x16x32_bf16 v[62:65], v[142:145], v[196:199], v[62:65]
	v_mfma_f32_16x16x32_bf16 v[54:57], v[172:175], v[196:199], v[54:57]
	v_mfma_f32_16x16x32_bf16 v[46:49], v[142:145], v[218:221], v[46:49]
	v_mfma_f32_16x16x32_bf16 v[38:41], v[172:175], v[218:221], v[38:41]
	v_mfma_f32_16x16x32_bf16 v[30:33], v[142:145], v[226:229], v[30:33]
	v_mfma_f32_16x16x32_bf16 v[22:25], v[172:175], v[226:229], v[22:25]
	v_mfma_f32_16x16x32_bf16 v[14:17], v[142:145], v[234:237], v[14:17]
	v_mfma_f32_16x16x32_bf16 v[6:9], v[172:175], v[234:237], v[6:9]
	v_mfma_f32_16x16x32_bf16 v[62:65], v[152:155], v[214:217], v[62:65]
	v_mfma_f32_16x16x32_bf16 v[54:57], v[176:179], v[214:217], v[54:57]
	v_mfma_f32_16x16x32_bf16 v[46:49], v[152:155], v[222:225], v[46:49]
	v_mfma_f32_16x16x32_bf16 v[38:41], v[176:179], v[222:225], v[38:41]
	v_mfma_f32_16x16x32_bf16 v[30:33], v[152:155], v[230:233], v[30:33]
	v_mfma_f32_16x16x32_bf16 v[22:25], v[176:179], v[230:233], v[22:25]
	v_mfma_f32_16x16x32_bf16 v[14:17], v[152:155], v[238:241], v[14:17]
	v_mfma_f32_16x16x32_bf16 v[6:9], v[176:179], v[238:241], v[6:9]
	s_setprio 0
	s_setprio 1
	v_mfma_f32_16x16x32_bf16 v[58:61], v[180:183], v[196:199], v[58:61]
	v_mfma_f32_16x16x32_bf16 v[50:53], v[188:191], v[196:199], v[50:53]
	v_mfma_f32_16x16x32_bf16 v[42:45], v[180:183], v[218:221], v[42:45]
	v_mfma_f32_16x16x32_bf16 v[34:37], v[188:191], v[218:221], v[34:37]
	v_mfma_f32_16x16x32_bf16 v[26:29], v[180:183], v[226:229], v[26:29]
	v_mfma_f32_16x16x32_bf16 v[18:21], v[188:191], v[226:229], v[18:21]
	v_mfma_f32_16x16x32_bf16 v[10:13], v[180:183], v[234:237], v[10:13]
	v_mfma_f32_16x16x32_bf16 v[2:5], v[188:191], v[234:237], v[2:5]
	v_mfma_f32_16x16x32_bf16 v[58:61], v[184:187], v[214:217], v[58:61]
	v_mfma_f32_16x16x32_bf16 v[50:53], v[192:195], v[214:217], v[50:53]
	v_mfma_f32_16x16x32_bf16 v[42:45], v[184:187], v[222:225], v[42:45]
	v_mfma_f32_16x16x32_bf16 v[34:37], v[192:195], v[222:225], v[34:37]
	v_mfma_f32_16x16x32_bf16 v[26:29], v[184:187], v[230:233], v[26:29]
	v_mfma_f32_16x16x32_bf16 v[18:21], v[192:195], v[230:233], v[18:21]
	v_mfma_f32_16x16x32_bf16 v[10:13], v[184:187], v[238:241], v[10:13]
	v_mfma_f32_16x16x32_bf16 v[2:5], v[192:195], v[238:241], v[2:5]
	s_setprio 0
	s_barrier
; #define PG8_STAGE(bufoff, gbase, voff) do { _Pragma("unroll") for (int _i = 0; _i < 2; ++_i) \
;         __builtin_amdgcn_global_load_lds((const unsigned*)((const char*)(gbase) + (voff)[_i]), (PG8_LAS unsigned*)(lds + (bufoff) + ldsw + _i * 8192), 16, 0, 0); } while (0)
; #define PG8_LDA(dst, b, h) do { _Pragma("unroll") for (int m = 0; m < 4; ++m) _Pragma("unroll") for (int k = 0; k < 2; ++k) dst[m][k] = *(const PG8_LAS bf16x8*)(lds + PG8_SA(b, h) + aoff + m * 2048 + k * 1024); } while (0)
; #define PG8_LDB(dst, b, h) do { _Pragma("unroll") for (int n = 0; n < 2; ++n) _Pragma("unroll") for (int k = 0; k < 2; ++k) dst[n][k] = *(const PG8_LAS bf16x8*)(lds + PG8_SB(b, h) + boff + n * 2048 + k * 1024); } while (0)
; #define PG8_MMA(ai, bj, At, Bt) do { __builtin_amdgcn_s_setprio(1); _Pragma("unroll") for (int m = 0; m < 4; ++m) _Pragma("unroll") for (int n = 0; n < 2; ++n) _Pragma("unroll") for (int k = 0; k < 2; ++k) \
;         acc[ai][bj][m][n] = __builtin_amdgcn_mfma_f32_16x16x32_bf16(Bt[n][k], At[m][k], acc[ai][bj][m][n], 0, 0, 0); __builtin_amdgcn_s_setprio(0); } while (0)
; #define PG8_WAIT_V(n) asm volatile("s_waitcnt vmcnt(" #n ")" ::: "memory")
; #define PG8_WAIT_L(n) asm volatile("s_waitcnt lgkmcnt(" #n ")" ::: "memory")
; #define PG8_BAR __builtin_amdgcn_s_barrier()
; #define PG8_SCHED __builtin_amdgcn_sched_barrier(0)
; template <class Epi, class Sched, bool ALIGN_EPI = false, bool SP2 = false>
; __device__ __forceinline__ void gemm_phase(PG8_LAS unsigned char* lds, const Gemm g, const Sched& S, const Epi& E) {
;     ...
;             PG8_LDB(B0, 1, 0); PG8_LDB(B1, 1, 1); PG8_SCHED; PG8_LDA(At, 1, 0); PG8_STAGE(PG8_SA(0, 1), a2 + hstep, voffA);
;             PG8_WAIT_V(8); PG8_WAIT_L(0); PG8_BAR; PG8_MMA(0, 0, At, B0); PG8_MMA(0, 1, At, B1); PG8_BAR; PG8_SCHED;
;             PG8_LDA(At, 1, 1); PG8_STAGE(PG8_SB(1, 0), b3, voffB); PG8_STAGE(PG8_SB(1, 1), b3 + hstep, voffB); PG8_STAGE(PG8_SA(1, 0), a3, voffA);
;             PG8_WAIT_V(8); PG8_WAIT_L(0); PG8_BAR; PG8_MMA(1, 0, At, B0); PG8_MMA(1, 1, At, B1); PG8_BAR; PG8_SCHED;
	s_add_i32 s51, 0, 0x18000
	v_add_u32_e32 v158, s51, v149
	s_add_i32 s52, 0, 0x1c000
	ds_read_b128 v[142:145], v158
	ds_read_b128 v[152:155], v158 offset:1024
	ds_read_b128 v[172:175], v158 offset:2048
	ds_read_b128 v[176:179], v158 offset:3072
	v_add_u32_e32 v158, s52, v149
	ds_read_b128 v[180:183], v158
	ds_read_b128 v[184:187], v158 offset:1024
	ds_read_b128 v[188:191], v158 offset:2048
	ds_read_b128 v[192:195], v158 offset:3072
	s_add_u32 s26, s26, 0x40000
	s_addc_u32 s27, s27, 0
	s_mov_b32 m0, s34
	ds_read_b128 v[196:199], v151 offset:32768
	ds_read_b128 v[214:217], v151 offset:33792
	ds_read_b128 v[218:221], v151 offset:34816
	ds_read_b128 v[222:225], v151 offset:35840
	ds_read_b128 v[226:229], v151 offset:36864
	ds_read_b128 v[230:233], v151 offset:37888
	ds_read_b128 v[234:237], v151 offset:38912
	ds_read_b128 v[238:241], v151 offset:39936
	global_load_lds_dwordx4 v134, s[26:27]
	s_mov_b32 m0, s35
	s_nop 0
	global_load_lds_dwordx4 v132, s[26:27]
	s_waitcnt vmcnt(8)
	s_waitcnt lgkmcnt(0)
	s_barrier
	s_setprio 1
	s_waitcnt lgkmcnt(0)
	v_mfma_f32_16x16x32_bf16 v[126:129], v[142:145], v[196:199], v[126:129]
	v_mfma_f32_16x16x32_bf16 v[118:121], v[172:175], v[196:199], v[118:121]
	v_mfma_f32_16x16x32_bf16 v[110:113], v[142:145], v[218:221], v[110:113]
	v_mfma_f32_16x16x32_bf16 v[102:105], v[172:175], v[218:221], v[102:105]
	v_mfma_f32_16x16x32_bf16 v[94:97], v[142:145], v[226:229], v[94:97]
	v_mfma_f32_16x16x32_bf16 v[86:89], v[172:175], v[226:229], v[86:89]
	v_mfma_f32_16x16x32_bf16 v[78:81], v[142:145], v[234:237], v[78:81]
	v_mfma_f32_16x16x32_bf16 v[70:73], v[172:175], v[234:237], v[70:73]
	v_mfma_f32_16x16x32_bf16 v[126:129], v[152:155], v[214:217], v[126:129]
	v_mfma_f32_16x16x32_bf16 v[118:121], v[176:179], v[214:217], v[118:121]
	v_mfma_f32_16x16x32_bf16 v[110:113], v[152:155], v[222:225], v[110:113]
	v_mfma_f32_16x16x32_bf16 v[102:105], v[176:179], v[222:225], v[102:105]
	v_mfma_f32_16x16x32_bf16 v[94:97], v[152:155], v[230:233], v[94:97]
	v_mfma_f32_16x16x32_bf16 v[86:89], v[176:179], v[230:233], v[86:89]
	v_mfma_f32_16x16x32_bf16 v[78:81], v[152:155], v[238:241], v[78:81]
	v_mfma_f32_16x16x32_bf16 v[70:73], v[176:179], v[238:241], v[70:73]
	s_setprio 0
	s_setprio 1
	v_mfma_f32_16x16x32_bf16 v[122:125], v[180:183], v[196:199], v[122:125]
	v_mfma_f32_16x16x32_bf16 v[114:117], v[188:191], v[196:199], v[114:117]
	v_mfma_f32_16x16x32_bf16 v[106:109], v[180:183], v[218:221], v[106:109]
	v_mfma_f32_16x16x32_bf16 v[98:101], v[188:191], v[218:221], v[98:101]
	v_mfma_f32_16x16x32_bf16 v[90:93], v[180:183], v[226:229], v[90:93]
	v_mfma_f32_16x16x32_bf16 v[82:85], v[188:191], v[226:229], v[82:85]
	v_mfma_f32_16x16x32_bf16 v[74:77], v[180:183], v[234:237], v[74:77]
	v_mfma_f32_16x16x32_bf16 v[66:69], v[188:191], v[234:237], v[66:69]
	v_mfma_f32_16x16x32_bf16 v[122:125], v[184:187], v[214:217], v[122:125]
	v_mfma_f32_16x16x32_bf16 v[114:117], v[192:195], v[214:217], v[114:117]
	v_mfma_f32_16x16x32_bf16 v[106:109], v[184:187], v[222:225], v[106:109]
	v_mfma_f32_16x16x32_bf16 v[98:101], v[192:195], v[222:225], v[98:101]
	v_mfma_f32_16x16x32_bf16 v[90:93], v[184:187], v[230:233], v[90:93]
	v_mfma_f32_16x16x32_bf16 v[82:85], v[192:195], v[230:233], v[82:85]
	v_mfma_f32_16x16x32_bf16 v[74:77], v[184:187], v[238:241], v[74:77]
	v_mfma_f32_16x16x32_bf16 v[66:69], v[192:195], v[238:241], v[66:69]
	s_setprio 0
	s_barrier
	s_add_u32 s98, s26, 0xfffc0080
	s_addc_u32 s99, s27, -1
	s_add_i32 s26, s51, s2
	s_add_u32 s100, s24, 0x80
	s_addc_u32 s101, s25, 0
	s_mov_b32 m0, s26
	ds_read_b128 v[196:199], v151 offset:49152
	ds_read_b128 v[214:217], v151 offset:50176
	ds_read_b128 v[218:221], v151 offset:51200
	ds_read_b128 v[222:225], v151 offset:52224
	ds_read_b128 v[226:229], v151 offset:53248
	ds_read_b128 v[230:233], v151 offset:54272
	ds_read_b128 v[234:237], v151 offset:55296
	ds_read_b128 v[238:241], v151 offset:56320
	global_load_lds_dwordx4 v0, s[100:101]
	s_add_i32 m0, s26, 0x2000
	s_add_u32 s24, s24, 0x40080
	s_addc_u32 s25, s25, 0
	s_add_i32 s26, s52, s2
	global_load_lds_dwordx4 v130, s[100:101]
	s_mov_b32 m0, s26
	s_nop 0
	global_load_lds_dwordx4 v0, s[24:25]
	s_add_i32 m0, s26, 0x2000
	s_nop 0
	global_load_lds_dwordx4 v130, s[24:25]
	s_mov_b32 m0, s37
	s_nop 0
	global_load_lds_dwordx4 v134, s[98:99]
	s_mov_b32 m0, s38
	s_nop 0
	global_load_lds_dwordx4 v132, s[98:99]
	s_waitcnt vmcnt(8)
	s_waitcnt lgkmcnt(0)
	s_barrier
	s_setprio 1
	s_waitcnt lgkmcnt(0)
	v_mfma_f32_16x16x32_bf16 v[62:65], v[142:145], v[196:199], v[62:65]
	v_mfma_f32_16x16x32_bf16 v[54:57], v[172:175], v[196:199], v[54:57]
	v_mfma_f32_16x16x32_bf16 v[46:49], v[142:145], v[218:221], v[46:49]
	v_mfma_f32_16x16x32_bf16 v[38:41], v[172:175], v[218:221], v[38:41]
	v_mfma_f32_16x16x32_bf16 v[30:33], v[142:145], v[226:229], v[30:33]
	v_mfma_f32_16x16x32_bf16 v[22:25], v[172:175], v[226:229], v[22:25]
	v_mfma_f32_16x16x32_bf16 v[14:17], v[142:145], v[234:237], v[14:17]
	v_mfma_f32_16x16x32_bf16 v[6:9], v[172:175], v[234:237], v[6:9]
	v_mfma_f32_16x16x32_bf16 v[62:65], v[152:155], v[214:217], v[62:65]
	v_mfma_f32_16x16x32_bf16 v[54:57], v[176:179], v[214:217], v[54:57]
	v_mfma_f32_16x16x32_bf16 v[46:49], v[152:155], v[222:225], v[46:49]
	v_mfma_f32_16x16x32_bf16 v[38:41], v[176:179], v[222:225], v[38:41]
	v_mfma_f32_16x16x32_bf16 v[30:33], v[152:155], v[230:233], v[30:33]
	v_mfma_f32_16x16x32_bf16 v[22:25], v[176:179], v[230:233], v[22:25]
	v_mfma_f32_16x16x32_bf16 v[14:17], v[152:155], v[238:241], v[14:17]
	v_mfma_f32_16x16x32_bf16 v[6:9], v[176:179], v[238:241], v[6:9]
	s_setprio 0
	s_setprio 1
	v_mfma_f32_16x16x32_bf16 v[58:61], v[180:183], v[196:199], v[58:61]
	v_mfma_f32_16x16x32_bf16 v[50:53], v[188:191], v[196:199], v[50:53]
	v_mfma_f32_16x16x32_bf16 v[42:45], v[180:183], v[218:221], v[42:45]
	v_mfma_f32_16x16x32_bf16 v[34:37], v[188:191], v[218:221], v[34:37]
	v_mfma_f32_16x16x32_bf16 v[26:29], v[180:183], v[226:229], v[26:29]
	v_mfma_f32_16x16x32_bf16 v[18:21], v[188:191], v[226:229], v[18:21]
	v_mfma_f32_16x16x32_bf16 v[10:13], v[180:183], v[234:237], v[10:13]
	v_mfma_f32_16x16x32_bf16 v[2:5], v[188:191], v[234:237], v[2:5]
	v_mfma_f32_16x16x32_bf16 v[58:61], v[184:187], v[214:217], v[58:61]
	v_mfma_f32_16x16x32_bf16 v[50:53], v[192:195], v[214:217], v[50:53]
	v_mfma_f32_16x16x32_bf16 v[42:45], v[184:187], v[222:225], v[42:45]
	v_mfma_f32_16x16x32_bf16 v[34:37], v[192:195], v[222:225], v[34:37]
	v_mfma_f32_16x16x32_bf16 v[26:29], v[184:187], v[230:233], v[26:29]
	v_mfma_f32_16x16x32_bf16 v[18:21], v[192:195], v[230:233], v[18:21]
	v_mfma_f32_16x16x32_bf16 v[10:13], v[184:187], v[238:241], v[10:13]
	v_mfma_f32_16x16x32_bf16 v[2:5], v[192:195], v[238:241], v[2:5]
	s_setprio 0
	s_barrier
; __device__ __forceinline__ float row_rstd(const float* rsp, int row, int fq) {
;     const f32x4 v = *(const f32x4*)(rsp + (size_t)row * 16 + 4 * fq);
;     float s = (v[0] + v[1]) + (v[2] + v[3]); s += __shfl_xor(s, 16); s += __shfl_xor(s, 32);
;     return rsqrtf(s * (1.0f / 1024.0f) + RMS_EPS);
;     __device__ __forceinline__ void operator()(const f32x4 (&acc)[2][2][4][2], const Unit& u, int wr, int wc, int fr, int fq) const {
;         const int row0 = u.pm * BM + wr * 64 + fr, col0 = u.pn * HALF + wc * 32 + 8 * fq;
; #pragma unroll
;         for (int ai = 0; ai < 2; ++ai)
; #pragma unroll
;             for (int m = 0; m < 4; ++m) {
;                 const int row = row0 + ai * HALF + m * 16; const float rs = row_rstd(rsp, row, fq);
;                 const float nrs = -LOG2E * rs, rs2 = rs * rs;
;                 const f32x4 g0 = acc[ai][0][m][0], g1 = acc[ai][0][m][1], u0 = acc[ai][1][m][0], u1 = acc[ai][1][m][1];
;                 const f32x4 a0 = g0 * nrs, a1 = g1 * nrs;
;                 f32x4 e0, e1;
; #pragma unroll
;                 for (int q = 0; q < 4; ++q) { e0[q] = __builtin_amdgcn_exp2f(a0[q]); e1[q] = __builtin_amdgcn_exp2f(a1[q]); }
;                 const f32x4 d0 = e0 + 1.0f, d1 = e1 + 1.0f;
;                 f32x4 r0, r1;
; #pragma unroll
;                 for (int q = 0; q < 4; ++q) { r0[q] = __builtin_amdgcn_rcpf(d0[q]); r1[q] = __builtin_amdgcn_rcpf(d1[q]); }
;                 const f32x4 o0 = ((g0 * u0) * rs2) * r0, o1 = ((g1 * u1) * rs2) * r1;
	s_add_i32 s50, s50, 2
	s_add_u32 s22, s22, 0x100
	s_addc_u32 s23, s23, 0
	s_add_u32 s48, s48, 0x100
	s_addc_u32 s49, s49, 0
	s_cmp_gt_u32 s50, 13
	s_cbranch_scc0 .LBB0_493
	v_lshl_add_u32 v142, s45, 8, v148
	v_mov_b32_e32 v143, 0
	s_mov_b32 s26, 0x2000
	s_mov_b32 s27, 0
	v_lshlrev_b64 v[146:147], 6, v[142:143]
	v_lshl_add_u64 v[146:147], v[136:137], 0, v[146:147]
	v_lshl_add_u64 v[156:157], v[146:147], 0, s[26:27]
	global_load_dwordx4 v[172:175], v[146:147], off
	global_load_dwordx4 v[176:179], v[146:147], off offset:1024
	global_load_dwordx4 v[180:183], v[146:147], off offset:2048
	global_load_dwordx4 v[184:187], v[146:147], off offset:3072
	global_load_dwordx4 v[188:191], v[156:157], off
	global_load_dwordx4 v[192:195], v[156:157], off offset:1024
	global_load_dwordx4 v[196:199], v[156:157], off offset:2048
	global_load_dwordx4 v[214:217], v[156:157], off offset:3072
	v_xor_b32_e32 v152, 16, v201
	v_xor_b32_e32 v153, 32, v201
	v_lshlrev_b32_e32 v152, 2, v152
	v_lshlrev_b32_e32 v153, 2, v153
	v_lshl_or_b32 v144, s44, 7, v150
	v_mov_b32_e32 v145, 0
	v_mov_b32_e32 v238, s0
	v_mov_b32_e32 v239, s1
	v_mad_i64_i32 v[236:237], s[22:23], v142, s93, v[238:239]
	v_lshlrev_b64 v[240:241], 1, v[144:145]
	v_mov_b32_e32 v234, 1.0
	v_mov_b32_e32 v235, 1.0
	v_lshl_add_u64 v[236:237], v[236:237], 0, v[240:241]
	s_mov_b32 s26, 0x16000
	s_mov_b32 s24, 0x6e000
	s_mov_b32 s25, 0
	v_pk_mul_f32 v[122:123], v[126:127], v[122:123]
	v_pk_mul_f32 v[124:125], v[128:129], v[124:125]
	v_pk_mul_f32 v[114:115], v[118:119], v[114:115]
	v_pk_mul_f32 v[116:117], v[120:121], v[116:117]
	v_pk_mul_f32 v[106:107], v[110:111], v[106:107]
	v_pk_mul_f32 v[108:109], v[112:113], v[108:109]
	v_pk_mul_f32 v[98:99], v[102:103], v[98:99]
	v_pk_mul_f32 v[100:101], v[104:105], v[100:101]
	v_pk_mul_f32 v[90:91], v[94:95], v[90:91]
	v_pk_mul_f32 v[92:93], v[96:97], v[92:93]
	v_pk_mul_f32 v[82:83], v[86:87], v[82:83]
	v_pk_mul_f32 v[84:85], v[88:89], v[84:85]
	v_pk_mul_f32 v[74:75], v[78:79], v[74:75]
	v_pk_mul_f32 v[76:77], v[80:81], v[76:77]
	v_pk_mul_f32 v[66:67], v[70:71], v[66:67]
	v_pk_mul_f32 v[68:69], v[72:73], v[68:69]
	v_pk_mul_f32 v[58:59], v[62:63], v[58:59]
	v_pk_mul_f32 v[60:61], v[64:65], v[60:61]
	v_pk_mul_f32 v[50:51], v[54:55], v[50:51]
	v_pk_mul_f32 v[52:53], v[56:57], v[52:53]
	v_pk_mul_f32 v[42:43], v[46:47], v[42:43]
	v_pk_mul_f32 v[44:45], v[48:49], v[44:45]
	v_pk_mul_f32 v[34:35], v[38:39], v[34:35]
	v_pk_mul_f32 v[36:37], v[40:41], v[36:37]
	v_pk_mul_f32 v[26:27], v[30:31], v[26:27]
	v_pk_mul_f32 v[28:29], v[32:33], v[28:29]
	v_pk_mul_f32 v[18:19], v[22:23], v[18:19]
	v_pk_mul_f32 v[20:21], v[24:25], v[20:21]
	v_pk_mul_f32 v[10:11], v[14:15], v[10:11]
	v_pk_mul_f32 v[12:13], v[16:17], v[12:13]
	v_pk_mul_f32 v[2:3], v[6:7], v[2:3]
	v_pk_mul_f32 v[4:5], v[8:9], v[4:5]
	s_waitcnt vmcnt(0)
	v_add_f32_e32 v172, v172, v173
	v_add_f32_e32 v176, v176, v177
	v_add_f32_e32 v180, v180, v181
	v_add_f32_e32 v184, v184, v185
	v_add_f32_e32 v188, v188, v189
	v_add_f32_e32 v192, v192, v193
	v_add_f32_e32 v196, v196, v197
	v_add_f32_e32 v214, v214, v215
	v_add_f32_e32 v174, v174, v175
	v_add_f32_e32 v178, v178, v179
	v_add_f32_e32 v182, v182, v183
	v_add_f32_e32 v186, v186, v187
	v_add_f32_e32 v190, v190, v191
	v_add_f32_e32 v194, v194, v195
	v_add_f32_e32 v198, v198, v199
	v_add_f32_e32 v216, v216, v217
	v_add_f32_e32 v172, v172, v174
	v_add_f32_e32 v176, v176, v178
	v_add_f32_e32 v180, v180, v182
	v_add_f32_e32 v184, v184, v186
	v_add_f32_e32 v188, v188, v190
	v_add_f32_e32 v192, v192, v194
	v_add_f32_e32 v196, v196, v198
	v_add_f32_e32 v214, v214, v216
	ds_bpermute_b32 v173, v152, v172
	ds_bpermute_b32 v177, v152, v176
	ds_bpermute_b32 v181, v152, v180
	ds_bpermute_b32 v185, v152, v184
	ds_bpermute_b32 v189, v152, v188
	ds_bpermute_b32 v193, v152, v192
	ds_bpermute_b32 v197, v152, v196
	ds_bpermute_b32 v215, v152, v214
	s_waitcnt lgkmcnt(0)
	v_add_f32_e32 v172, v172, v173
	v_add_f32_e32 v176, v176, v177
	v_add_f32_e32 v180, v180, v181
	v_add_f32_e32 v184, v184, v185
	v_add_f32_e32 v188, v188, v189
	v_add_f32_e32 v192, v192, v193
	v_add_f32_e32 v196, v196, v197
	v_add_f32_e32 v214, v214, v215
	ds_bpermute_b32 v173, v153, v172
	ds_bpermute_b32 v177, v153, v176
	ds_bpermute_b32 v181, v153, v180
	ds_bpermute_b32 v185, v153, v184
	ds_bpermute_b32 v189, v153, v188
	ds_bpermute_b32 v193, v153, v192
	ds_bpermute_b32 v197, v153, v196
	ds_bpermute_b32 v215, v153, v214
	s_waitcnt lgkmcnt(0)
	v_add_f32_e32 v172, v172, v173
	v_add_f32_e32 v176, v176, v177
	v_add_f32_e32 v180, v180, v181
	v_add_f32_e32 v184, v184, v185
	v_add_f32_e32 v188, v188, v189
	v_add_f32_e32 v192, v192, v193
	v_add_f32_e32 v196, v196, v197
	v_add_f32_e32 v214, v214, v215
	v_fmamk_f32 v172, v172, 0x3a800000, v207
	v_fmamk_f32 v176, v176, 0x3a800000, v207
	v_fmamk_f32 v180, v180, 0x3a800000, v207
	v_fmamk_f32 v184, v184, 0x3a800000, v207
	v_fmamk_f32 v188, v188, 0x3a800000, v207
	v_fmamk_f32 v192, v192, 0x3a800000, v207
	v_fmamk_f32 v196, v196, 0x3a800000, v207
	v_fmamk_f32 v214, v214, 0x3a800000, v207
	v_rsq_f32_e32 v172, v172
	v_rsq_f32_e32 v176, v176
	v_rsq_f32_e32 v180, v180
	v_rsq_f32_e32 v184, v184
	v_rsq_f32_e32 v188, v188
	v_rsq_f32_e32 v192, v192
	v_rsq_f32_e32 v196, v196
	v_rsq_f32_e32 v214, v214
	v_mul_f32_e32 v174, v172, v172
	v_mul_f32_e32 v178, v176, v176
	v_mul_f32_e32 v182, v180, v180
	v_mul_f32_e32 v186, v184, v184
	v_mul_f32_e32 v190, v188, v188
	v_mul_f32_e32 v194, v192, v192
	v_mul_f32_e32 v198, v196, v196
	v_mul_f32_e32 v216, v214, v214
	v_mul_f32_e32 v172, 0xbfb8aa3b, v172
	v_mul_f32_e32 v176, 0xbfb8aa3b, v176
	v_mul_f32_e32 v180, 0xbfb8aa3b, v180
	v_mul_f32_e32 v184, 0xbfb8aa3b, v184
	v_mul_f32_e32 v188, 0xbfb8aa3b, v188
	v_mul_f32_e32 v192, 0xbfb8aa3b, v192
	v_mul_f32_e32 v196, 0xbfb8aa3b, v196
	v_mul_f32_e32 v214, 0xbfb8aa3b, v214
	s_and_b64 vcc, exec, s[12:13]
	s_cbranch_vccz .LBB0_496
	s_barrier
; __device__ __forceinline__ unsigned cvt_pk_bf16(float lo, float hi) { f32x2_cv v = {lo, hi}; bf16x2_cv b = __builtin_convertvector(v, bf16x2_cv); return __builtin_bit_cast(unsigned, b); }
;     __device__ __forceinline__ void operator()(const f32x4 (&acc)[2][2][4][2], const Unit& u, int wr, int wc, int fr, int fq) const {
;     ...
;                 const int row = row0 + ai * HALF + m * 16; const float rs = row_rstd(rsp, row, fq);
;                 const float nrs = -LOG2E * rs, rs2 = rs * rs;
;                 const f32x4 g0 = acc[ai][0][m][0], g1 = acc[ai][0][m][1], u0 = acc[ai][1][m][0], u1 = acc[ai][1][m][1];
;                 const f32x4 a0 = g0 * nrs, a1 = g1 * nrs;
;                 f32x4 e0, e1;
; #pragma unroll
;                 for (int q = 0; q < 4; ++q) { e0[q] = __builtin_amdgcn_exp2f(a0[q]); e1[q] = __builtin_amdgcn_exp2f(a1[q]); }
;                 const f32x4 d0 = e0 + 1.0f, d1 = e1 + 1.0f;
;                 f32x4 r0, r1;
; #pragma unroll
;                 for (int q = 0; q < 4; ++q) { r0[q] = __builtin_amdgcn_rcpf(d0[q]); r1[q] = __builtin_amdgcn_rcpf(d1[q]); }
;                 const f32x4 o0 = ((g0 * u0) * rs2) * r0, o1 = ((g1 * u1) * rs2) * r1;
;                 u32x4 w; w.x = cvt_pk_bf16(o0[0], o0[1]); w.y = cvt_pk_bf16(o0[2], o0[3]); w.z = cvt_pk_bf16(o1[0], o1[1]); w.w = cvt_pk_bf16(o1[2], o1[3]);
;                 *(u32x4*)(O + (size_t)row * ldc + col0) = w;
.LBB0_496:
	v_pk_mul_f32 v[218:219], v[126:127], v[172:173] op_sel_hi:[1,0]
	v_pk_mul_f32 v[220:221], v[128:129], v[172:173] op_sel_hi:[1,0]
	v_pk_mul_f32 v[222:223], v[118:119], v[172:173] op_sel_hi:[1,0]
	v_pk_mul_f32 v[224:225], v[120:121], v[172:173] op_sel_hi:[1,0]
	v_exp_f32_e32 v218, v218
	v_exp_f32_e32 v219, v219
	v_exp_f32_e32 v220, v220
	v_exp_f32_e32 v221, v221
	v_exp_f32_e32 v222, v222
	v_exp_f32_e32 v223, v223
	v_exp_f32_e32 v224, v224
	v_exp_f32_e32 v225, v225
	v_pk_add_f32 v[218:219], v[218:219], v[234:235]
	v_pk_add_f32 v[220:221], v[220:221], v[234:235]
	v_pk_add_f32 v[222:223], v[222:223], v[234:235]
	v_pk_add_f32 v[224:225], v[224:225], v[234:235]
	v_rcp_f32_e32 v218, v218
	v_rcp_f32_e32 v219, v219
	v_rcp_f32_e32 v220, v220
	v_rcp_f32_e32 v221, v221
	v_rcp_f32_e32 v222, v222
	v_rcp_f32_e32 v223, v223
	v_rcp_f32_e32 v224, v224
	v_rcp_f32_e32 v225, v225
	v_pk_mul_f32 v[122:123], v[122:123], v[174:175] op_sel_hi:[1,0]
	v_pk_mul_f32 v[124:125], v[124:125], v[174:175] op_sel_hi:[1,0]
	v_pk_mul_f32 v[114:115], v[114:115], v[174:175] op_sel_hi:[1,0]
	v_pk_mul_f32 v[116:117], v[116:117], v[174:175] op_sel_hi:[1,0]
	v_pk_mul_f32 v[122:123], v[122:123], v[218:219]
	v_pk_mul_f32 v[124:125], v[124:125], v[220:221]
	v_pk_mul_f32 v[114:115], v[114:115], v[222:223]
	v_pk_mul_f32 v[116:117], v[116:117], v[224:225]
	v_cvt_pk_bf16_f32 v118, v122, v123
	v_cvt_pk_bf16_f32 v119, v124, v125
	v_cvt_pk_bf16_f32 v120, v114, v115
	v_cvt_pk_bf16_f32 v121, v116, v117
	global_store_dwordx4 v[236:237], v[118:121], off
	v_lshl_add_u64 v[236:237], v[236:237], 0, s[26:27]
	v_pk_mul_f32 v[226:227], v[110:111], v[176:177] op_sel_hi:[1,0]
	v_pk_mul_f32 v[228:229], v[112:113], v[176:177] op_sel_hi:[1,0]
	v_pk_mul_f32 v[230:231], v[102:103], v[176:177] op_sel_hi:[1,0]
	v_pk_mul_f32 v[232:233], v[104:105], v[176:177] op_sel_hi:[1,0]
	v_exp_f32_e32 v226, v226
	v_exp_f32_e32 v227, v227
	v_exp_f32_e32 v228, v228
	v_exp_f32_e32 v229, v229
	v_exp_f32_e32 v230, v230
	v_exp_f32_e32 v231, v231
	v_exp_f32_e32 v232, v232
	v_exp_f32_e32 v233, v233
	v_pk_add_f32 v[226:227], v[226:227], v[234:235]
	v_pk_add_f32 v[228:229], v[228:229], v[234:235]
	v_pk_add_f32 v[230:231], v[230:231], v[234:235]
	v_pk_add_f32 v[232:233], v[232:233], v[234:235]
	v_rcp_f32_e32 v226, v226
	v_rcp_f32_e32 v227, v227
	v_rcp_f32_e32 v228, v228
	v_rcp_f32_e32 v229, v229
	v_rcp_f32_e32 v230, v230
	v_rcp_f32_e32 v231, v231
	v_rcp_f32_e32 v232, v232
	v_rcp_f32_e32 v233, v233
	v_pk_mul_f32 v[106:107], v[106:107], v[178:179] op_sel_hi:[1,0]
	v_pk_mul_f32 v[108:109], v[108:109], v[178:179] op_sel_hi:[1,0]
	v_pk_mul_f32 v[98:99], v[98:99], v[178:179] op_sel_hi:[1,0]
	v_pk_mul_f32 v[100:101], v[100:101], v[178:179] op_sel_hi:[1,0]
	v_pk_mul_f32 v[106:107], v[106:107], v[226:227]
	v_pk_mul_f32 v[108:109], v[108:109], v[228:229]
	v_pk_mul_f32 v[98:99], v[98:99], v[230:231]
	v_pk_mul_f32 v[100:101], v[100:101], v[232:233]
	v_cvt_pk_bf16_f32 v102, v106, v107
	v_cvt_pk_bf16_f32 v103, v108, v109
	v_cvt_pk_bf16_f32 v104, v98, v99
	v_cvt_pk_bf16_f32 v105, v100, v101
	global_store_dwordx4 v[236:237], v[102:105], off
	v_lshl_add_u64 v[236:237], v[236:237], 0, s[26:27]
	v_pk_mul_f32 v[218:219], v[94:95], v[180:181] op_sel_hi:[1,0]
	v_pk_mul_f32 v[220:221], v[96:97], v[180:181] op_sel_hi:[1,0]
	v_pk_mul_f32 v[222:223], v[86:87], v[180:181] op_sel_hi:[1,0]
	v_pk_mul_f32 v[224:225], v[88:89], v[180:181] op_sel_hi:[1,0]
	v_exp_f32_e32 v218, v218
	v_exp_f32_e32 v219, v219
	v_exp_f32_e32 v220, v220
	v_exp_f32_e32 v221, v221
	v_exp_f32_e32 v222, v222
	v_exp_f32_e32 v223, v223
	v_exp_f32_e32 v224, v224
	v_exp_f32_e32 v225, v225
	v_pk_add_f32 v[218:219], v[218:219], v[234:235]
	v_pk_add_f32 v[220:221], v[220:221], v[234:235]
	v_pk_add_f32 v[222:223], v[222:223], v[234:235]
	v_pk_add_f32 v[224:225], v[224:225], v[234:235]
	v_rcp_f32_e32 v218, v218
	v_rcp_f32_e32 v219, v219
	v_rcp_f32_e32 v220, v220
	v_rcp_f32_e32 v221, v221
	v_rcp_f32_e32 v222, v222
	v_rcp_f32_e32 v223, v223
	v_rcp_f32_e32 v224, v224
	v_rcp_f32_e32 v225, v225
	v_pk_mul_f32 v[90:91], v[90:91], v[182:183] op_sel_hi:[1,0]
	v_pk_mul_f32 v[92:93], v[92:93], v[182:183] op_sel_hi:[1,0]
	v_pk_mul_f32 v[82:83], v[82:83], v[182:183] op_sel_hi:[1,0]
	v_pk_mul_f32 v[84:85], v[84:85], v[182:183] op_sel_hi:[1,0]
	v_pk_mul_f32 v[90:91], v[90:91], v[218:219]
	v_pk_mul_f32 v[92:93], v[92:93], v[220:221]
	v_pk_mul_f32 v[82:83], v[82:83], v[222:223]
	v_pk_mul_f32 v[84:85], v[84:85], v[224:225]
	v_cvt_pk_bf16_f32 v86, v90, v91
	v_cvt_pk_bf16_f32 v87, v92, v93
	v_cvt_pk_bf16_f32 v88, v82, v83
	v_cvt_pk_bf16_f32 v89, v84, v85
	global_store_dwordx4 v[236:237], v[86:89], off
	v_lshl_add_u64 v[236:237], v[236:237], 0, s[26:27]
	v_pk_mul_f32 v[226:227], v[78:79], v[184:185] op_sel_hi:[1,0]
	v_pk_mul_f32 v[228:229], v[80:81], v[184:185] op_sel_hi:[1,0]
	v_pk_mul_f32 v[230:231], v[70:71], v[184:185] op_sel_hi:[1,0]
	v_pk_mul_f32 v[232:233], v[72:73], v[184:185] op_sel_hi:[1,0]
	v_exp_f32_e32 v226, v226
	v_exp_f32_e32 v227, v227
	v_exp_f32_e32 v228, v228
	v_exp_f32_e32 v229, v229
	v_exp_f32_e32 v230, v230
	v_exp_f32_e32 v231, v231
	v_exp_f32_e32 v232, v232
	v_exp_f32_e32 v233, v233
	v_pk_add_f32 v[226:227], v[226:227], v[234:235]
	v_pk_add_f32 v[228:229], v[228:229], v[234:235]
	v_pk_add_f32 v[230:231], v[230:231], v[234:235]
	v_pk_add_f32 v[232:233], v[232:233], v[234:235]
	v_rcp_f32_e32 v226, v226
	v_rcp_f32_e32 v227, v227
	v_rcp_f32_e32 v228, v228
	v_rcp_f32_e32 v229, v229
	v_rcp_f32_e32 v230, v230
	v_rcp_f32_e32 v231, v231
	v_rcp_f32_e32 v232, v232
	v_rcp_f32_e32 v233, v233
	v_pk_mul_f32 v[74:75], v[74:75], v[186:187] op_sel_hi:[1,0]
	v_pk_mul_f32 v[76:77], v[76:77], v[186:187] op_sel_hi:[1,0]
; __device__ __forceinline__ unsigned cvt_pk_bf16(float lo, float hi) { f32x2_cv v = {lo, hi}; bf16x2_cv b = __builtin_convertvector(v, bf16x2_cv); return __builtin_bit_cast(unsigned, b); }
;     __device__ __forceinline__ void operator()(const f32x4 (&acc)[2][2][4][2], const Unit& u, int wr, int wc, int fr, int fq) const {
;     ...
;                 const int row = row0 + ai * HALF + m * 16; const float rs = row_rstd(rsp, row, fq);
;                 const float nrs = -LOG2E * rs, rs2 = rs * rs;
;                 const f32x4 g0 = acc[ai][0][m][0], g1 = acc[ai][0][m][1], u0 = acc[ai][1][m][0], u1 = acc[ai][1][m][1];
;                 const f32x4 a0 = g0 * nrs, a1 = g1 * nrs;
;                 f32x4 e0, e1;
; #pragma unroll
;                 for (int q = 0; q < 4; ++q) { e0[q] = __builtin_amdgcn_exp2f(a0[q]); e1[q] = __builtin_amdgcn_exp2f(a1[q]); }
;                 const f32x4 d0 = e0 + 1.0f, d1 = e1 + 1.0f;
;                 f32x4 r0, r1;
; #pragma unroll
;                 for (int q = 0; q < 4; ++q) { r0[q] = __builtin_amdgcn_rcpf(d0[q]); r1[q] = __builtin_amdgcn_rcpf(d1[q]); }
;                 const f32x4 o0 = ((g0 * u0) * rs2) * r0, o1 = ((g1 * u1) * rs2) * r1;
;                 u32x4 w; w.x = cvt_pk_bf16(o0[0], o0[1]); w.y = cvt_pk_bf16(o0[2], o0[3]); w.z = cvt_pk_bf16(o1[0], o1[1]); w.w = cvt_pk_bf16(o1[2], o1[3]);
;                 *(u32x4*)(O + (size_t)row * ldc + col0) = w;
	v_pk_mul_f32 v[66:67], v[66:67], v[186:187] op_sel_hi:[1,0]
	v_pk_mul_f32 v[68:69], v[68:69], v[186:187] op_sel_hi:[1,0]
	v_pk_mul_f32 v[74:75], v[74:75], v[226:227]
	v_pk_mul_f32 v[76:77], v[76:77], v[228:229]
	v_pk_mul_f32 v[66:67], v[66:67], v[230:231]
	v_pk_mul_f32 v[68:69], v[68:69], v[232:233]
	v_cvt_pk_bf16_f32 v70, v74, v75
	v_cvt_pk_bf16_f32 v71, v76, v77
	v_cvt_pk_bf16_f32 v72, v66, v67
	v_cvt_pk_bf16_f32 v73, v68, v69
	global_store_dwordx4 v[236:237], v[70:73], off
	v_lshl_add_u64 v[236:237], v[236:237], 0, s[24:25]
	v_pk_mul_f32 v[218:219], v[62:63], v[188:189] op_sel_hi:[1,0]
	v_pk_mul_f32 v[220:221], v[64:65], v[188:189] op_sel_hi:[1,0]
	v_pk_mul_f32 v[222:223], v[54:55], v[188:189] op_sel_hi:[1,0]
	v_pk_mul_f32 v[224:225], v[56:57], v[188:189] op_sel_hi:[1,0]
	v_exp_f32_e32 v218, v218
	v_exp_f32_e32 v219, v219
	v_exp_f32_e32 v220, v220
	v_exp_f32_e32 v221, v221
	v_exp_f32_e32 v222, v222
	v_exp_f32_e32 v223, v223
	v_exp_f32_e32 v224, v224
	v_exp_f32_e32 v225, v225
	v_pk_add_f32 v[218:219], v[218:219], v[234:235]
	v_pk_add_f32 v[220:221], v[220:221], v[234:235]
	v_pk_add_f32 v[222:223], v[222:223], v[234:235]
	v_pk_add_f32 v[224:225], v[224:225], v[234:235]
	v_rcp_f32_e32 v218, v218
	v_rcp_f32_e32 v219, v219
	v_rcp_f32_e32 v220, v220
	v_rcp_f32_e32 v221, v221
	v_rcp_f32_e32 v222, v222
	v_rcp_f32_e32 v223, v223
	v_rcp_f32_e32 v224, v224
	v_rcp_f32_e32 v225, v225
	v_pk_mul_f32 v[58:59], v[58:59], v[190:191] op_sel_hi:[1,0]
	v_pk_mul_f32 v[60:61], v[60:61], v[190:191] op_sel_hi:[1,0]
	v_pk_mul_f32 v[50:51], v[50:51], v[190:191] op_sel_hi:[1,0]
	v_pk_mul_f32 v[52:53], v[52:53], v[190:191] op_sel_hi:[1,0]
	v_pk_mul_f32 v[58:59], v[58:59], v[218:219]
	v_pk_mul_f32 v[60:61], v[60:61], v[220:221]
	v_pk_mul_f32 v[50:51], v[50:51], v[222:223]
	v_pk_mul_f32 v[52:53], v[52:53], v[224:225]
	v_cvt_pk_bf16_f32 v54, v58, v59
	v_cvt_pk_bf16_f32 v55, v60, v61
	v_cvt_pk_bf16_f32 v56, v50, v51
	v_cvt_pk_bf16_f32 v57, v52, v53
	global_store_dwordx4 v[236:237], v[54:57], off
	v_lshl_add_u64 v[236:237], v[236:237], 0, s[26:27]
	v_pk_mul_f32 v[226:227], v[46:47], v[192:193] op_sel_hi:[1,0]
	v_pk_mul_f32 v[228:229], v[48:49], v[192:193] op_sel_hi:[1,0]
	v_pk_mul_f32 v[230:231], v[38:39], v[192:193] op_sel_hi:[1,0]
	v_pk_mul_f32 v[232:233], v[40:41], v[192:193] op_sel_hi:[1,0]
	v_exp_f32_e32 v226, v226
	v_exp_f32_e32 v227, v227
	v_exp_f32_e32 v228, v228
	v_exp_f32_e32 v229, v229
	v_exp_f32_e32 v230, v230
	v_exp_f32_e32 v231, v231
	v_exp_f32_e32 v232, v232
	v_exp_f32_e32 v233, v233
	v_pk_add_f32 v[226:227], v[226:227], v[234:235]
	v_pk_add_f32 v[228:229], v[228:229], v[234:235]
	v_pk_add_f32 v[230:231], v[230:231], v[234:235]
	v_pk_add_f32 v[232:233], v[232:233], v[234:235]
	v_rcp_f32_e32 v226, v226
	v_rcp_f32_e32 v227, v227
	v_rcp_f32_e32 v228, v228
	v_rcp_f32_e32 v229, v229
	v_rcp_f32_e32 v230, v230
	v_rcp_f32_e32 v231, v231
	v_rcp_f32_e32 v232, v232
	v_rcp_f32_e32 v233, v233
	v_pk_mul_f32 v[42:43], v[42:43], v[194:195] op_sel_hi:[1,0]
	v_pk_mul_f32 v[44:45], v[44:45], v[194:195] op_sel_hi:[1,0]
	v_pk_mul_f32 v[34:35], v[34:35], v[194:195] op_sel_hi:[1,0]
	v_pk_mul_f32 v[36:37], v[36:37], v[194:195] op_sel_hi:[1,0]
	v_pk_mul_f32 v[42:43], v[42:43], v[226:227]
	v_pk_mul_f32 v[44:45], v[44:45], v[228:229]
	v_pk_mul_f32 v[34:35], v[34:35], v[230:231]
	v_pk_mul_f32 v[36:37], v[36:37], v[232:233]
	v_cvt_pk_bf16_f32 v38, v42, v43
	v_cvt_pk_bf16_f32 v39, v44, v45
	v_cvt_pk_bf16_f32 v40, v34, v35
	v_cvt_pk_bf16_f32 v41, v36, v37
	global_store_dwordx4 v[236:237], v[38:41], off
	v_lshl_add_u64 v[236:237], v[236:237], 0, s[26:27]
	v_pk_mul_f32 v[218:219], v[30:31], v[196:197] op_sel_hi:[1,0]
	v_pk_mul_f32 v[220:221], v[32:33], v[196:197] op_sel_hi:[1,0]
	v_pk_mul_f32 v[222:223], v[22:23], v[196:197] op_sel_hi:[1,0]
	v_pk_mul_f32 v[224:225], v[24:25], v[196:197] op_sel_hi:[1,0]
	v_exp_f32_e32 v218, v218
	v_exp_f32_e32 v219, v219
	v_exp_f32_e32 v220, v220
	v_exp_f32_e32 v221, v221
	v_exp_f32_e32 v222, v222
	v_exp_f32_e32 v223, v223
	v_exp_f32_e32 v224, v224
	v_exp_f32_e32 v225, v225
	v_pk_add_f32 v[218:219], v[218:219], v[234:235]
	v_pk_add_f32 v[220:221], v[220:221], v[234:235]
	v_pk_add_f32 v[222:223], v[222:223], v[234:235]
	v_pk_add_f32 v[224:225], v[224:225], v[234:235]
	v_rcp_f32_e32 v218, v218
	v_rcp_f32_e32 v219, v219
	v_rcp_f32_e32 v220, v220
	v_rcp_f32_e32 v221, v221
	v_rcp_f32_e32 v222, v222
	v_rcp_f32_e32 v223, v223
	v_rcp_f32_e32 v224, v224
	v_rcp_f32_e32 v225, v225
	v_pk_mul_f32 v[26:27], v[26:27], v[198:199] op_sel_hi:[1,0]
	v_pk_mul_f32 v[28:29], v[28:29], v[198:199] op_sel_hi:[1,0]
	v_pk_mul_f32 v[18:19], v[18:19], v[198:199] op_sel_hi:[1,0]
	v_pk_mul_f32 v[20:21], v[20:21], v[198:199] op_sel_hi:[1,0]
	v_pk_mul_f32 v[26:27], v[26:27], v[218:219]
	v_pk_mul_f32 v[28:29], v[28:29], v[220:221]
	v_pk_mul_f32 v[18:19], v[18:19], v[222:223]
	v_pk_mul_f32 v[20:21], v[20:21], v[224:225]
	v_cvt_pk_bf16_f32 v22, v26, v27
	v_cvt_pk_bf16_f32 v23, v28, v29
	v_cvt_pk_bf16_f32 v24, v18, v19
	v_cvt_pk_bf16_f32 v25, v20, v21
	global_store_dwordx4 v[236:237], v[22:25], off
	v_lshl_add_u64 v[236:237], v[236:237], 0, s[26:27]
	v_pk_mul_f32 v[226:227], v[14:15], v[214:215] op_sel_hi:[1,0]
	v_pk_mul_f32 v[228:229], v[16:17], v[214:215] op_sel_hi:[1,0]
	v_pk_mul_f32 v[230:231], v[6:7], v[214:215] op_sel_hi:[1,0]
	v_pk_mul_f32 v[232:233], v[8:9], v[214:215] op_sel_hi:[1,0]
	v_exp_f32_e32 v226, v226
	v_exp_f32_e32 v227, v227
	v_exp_f32_e32 v228, v228
	v_exp_f32_e32 v229, v229
	v_exp_f32_e32 v230, v230
	v_exp_f32_e32 v231, v231
	v_exp_f32_e32 v232, v232
	v_exp_f32_e32 v233, v233
	v_pk_add_f32 v[226:227], v[226:227], v[234:235]
	v_pk_add_f32 v[228:229], v[228:229], v[234:235]
	v_pk_add_f32 v[230:231], v[230:231], v[234:235]
	v_pk_add_f32 v[232:233], v[232:233], v[234:235]
	v_rcp_f32_e32 v226, v226
	v_rcp_f32_e32 v227, v227
	v_rcp_f32_e32 v228, v228
	v_rcp_f32_e32 v229, v229
	v_rcp_f32_e32 v230, v230
	v_rcp_f32_e32 v231, v231
	v_rcp_f32_e32 v232, v232
	v_rcp_f32_e32 v233, v233
	v_pk_mul_f32 v[10:11], v[10:11], v[216:217] op_sel_hi:[1,0]
	v_pk_mul_f32 v[12:13], v[12:13], v[216:217] op_sel_hi:[1,0]
	v_pk_mul_f32 v[2:3], v[2:3], v[216:217] op_sel_hi:[1,0]
	v_pk_mul_f32 v[4:5], v[4:5], v[216:217] op_sel_hi:[1,0]
	v_pk_mul_f32 v[10:11], v[10:11], v[226:227]
	v_pk_mul_f32 v[12:13], v[12:13], v[228:229]
	v_pk_mul_f32 v[2:3], v[2:3], v[230:231]
	v_pk_mul_f32 v[4:5], v[4:5], v[232:233]
	v_cvt_pk_bf16_f32 v6, v10, v11
	v_cvt_pk_bf16_f32 v7, v12, v13
	v_cvt_pk_bf16_f32 v8, v2, v3
	v_cvt_pk_bf16_f32 v9, v4, v5
	global_store_dwordx4 v[236:237], v[6:9], off
	s_mov_b64 s[22:23], -1
	s_andn2_b64 vcc, exec, s[4:5]
	s_cbranch_vccnz .LBB0_489
	s_andn2_b64 vcc, exec, s[8:9]
	s_cbranch_vccnz .LBB0_488
	s_barrier
	s_branch .LBB0_488
